# dft16 v2: coalesced row loads (8 lanes x 16 B per token row), pitch-68 LDS tile (conflict-free b16 writes), pipelined copy-out
# speedup vs baseline: 1.0125x; 1.0125x over previous
; __device__ __forceinline__ void dft16_phase(const Ctx& X, const bf16_t* HN, bf16_t* GT) {
;     ...
;         const int b = unit >> 6, bt = (unit >> 4) & 3, ct = unit & 15, b0 = bt * 64, ch0 = ct * 64;
;         const int i = X.tid >> 3, cchunk = X.tid & 7;
;         u32x4 xin[16];
; #pragma unroll
;         for (int a = 0; a < 16; ++a) xin[a] = *(const u32x4*)(HN + (size_t)(b * 4096 + 256 * a + b0 + i) * 1024 + ch0 + cchunk * 8);
;         const int bp = b0 + i;
; #pragma unroll 1
;         for (int kq = 0; kq < 3; ++kq) {
;             __syncthreads();
; #pragma unroll 1
;             for (int kl = 0; kl < 4; ++kl) { const int ka = kq * 4 + kl; if (ka > 8) break;
;                 const float tang = (float)(bp * ka) * (1.0f / 2048.0f); const float tc = cospif(tang), ts = -sinpif(tang);
.LBB0_1441:
	s_or_b64 exec, exec, s[0:1]
	v_mov_b32_e32 v14, v206
	s_waitcnt lgkmcnt(0)
	s_barrier
	v_readfirstlane_b32 s12, v206
	s_lshr_b32 s12, s12, 6
	v_and_b32_e32 v1, 63, v206
	v_lshrrev_b32_e32 v10, 3, v1
	v_and_b32_e32 v11, 7, v1
	v_lshlrev_b32_e32 v12, 11, v10
	v_lshl_add_u32 v2, v11, 4, v12
	s_lshl_b32 s0, s12, 3
	v_add_u32_e32 v12, s0, v10
	v_mov_b32_e32 v14, v12
	s_movk_i32 s0, 0x220
	v_mul_lo_u32 v13, v11, s0
	v_lshl_add_u32 v3, v12, 1, v13
	v_add_u32_e32 v4, 0x8800, v3
	v_lshrrev_b32_e32 v10, 3, v206
	v_and_b32_e32 v11, 7, v206
	s_movk_i32 s0, 0x88
	v_mul_lo_u32 v12, v10, s0
	v_lshl_add_u32 v5, v11, 4, v12
	v_add_u32_e32 v6, 0x8800, v5
	v_and_b32_e32 v12, 31, v10
	v_lshrrev_b32_e32 v13, 2, v12
	v_and_b32_e32 v12, 3, v12
	v_lshl_add_u32 v12, v13, 3, v12
	v_lshlrev_b32_e32 v12, 10, v12
	v_lshrrev_b32_e32 v13, 8, v206
	v_and_b32_e32 v13, 1, v13
	v_lshl_add_u32 v12, v13, 9, v12
	v_lshl_add_u32 v7, v11, 4, v12
	s_add_u32 s0, s2, 0
	s_lshr_b32 s1, s0, 6
	s_bfe_u32 s6, s0, 0x20004
	s_and_b32 s7, s0, 15
	s_lshl_b32 s28, s6, 6
	s_lshl_b32 s8, s1, 23
	s_lshl_b32 s9, s28, 11
	s_add_u32 s8, s8, s9
	s_lshl_b32 s9, s7, 7
	s_add_u32 s8, s8, s9
	s_lshl_b32 s9, s12, 14
	s_add_u32 s8, s8, s9
	s_add_u32 s24, s88, s8
	s_addc_u32 s25, s89, 0
	s_add_u32 s24, s24, 0x13000000
	s_addc_u32 s25, s25, 0
	s_mul_i32 s8, s1, 0x900000
	s_lshl_b32 s9, s7, 16
	s_add_u32 s8, s8, s9
	s_lshl_b32 s9, s28, 1
	s_add_u32 s8, s8, s9
	s_add_u32 s26, s88, s8
	s_addc_u32 s27, s89, 0
	s_add_u32 s26, s26, 0x7500000
	s_addc_u32 s27, s27, 0
	s_add_u32 s0, s2, 256
	s_lshr_b32 s1, s0, 6
	s_bfe_u32 s6, s0, 0x20004
	s_and_b32 s7, s0, 15
	s_lshl_b32 s38, s6, 6
	s_lshl_b32 s8, s1, 23
	s_lshl_b32 s9, s38, 11
	s_add_u32 s8, s8, s9
	s_lshl_b32 s9, s7, 7
	s_add_u32 s8, s8, s9
	s_lshl_b32 s9, s12, 14
	s_add_u32 s8, s8, s9
	s_add_u32 s34, s88, s8
	s_addc_u32 s35, s89, 0
	s_add_u32 s34, s34, 0x13000000
	s_addc_u32 s35, s35, 0
	s_mul_i32 s8, s1, 0x900000
	s_lshl_b32 s9, s7, 16
	s_add_u32 s8, s8, s9
	s_lshl_b32 s9, s38, 1
	s_add_u32 s8, s8, s9
	s_add_u32 s36, s88, s8
	s_addc_u32 s37, s89, 0
	s_add_u32 s36, s36, 0x7500000
	s_addc_u32 s37, s37, 0
	s_mov_b64 s[8:9], s[24:25]
	global_load_dwordx4 v[64:67], v2, s[8:9]
	s_add_u32 s8, s8, 0x80000
	s_addc_u32 s9, s9, 0
	global_load_dwordx4 v[68:71], v2, s[8:9]
	s_add_u32 s8, s8, 0x80000
	s_addc_u32 s9, s9, 0
	global_load_dwordx4 v[72:75], v2, s[8:9]
	s_add_u32 s8, s8, 0x80000
	s_addc_u32 s9, s9, 0
	global_load_dwordx4 v[76:79], v2, s[8:9]
	s_add_u32 s8, s8, 0x80000
	s_addc_u32 s9, s9, 0
	global_load_dwordx4 v[80:83], v2, s[8:9]
	s_add_u32 s8, s8, 0x80000
	s_addc_u32 s9, s9, 0
	global_load_dwordx4 v[84:87], v2, s[8:9]
	s_add_u32 s8, s8, 0x80000
	s_addc_u32 s9, s9, 0
	global_load_dwordx4 v[88:91], v2, s[8:9]
	s_add_u32 s8, s8, 0x80000
	s_addc_u32 s9, s9, 0
	global_load_dwordx4 v[92:95], v2, s[8:9]
	s_add_u32 s8, s8, 0x80000
	s_addc_u32 s9, s9, 0
	global_load_dwordx4 v[96:99], v2, s[8:9]
	s_add_u32 s8, s8, 0x80000
	s_addc_u32 s9, s9, 0
	global_load_dwordx4 v[100:103], v2, s[8:9]
	s_add_u32 s8, s8, 0x80000
	s_addc_u32 s9, s9, 0
	global_load_dwordx4 v[104:107], v2, s[8:9]
	s_add_u32 s8, s8, 0x80000
	s_addc_u32 s9, s9, 0
	global_load_dwordx4 v[108:111], v2, s[8:9]
	s_add_u32 s8, s8, 0x80000
	s_addc_u32 s9, s9, 0
	global_load_dwordx4 v[112:115], v2, s[8:9]
	s_add_u32 s8, s8, 0x80000
	s_addc_u32 s9, s9, 0
	global_load_dwordx4 v[116:119], v2, s[8:9]
	s_add_u32 s8, s8, 0x80000
	s_addc_u32 s9, s9, 0
	global_load_dwordx4 v[120:123], v2, s[8:9]
	s_add_u32 s8, s8, 0x80000
	s_addc_u32 s9, s9, 0
	global_load_dwordx4 v[124:127], v2, s[8:9]
	s_mov_b64 s[8:9], s[34:35]
	global_load_dwordx4 v[128:131], v2, s[8:9]
	s_add_u32 s8, s8, 0x80000
	s_addc_u32 s9, s9, 0
	global_load_dwordx4 v[132:135], v2, s[8:9]
	s_add_u32 s8, s8, 0x80000
	s_addc_u32 s9, s9, 0
	global_load_dwordx4 v[136:139], v2, s[8:9]
	s_add_u32 s8, s8, 0x80000
	s_addc_u32 s9, s9, 0
	global_load_dwordx4 v[140:143], v2, s[8:9]
	s_add_u32 s8, s8, 0x80000
	s_addc_u32 s9, s9, 0
	global_load_dwordx4 v[144:147], v2, s[8:9]
	s_add_u32 s8, s8, 0x80000
	s_addc_u32 s9, s9, 0
	global_load_dwordx4 v[148:151], v2, s[8:9]
	s_add_u32 s8, s8, 0x80000
	s_addc_u32 s9, s9, 0
	global_load_dwordx4 v[152:155], v2, s[8:9]
	s_add_u32 s8, s8, 0x80000
	s_addc_u32 s9, s9, 0
	global_load_dwordx4 v[156:159], v2, s[8:9]
	s_add_u32 s8, s8, 0x80000
	s_addc_u32 s9, s9, 0
	global_load_dwordx4 v[160:163], v2, s[8:9]
	s_add_u32 s8, s8, 0x80000
	s_addc_u32 s9, s9, 0
	global_load_dwordx4 v[164:167], v2, s[8:9]
	s_add_u32 s8, s8, 0x80000
	s_addc_u32 s9, s9, 0
	global_load_dwordx4 v[168:171], v2, s[8:9]
	s_add_u32 s8, s8, 0x80000
	s_addc_u32 s9, s9, 0
	global_load_dwordx4 v[172:175], v2, s[8:9]
	s_add_u32 s8, s8, 0x80000
	s_addc_u32 s9, s9, 0
	global_load_dwordx4 v[176:179], v2, s[8:9]
	s_add_u32 s8, s8, 0x80000
	s_addc_u32 s9, s9, 0
	global_load_dwordx4 v[180:183], v2, s[8:9]
	s_add_u32 s8, s8, 0x80000
	s_addc_u32 s9, s9, 0
	global_load_dwordx4 v[184:187], v2, s[8:9]
	s_add_u32 s8, s8, 0x80000
	s_addc_u32 s9, s9, 0
	global_load_dwordx4 v[188:191], v2, s[8:9]
	s_waitcnt vmcnt(16)
	v_add_u32_e32 v10, s28, v14
	v_cvt_f32_u32_e32 v10, v10
	v_mul_f32_e32 v11, 0x39800000, v10
	v_cos_f32_e32 v208, v11
	v_sin_f32_e32 v216, v11
	v_mul_f32_e32 v11, 0x3a000000, v10
	v_cos_f32_e32 v209, v11
	v_sin_f32_e32 v217, v11
	v_mul_f32_e32 v11, 0x3a400000, v10
	v_cos_f32_e32 v210, v11
	v_sin_f32_e32 v218, v11
	v_mul_f32_e32 v11, 0x3a800000, v10
	v_cos_f32_e32 v211, v11
	v_sin_f32_e32 v219, v11
	v_mul_f32_e32 v11, 0x3aa00000, v10
	v_cos_f32_e32 v212, v11
	v_sin_f32_e32 v220, v11
	v_mul_f32_e32 v11, 0x3ac00000, v10
	v_cos_f32_e32 v213, v11
	v_sin_f32_e32 v221, v11
	v_mul_f32_e32 v11, 0x3ae00000, v10
	v_cos_f32_e32 v214, v11
	v_sin_f32_e32 v222, v11
	v_mul_f32_e32 v11, 0x3b000000, v10
	v_cos_f32_e32 v215, v11
	v_sin_f32_e32 v223, v11
	s_barrier
; __device__ __forceinline__ bf16_t f2bf(float f) { return (bf16_t)(cvt_pk_bf16(f, 0.f) & 0xffffu); }
; __device__ __forceinline__ void dft16_phase(const Ctx& X, const bf16_t* HN, bf16_t* GT) {
;     ...
;                 for (int e = 0; e < 8; ++e) { float re = 0.f, im = 0.f;
; #pragma unroll
;                     for (int a = 0; a < 16; ++a) { const unsigned wv = xin[a][e >> 1]; const float x = (e & 1) ? bf2f(wv >> 16) : bf2f(wv & 0xffffu); re += x * cw[a]; im -= x * sw[a]; }
;                     const float orr = re * tc - im * ts, oi = re * ts + im * tc;
;                     tile[((kl * 2 + 0) * 64 + cchunk * 8 + e) * 72 + i] = f2bf(orr); tile[((kl * 2 + 1) * 64 + cchunk * 8 + e) * 72 + i] = f2bf(oi); } }
	v_lshlrev_b32_e32 v16, 16, v64
	v_lshlrev_b32_e32 v17, 16, v68
	v_lshlrev_b32_e32 v18, 16, v72
	v_lshlrev_b32_e32 v19, 16, v76
	v_lshlrev_b32_e32 v20, 16, v80
	v_lshlrev_b32_e32 v21, 16, v84
	v_lshlrev_b32_e32 v22, 16, v88
	v_lshlrev_b32_e32 v23, 16, v92
	v_lshlrev_b32_e32 v24, 16, v96
	v_lshlrev_b32_e32 v25, 16, v100
	v_lshlrev_b32_e32 v26, 16, v104
	v_lshlrev_b32_e32 v27, 16, v108
	v_lshlrev_b32_e32 v28, 16, v112
	v_lshlrev_b32_e32 v29, 16, v116
	v_lshlrev_b32_e32 v30, 16, v120
	v_lshlrev_b32_e32 v31, 16, v124
	v_add_f32_e32 v32, v17, v31
	v_sub_f32_e32 v40, v17, v31
	v_add_f32_e32 v33, v18, v30
	v_sub_f32_e32 v41, v18, v30
	v_add_f32_e32 v34, v19, v29
	v_sub_f32_e32 v42, v19, v29
	v_add_f32_e32 v35, v20, v28
	v_sub_f32_e32 v43, v20, v28
	v_add_f32_e32 v36, v21, v27
	v_sub_f32_e32 v44, v21, v27
	v_add_f32_e32 v37, v22, v26
	v_sub_f32_e32 v45, v22, v26
	v_add_f32_e32 v38, v23, v25
	v_sub_f32_e32 v46, v23, v25
	v_add_f32_e32 v48, v16, v24
	v_add_f32_e32 v48, v48, v32
	v_add_f32_e32 v48, v48, v33
	v_add_f32_e32 v48, v48, v34
	v_add_f32_e32 v48, v48, v35
	v_add_f32_e32 v48, v48, v36
	v_add_f32_e32 v48, v48, v37
	v_add_f32_e32 v48, v48, v38
	v_cvt_pk_bf16_f32 v52, v48, 0
	ds_write_b16 v3, v52 offset:0
	ds_write_b16_d16_hi v3, v52 offset:4352
	v_sub_f32_e32 v48, v16, v24
	v_fmac_f32_e32 v48, 0x3f6c835e, v32
	v_fmac_f32_e32 v48, 0x3f3504f3, v33
	v_fmac_f32_e32 v48, 0x3ec3ef15, v34
	v_fmac_f32_e32 v48, 0xbec3ef15, v36
	v_fmac_f32_e32 v48, 0xbf3504f3, v37
	v_fmac_f32_e32 v48, 0xbf6c835e, v38
	v_mul_f32_e32 v49, 0xbec3ef15, v40
	v_fmac_f32_e32 v49, 0xbf3504f3, v41
	v_fmac_f32_e32 v49, 0xbf6c835e, v42
	v_sub_f32_e32 v49, v49, v43
	v_fmac_f32_e32 v49, 0xbf6c835e, v44
	v_fmac_f32_e32 v49, 0xbf3504f3, v45
	v_fmac_f32_e32 v49, 0xbec3ef15, v46
	v_mul_f32_e32 v50, v49, v216
	v_fmac_f32_e32 v50, v48, v208
	v_mul_f32_e32 v51, v48, v216
	v_fma_f32 v51, v49, v208, -v51
	v_cvt_pk_bf16_f32 v52, v50, v51
	ds_write_b16 v3, v52 offset:8704
	ds_write_b16_d16_hi v3, v52 offset:13056
	v_add_f32_e32 v48, v16, v24
	v_fmac_f32_e32 v48, 0x3f3504f3, v32
	v_fmac_f32_e32 v48, 0xbf3504f3, v34
	v_sub_f32_e32 v48, v48, v35
	v_fmac_f32_e32 v48, 0xbf3504f3, v36
	v_fmac_f32_e32 v48, 0x3f3504f3, v38
	v_mul_f32_e32 v49, 0xbf3504f3, v40
	v_sub_f32_e32 v49, v49, v41
	v_fmac_f32_e32 v49, 0xbf3504f3, v42
	v_fmac_f32_e32 v49, 0x3f3504f3, v44
	v_add_f32_e32 v49, v49, v45
	v_fmac_f32_e32 v49, 0x3f3504f3, v46
	v_mul_f32_e32 v50, v49, v217
	v_fmac_f32_e32 v50, v48, v209
	v_mul_f32_e32 v51, v48, v217
	v_fma_f32 v51, v49, v209, -v51
	v_cvt_pk_bf16_f32 v52, v50, v51
	ds_write_b16 v3, v52 offset:17408
	ds_write_b16_d16_hi v3, v52 offset:21760
	v_sub_f32_e32 v48, v16, v24
	v_fmac_f32_e32 v48, 0x3ec3ef15, v32
	v_fmac_f32_e32 v48, 0xbf3504f3, v33
	v_fmac_f32_e32 v48, 0xbf6c835e, v34
	v_fmac_f32_e32 v48, 0x3f6c835e, v36
	v_fmac_f32_e32 v48, 0x3f3504f3, v37
	v_fmac_f32_e32 v48, 0xbec3ef15, v38
	v_mul_f32_e32 v49, 0xbf6c835e, v40
	v_fmac_f32_e32 v49, 0xbf3504f3, v41
	v_fmac_f32_e32 v49, 0x3ec3ef15, v42
	v_add_f32_e32 v49, v49, v43
	v_fmac_f32_e32 v49, 0x3ec3ef15, v44
	v_fmac_f32_e32 v49, 0xbf3504f3, v45
	v_fmac_f32_e32 v49, 0xbf6c835e, v46
	v_mul_f32_e32 v50, v49, v218
	v_fmac_f32_e32 v50, v48, v210
	v_mul_f32_e32 v51, v48, v218
	v_fma_f32 v51, v49, v210, -v51
	v_cvt_pk_bf16_f32 v52, v50, v51
	ds_write_b16 v3, v52 offset:26112
	ds_write_b16_d16_hi v3, v52 offset:30464
	v_add_f32_e32 v48, v16, v24
	v_sub_f32_e32 v48, v48, v33
	v_add_f32_e32 v48, v48, v35
	v_sub_f32_e32 v48, v48, v37
	v_sub_f32_e32 v49, 0, v40
	v_add_f32_e32 v49, v49, v42
	v_sub_f32_e32 v49, v49, v44
	v_add_f32_e32 v49, v49, v46
	v_mul_f32_e32 v50, v49, v219
	v_fmac_f32_e32 v50, v48, v211
	v_mul_f32_e32 v51, v48, v219
	v_fma_f32 v51, v49, v211, -v51
	v_cvt_pk_bf16_f32 v52, v50, v51
	ds_write_b16 v4, v52 offset:0
	ds_write_b16_d16_hi v4, v52 offset:4352
	v_sub_f32_e32 v48, v16, v24
	v_fmac_f32_e32 v48, 0xbec3ef15, v32
	v_fmac_f32_e32 v48, 0xbf3504f3, v33
	v_fmac_f32_e32 v48, 0x3f6c835e, v34
	v_fmac_f32_e32 v48, 0xbf6c835e, v36
	v_fmac_f32_e32 v48, 0x3f3504f3, v37
	v_fmac_f32_e32 v48, 0x3ec3ef15, v38
	v_mul_f32_e32 v49, 0xbf6c835e, v40
	v_fmac_f32_e32 v49, 0x3f3504f3, v41
	v_fmac_f32_e32 v49, 0x3ec3ef15, v42
	v_sub_f32_e32 v49, v49, v43
	v_fmac_f32_e32 v49, 0x3ec3ef15, v44
	v_fmac_f32_e32 v49, 0x3f3504f3, v45
	v_fmac_f32_e32 v49, 0xbf6c835e, v46
	v_mul_f32_e32 v50, v49, v220
	v_fmac_f32_e32 v50, v48, v212
	v_mul_f32_e32 v51, v48, v220
	v_fma_f32 v51, v49, v212, -v51
	v_cvt_pk_bf16_f32 v52, v50, v51
	ds_write_b16 v4, v52 offset:8704
	ds_write_b16_d16_hi v4, v52 offset:13056
	v_add_f32_e32 v48, v16, v24
	v_fmac_f32_e32 v48, 0xbf3504f3, v32
	v_fmac_f32_e32 v48, 0x3f3504f3, v34
	v_sub_f32_e32 v48, v48, v35
	v_fmac_f32_e32 v48, 0x3f3504f3, v36
	v_fmac_f32_e32 v48, 0xbf3504f3, v38
	v_mul_f32_e32 v49, 0xbf3504f3, v40
	v_add_f32_e32 v49, v49, v41
	v_fmac_f32_e32 v49, 0xbf3504f3, v42
	v_fmac_f32_e32 v49, 0x3f3504f3, v44
	v_sub_f32_e32 v49, v49, v45
	v_fmac_f32_e32 v49, 0x3f3504f3, v46
	v_mul_f32_e32 v50, v49, v221
	v_fmac_f32_e32 v50, v48, v213
	v_mul_f32_e32 v51, v48, v221
	v_fma_f32 v51, v49, v213, -v51
	v_cvt_pk_bf16_f32 v52, v50, v51
	ds_write_b16 v4, v52 offset:17408
	ds_write_b16_d16_hi v4, v52 offset:21760
	v_sub_f32_e32 v48, v16, v24
	v_fmac_f32_e32 v48, 0xbf6c835e, v32
	v_fmac_f32_e32 v48, 0x3f3504f3, v33
	v_fmac_f32_e32 v48, 0xbec3ef15, v34
	v_fmac_f32_e32 v48, 0x3ec3ef15, v36
	v_fmac_f32_e32 v48, 0xbf3504f3, v37
	v_fmac_f32_e32 v48, 0x3f6c835e, v38
	v_mul_f32_e32 v49, 0xbec3ef15, v40
	v_fmac_f32_e32 v49, 0x3f3504f3, v41
	v_fmac_f32_e32 v49, 0xbf6c835e, v42
	v_add_f32_e32 v49, v49, v43
	v_fmac_f32_e32 v49, 0xbf6c835e, v44
; __device__ __forceinline__ bf16_t f2bf(float f) { return (bf16_t)(cvt_pk_bf16(f, 0.f) & 0xffffu); }
; __device__ __forceinline__ void dft16_phase(const Ctx& X, const bf16_t* HN, bf16_t* GT) {
;     ...
;                 for (int e = 0; e < 8; ++e) { float re = 0.f, im = 0.f;
; #pragma unroll
;                     for (int a = 0; a < 16; ++a) { const unsigned wv = xin[a][e >> 1]; const float x = (e & 1) ? bf2f(wv >> 16) : bf2f(wv & 0xffffu); re += x * cw[a]; im -= x * sw[a]; }
;                     const float orr = re * tc - im * ts, oi = re * ts + im * tc;
;                     tile[((kl * 2 + 0) * 64 + cchunk * 8 + e) * 72 + i] = f2bf(orr); tile[((kl * 2 + 1) * 64 + cchunk * 8 + e) * 72 + i] = f2bf(oi); } }
	v_fmac_f32_e32 v49, 0x3f3504f3, v45
	v_fmac_f32_e32 v49, 0xbec3ef15, v46
	v_mul_f32_e32 v50, v49, v222
	v_fmac_f32_e32 v50, v48, v214
	v_mul_f32_e32 v51, v48, v222
	v_fma_f32 v51, v49, v214, -v51
	v_cvt_pk_bf16_f32 v52, v50, v51
	ds_write_b16 v4, v52 offset:26112
	ds_write_b16_d16_hi v4, v52 offset:30464
	v_add_f32_e32 v48, v16, v24
	v_sub_f32_e32 v48, v48, v32
	v_add_f32_e32 v48, v48, v33
	v_sub_f32_e32 v48, v48, v34
	v_add_f32_e32 v48, v48, v35
	v_sub_f32_e32 v48, v48, v36
	v_add_f32_e32 v48, v48, v37
	v_sub_f32_e32 v48, v48, v38
	v_mul_f32_e32 v50, v48, v215
	v_mul_f32_e32 v51, v48, v223
	v_sub_f32_e32 v51, 0, v51
	v_cvt_pk_bf16_f32 v52, v50, v51
	ds_write_b16 v4, v52 offset:34816
	ds_write_b16_d16_hi v4, v52 offset:39168
	v_and_b32_e32 v16, 0xffff0000, v64
	v_and_b32_e32 v17, 0xffff0000, v68
	v_and_b32_e32 v18, 0xffff0000, v72
	v_and_b32_e32 v19, 0xffff0000, v76
	v_and_b32_e32 v20, 0xffff0000, v80
	v_and_b32_e32 v21, 0xffff0000, v84
	v_and_b32_e32 v22, 0xffff0000, v88
	v_and_b32_e32 v23, 0xffff0000, v92
	v_and_b32_e32 v24, 0xffff0000, v96
	v_and_b32_e32 v25, 0xffff0000, v100
	v_and_b32_e32 v26, 0xffff0000, v104
	v_and_b32_e32 v27, 0xffff0000, v108
	v_and_b32_e32 v28, 0xffff0000, v112
	v_and_b32_e32 v29, 0xffff0000, v116
	v_and_b32_e32 v30, 0xffff0000, v120
	v_and_b32_e32 v31, 0xffff0000, v124
	v_add_f32_e32 v32, v17, v31
	v_sub_f32_e32 v40, v17, v31
	v_add_f32_e32 v33, v18, v30
	v_sub_f32_e32 v41, v18, v30
	v_add_f32_e32 v34, v19, v29
	v_sub_f32_e32 v42, v19, v29
	v_add_f32_e32 v35, v20, v28
	v_sub_f32_e32 v43, v20, v28
	v_add_f32_e32 v36, v21, v27
	v_sub_f32_e32 v44, v21, v27
	v_add_f32_e32 v37, v22, v26
	v_sub_f32_e32 v45, v22, v26
	v_add_f32_e32 v38, v23, v25
	v_sub_f32_e32 v46, v23, v25
	v_add_f32_e32 v48, v16, v24
	v_add_f32_e32 v48, v48, v32
	v_add_f32_e32 v48, v48, v33
	v_add_f32_e32 v48, v48, v34
	v_add_f32_e32 v48, v48, v35
	v_add_f32_e32 v48, v48, v36
	v_add_f32_e32 v48, v48, v37
	v_add_f32_e32 v48, v48, v38
	v_cvt_pk_bf16_f32 v52, v48, 0
	ds_write_b16 v3, v52 offset:136
	ds_write_b16_d16_hi v3, v52 offset:4488
	v_sub_f32_e32 v48, v16, v24
	v_fmac_f32_e32 v48, 0x3f6c835e, v32
	v_fmac_f32_e32 v48, 0x3f3504f3, v33
	v_fmac_f32_e32 v48, 0x3ec3ef15, v34
	v_fmac_f32_e32 v48, 0xbec3ef15, v36
	v_fmac_f32_e32 v48, 0xbf3504f3, v37
	v_fmac_f32_e32 v48, 0xbf6c835e, v38
	v_mul_f32_e32 v49, 0xbec3ef15, v40
	v_fmac_f32_e32 v49, 0xbf3504f3, v41
	v_fmac_f32_e32 v49, 0xbf6c835e, v42
	v_sub_f32_e32 v49, v49, v43
	v_fmac_f32_e32 v49, 0xbf6c835e, v44
	v_fmac_f32_e32 v49, 0xbf3504f3, v45
	v_fmac_f32_e32 v49, 0xbec3ef15, v46
	v_mul_f32_e32 v50, v49, v216
	v_fmac_f32_e32 v50, v48, v208
	v_mul_f32_e32 v51, v48, v216
	v_fma_f32 v51, v49, v208, -v51
	v_cvt_pk_bf16_f32 v52, v50, v51
	ds_write_b16 v3, v52 offset:8840
	ds_write_b16_d16_hi v3, v52 offset:13192
	v_add_f32_e32 v48, v16, v24
	v_fmac_f32_e32 v48, 0x3f3504f3, v32
	v_fmac_f32_e32 v48, 0xbf3504f3, v34
	v_sub_f32_e32 v48, v48, v35
	v_fmac_f32_e32 v48, 0xbf3504f3, v36
	v_fmac_f32_e32 v48, 0x3f3504f3, v38
	v_mul_f32_e32 v49, 0xbf3504f3, v40
	v_sub_f32_e32 v49, v49, v41
	v_fmac_f32_e32 v49, 0xbf3504f3, v42
	v_fmac_f32_e32 v49, 0x3f3504f3, v44
	v_add_f32_e32 v49, v49, v45
	v_fmac_f32_e32 v49, 0x3f3504f3, v46
	v_mul_f32_e32 v50, v49, v217
	v_fmac_f32_e32 v50, v48, v209
	v_mul_f32_e32 v51, v48, v217
	v_fma_f32 v51, v49, v209, -v51
	v_cvt_pk_bf16_f32 v52, v50, v51
	ds_write_b16 v3, v52 offset:17544
	ds_write_b16_d16_hi v3, v52 offset:21896
	v_sub_f32_e32 v48, v16, v24
	v_fmac_f32_e32 v48, 0x3ec3ef15, v32
	v_fmac_f32_e32 v48, 0xbf3504f3, v33
	v_fmac_f32_e32 v48, 0xbf6c835e, v34
	v_fmac_f32_e32 v48, 0x3f6c835e, v36
	v_fmac_f32_e32 v48, 0x3f3504f3, v37
	v_fmac_f32_e32 v48, 0xbec3ef15, v38
	v_mul_f32_e32 v49, 0xbf6c835e, v40
	v_fmac_f32_e32 v49, 0xbf3504f3, v41
	v_fmac_f32_e32 v49, 0x3ec3ef15, v42
	v_add_f32_e32 v49, v49, v43
	v_fmac_f32_e32 v49, 0x3ec3ef15, v44
	v_fmac_f32_e32 v49, 0xbf3504f3, v45
	v_fmac_f32_e32 v49, 0xbf6c835e, v46
	v_mul_f32_e32 v50, v49, v218
	v_fmac_f32_e32 v50, v48, v210
	v_mul_f32_e32 v51, v48, v218
	v_fma_f32 v51, v49, v210, -v51
	v_cvt_pk_bf16_f32 v52, v50, v51
	ds_write_b16 v3, v52 offset:26248
	ds_write_b16_d16_hi v3, v52 offset:30600
	v_add_f32_e32 v48, v16, v24
	v_sub_f32_e32 v48, v48, v33
	v_add_f32_e32 v48, v48, v35
	v_sub_f32_e32 v48, v48, v37
	v_sub_f32_e32 v49, 0, v40
	v_add_f32_e32 v49, v49, v42
	v_sub_f32_e32 v49, v49, v44
	v_add_f32_e32 v49, v49, v46
	v_mul_f32_e32 v50, v49, v219
	v_fmac_f32_e32 v50, v48, v211
	v_mul_f32_e32 v51, v48, v219
	v_fma_f32 v51, v49, v211, -v51
	v_cvt_pk_bf16_f32 v52, v50, v51
	ds_write_b16 v4, v52 offset:136
	ds_write_b16_d16_hi v4, v52 offset:4488
	v_sub_f32_e32 v48, v16, v24
	v_fmac_f32_e32 v48, 0xbec3ef15, v32
	v_fmac_f32_e32 v48, 0xbf3504f3, v33
	v_fmac_f32_e32 v48, 0x3f6c835e, v34
	v_fmac_f32_e32 v48, 0xbf6c835e, v36
	v_fmac_f32_e32 v48, 0x3f3504f3, v37
	v_fmac_f32_e32 v48, 0x3ec3ef15, v38
	v_mul_f32_e32 v49, 0xbf6c835e, v40
	v_fmac_f32_e32 v49, 0x3f3504f3, v41
	v_fmac_f32_e32 v49, 0x3ec3ef15, v42
	v_sub_f32_e32 v49, v49, v43
	v_fmac_f32_e32 v49, 0x3ec3ef15, v44
	v_fmac_f32_e32 v49, 0x3f3504f3, v45
	v_fmac_f32_e32 v49, 0xbf6c835e, v46
	v_mul_f32_e32 v50, v49, v220
	v_fmac_f32_e32 v50, v48, v212
	v_mul_f32_e32 v51, v48, v220
	v_fma_f32 v51, v49, v212, -v51
	v_cvt_pk_bf16_f32 v52, v50, v51
	ds_write_b16 v4, v52 offset:8840
	ds_write_b16_d16_hi v4, v52 offset:13192
	v_add_f32_e32 v48, v16, v24
	v_fmac_f32_e32 v48, 0xbf3504f3, v32
	v_fmac_f32_e32 v48, 0x3f3504f3, v34
	v_sub_f32_e32 v48, v48, v35
	v_fmac_f32_e32 v48, 0x3f3504f3, v36
	v_fmac_f32_e32 v48, 0xbf3504f3, v38
	v_mul_f32_e32 v49, 0xbf3504f3, v40
	v_add_f32_e32 v49, v49, v41
; __device__ __forceinline__ bf16_t f2bf(float f) { return (bf16_t)(cvt_pk_bf16(f, 0.f) & 0xffffu); }
; __device__ __forceinline__ void dft16_phase(const Ctx& X, const bf16_t* HN, bf16_t* GT) {
;     ...
;                 for (int e = 0; e < 8; ++e) { float re = 0.f, im = 0.f;
; #pragma unroll
;                     for (int a = 0; a < 16; ++a) { const unsigned wv = xin[a][e >> 1]; const float x = (e & 1) ? bf2f(wv >> 16) : bf2f(wv & 0xffffu); re += x * cw[a]; im -= x * sw[a]; }
;                     const float orr = re * tc - im * ts, oi = re * ts + im * tc;
;                     tile[((kl * 2 + 0) * 64 + cchunk * 8 + e) * 72 + i] = f2bf(orr); tile[((kl * 2 + 1) * 64 + cchunk * 8 + e) * 72 + i] = f2bf(oi); } }
	v_fmac_f32_e32 v49, 0xbf3504f3, v42
	v_fmac_f32_e32 v49, 0x3f3504f3, v44
	v_sub_f32_e32 v49, v49, v45
	v_fmac_f32_e32 v49, 0x3f3504f3, v46
	v_mul_f32_e32 v50, v49, v221
	v_fmac_f32_e32 v50, v48, v213
	v_mul_f32_e32 v51, v48, v221
	v_fma_f32 v51, v49, v213, -v51
	v_cvt_pk_bf16_f32 v52, v50, v51
	ds_write_b16 v4, v52 offset:17544
	ds_write_b16_d16_hi v4, v52 offset:21896
	v_sub_f32_e32 v48, v16, v24
	v_fmac_f32_e32 v48, 0xbf6c835e, v32
	v_fmac_f32_e32 v48, 0x3f3504f3, v33
	v_fmac_f32_e32 v48, 0xbec3ef15, v34
	v_fmac_f32_e32 v48, 0x3ec3ef15, v36
	v_fmac_f32_e32 v48, 0xbf3504f3, v37
	v_fmac_f32_e32 v48, 0x3f6c835e, v38
	v_mul_f32_e32 v49, 0xbec3ef15, v40
	v_fmac_f32_e32 v49, 0x3f3504f3, v41
	v_fmac_f32_e32 v49, 0xbf6c835e, v42
	v_add_f32_e32 v49, v49, v43
	v_fmac_f32_e32 v49, 0xbf6c835e, v44
	v_fmac_f32_e32 v49, 0x3f3504f3, v45
	v_fmac_f32_e32 v49, 0xbec3ef15, v46
	v_mul_f32_e32 v50, v49, v222
	v_fmac_f32_e32 v50, v48, v214
	v_mul_f32_e32 v51, v48, v222
	v_fma_f32 v51, v49, v214, -v51
	v_cvt_pk_bf16_f32 v52, v50, v51
	ds_write_b16 v4, v52 offset:26248
	ds_write_b16_d16_hi v4, v52 offset:30600
	v_add_f32_e32 v48, v16, v24
	v_sub_f32_e32 v48, v48, v32
	v_add_f32_e32 v48, v48, v33
	v_sub_f32_e32 v48, v48, v34
	v_add_f32_e32 v48, v48, v35
	v_sub_f32_e32 v48, v48, v36
	v_add_f32_e32 v48, v48, v37
	v_sub_f32_e32 v48, v48, v38
	v_mul_f32_e32 v50, v48, v215
	v_mul_f32_e32 v51, v48, v223
	v_sub_f32_e32 v51, 0, v51
	v_cvt_pk_bf16_f32 v52, v50, v51
	ds_write_b16 v4, v52 offset:34952
	ds_write_b16_d16_hi v4, v52 offset:39304
	v_lshlrev_b32_e32 v16, 16, v65
	v_lshlrev_b32_e32 v17, 16, v69
	v_lshlrev_b32_e32 v18, 16, v73
	v_lshlrev_b32_e32 v19, 16, v77
	v_lshlrev_b32_e32 v20, 16, v81
	v_lshlrev_b32_e32 v21, 16, v85
	v_lshlrev_b32_e32 v22, 16, v89
	v_lshlrev_b32_e32 v23, 16, v93
	v_lshlrev_b32_e32 v24, 16, v97
	v_lshlrev_b32_e32 v25, 16, v101
	v_lshlrev_b32_e32 v26, 16, v105
	v_lshlrev_b32_e32 v27, 16, v109
	v_lshlrev_b32_e32 v28, 16, v113
	v_lshlrev_b32_e32 v29, 16, v117
	v_lshlrev_b32_e32 v30, 16, v121
	v_lshlrev_b32_e32 v31, 16, v125
	v_add_f32_e32 v32, v17, v31
	v_sub_f32_e32 v40, v17, v31
	v_add_f32_e32 v33, v18, v30
	v_sub_f32_e32 v41, v18, v30
	v_add_f32_e32 v34, v19, v29
	v_sub_f32_e32 v42, v19, v29
	v_add_f32_e32 v35, v20, v28
	v_sub_f32_e32 v43, v20, v28
	v_add_f32_e32 v36, v21, v27
	v_sub_f32_e32 v44, v21, v27
	v_add_f32_e32 v37, v22, v26
	v_sub_f32_e32 v45, v22, v26
	v_add_f32_e32 v38, v23, v25
	v_sub_f32_e32 v46, v23, v25
	v_add_f32_e32 v48, v16, v24
	v_add_f32_e32 v48, v48, v32
	v_add_f32_e32 v48, v48, v33
	v_add_f32_e32 v48, v48, v34
	v_add_f32_e32 v48, v48, v35
	v_add_f32_e32 v48, v48, v36
	v_add_f32_e32 v48, v48, v37
	v_add_f32_e32 v48, v48, v38
	v_cvt_pk_bf16_f32 v52, v48, 0
	ds_write_b16 v3, v52 offset:272
	ds_write_b16_d16_hi v3, v52 offset:4624
	v_sub_f32_e32 v48, v16, v24
	v_fmac_f32_e32 v48, 0x3f6c835e, v32
	v_fmac_f32_e32 v48, 0x3f3504f3, v33
	v_fmac_f32_e32 v48, 0x3ec3ef15, v34
	v_fmac_f32_e32 v48, 0xbec3ef15, v36
	v_fmac_f32_e32 v48, 0xbf3504f3, v37
	v_fmac_f32_e32 v48, 0xbf6c835e, v38
	v_mul_f32_e32 v49, 0xbec3ef15, v40
	v_fmac_f32_e32 v49, 0xbf3504f3, v41
	v_fmac_f32_e32 v49, 0xbf6c835e, v42
	v_sub_f32_e32 v49, v49, v43
	v_fmac_f32_e32 v49, 0xbf6c835e, v44
	v_fmac_f32_e32 v49, 0xbf3504f3, v45
	v_fmac_f32_e32 v49, 0xbec3ef15, v46
	v_mul_f32_e32 v50, v49, v216
	v_fmac_f32_e32 v50, v48, v208
	v_mul_f32_e32 v51, v48, v216
	v_fma_f32 v51, v49, v208, -v51
	v_cvt_pk_bf16_f32 v52, v50, v51
	ds_write_b16 v3, v52 offset:8976
	ds_write_b16_d16_hi v3, v52 offset:13328
	v_add_f32_e32 v48, v16, v24
	v_fmac_f32_e32 v48, 0x3f3504f3, v32
	v_fmac_f32_e32 v48, 0xbf3504f3, v34
	v_sub_f32_e32 v48, v48, v35
	v_fmac_f32_e32 v48, 0xbf3504f3, v36
	v_fmac_f32_e32 v48, 0x3f3504f3, v38
	v_mul_f32_e32 v49, 0xbf3504f3, v40
	v_sub_f32_e32 v49, v49, v41
	v_fmac_f32_e32 v49, 0xbf3504f3, v42
	v_fmac_f32_e32 v49, 0x3f3504f3, v44
	v_add_f32_e32 v49, v49, v45
	v_fmac_f32_e32 v49, 0x3f3504f3, v46
	v_mul_f32_e32 v50, v49, v217
	v_fmac_f32_e32 v50, v48, v209
	v_mul_f32_e32 v51, v48, v217
	v_fma_f32 v51, v49, v209, -v51
	v_cvt_pk_bf16_f32 v52, v50, v51
	ds_write_b16 v3, v52 offset:17680
	ds_write_b16_d16_hi v3, v52 offset:22032
	v_sub_f32_e32 v48, v16, v24
	v_fmac_f32_e32 v48, 0x3ec3ef15, v32
	v_fmac_f32_e32 v48, 0xbf3504f3, v33
	v_fmac_f32_e32 v48, 0xbf6c835e, v34
	v_fmac_f32_e32 v48, 0x3f6c835e, v36
	v_fmac_f32_e32 v48, 0x3f3504f3, v37
	v_fmac_f32_e32 v48, 0xbec3ef15, v38
	v_mul_f32_e32 v49, 0xbf6c835e, v40
	v_fmac_f32_e32 v49, 0xbf3504f3, v41
	v_fmac_f32_e32 v49, 0x3ec3ef15, v42
	v_add_f32_e32 v49, v49, v43
	v_fmac_f32_e32 v49, 0x3ec3ef15, v44
	v_fmac_f32_e32 v49, 0xbf3504f3, v45
	v_fmac_f32_e32 v49, 0xbf6c835e, v46
	v_mul_f32_e32 v50, v49, v218
	v_fmac_f32_e32 v50, v48, v210
	v_mul_f32_e32 v51, v48, v218
	v_fma_f32 v51, v49, v210, -v51
	v_cvt_pk_bf16_f32 v52, v50, v51
	ds_write_b16 v3, v52 offset:26384
	ds_write_b16_d16_hi v3, v52 offset:30736
	v_add_f32_e32 v48, v16, v24
	v_sub_f32_e32 v48, v48, v33
	v_add_f32_e32 v48, v48, v35
	v_sub_f32_e32 v48, v48, v37
	v_sub_f32_e32 v49, 0, v40
	v_add_f32_e32 v49, v49, v42
	v_sub_f32_e32 v49, v49, v44
	v_add_f32_e32 v49, v49, v46
	v_mul_f32_e32 v50, v49, v219
	v_fmac_f32_e32 v50, v48, v211
	v_mul_f32_e32 v51, v48, v219
	v_fma_f32 v51, v49, v211, -v51
	v_cvt_pk_bf16_f32 v52, v50, v51
	ds_write_b16 v4, v52 offset:272
	ds_write_b16_d16_hi v4, v52 offset:4624
	v_sub_f32_e32 v48, v16, v24
	v_fmac_f32_e32 v48, 0xbec3ef15, v32
	v_fmac_f32_e32 v48, 0xbf3504f3, v33
	v_fmac_f32_e32 v48, 0x3f6c835e, v34
	v_fmac_f32_e32 v48, 0xbf6c835e, v36
	v_fmac_f32_e32 v48, 0x3f3504f3, v37
	v_fmac_f32_e32 v48, 0x3ec3ef15, v38
	v_mul_f32_e32 v49, 0xbf6c835e, v40
; __device__ __forceinline__ bf16_t f2bf(float f) { return (bf16_t)(cvt_pk_bf16(f, 0.f) & 0xffffu); }
; __device__ __forceinline__ void dft16_phase(const Ctx& X, const bf16_t* HN, bf16_t* GT) {
;     ...
;                 for (int e = 0; e < 8; ++e) { float re = 0.f, im = 0.f;
; #pragma unroll
;                     for (int a = 0; a < 16; ++a) { const unsigned wv = xin[a][e >> 1]; const float x = (e & 1) ? bf2f(wv >> 16) : bf2f(wv & 0xffffu); re += x * cw[a]; im -= x * sw[a]; }
;                     const float orr = re * tc - im * ts, oi = re * ts + im * tc;
;                     tile[((kl * 2 + 0) * 64 + cchunk * 8 + e) * 72 + i] = f2bf(orr); tile[((kl * 2 + 1) * 64 + cchunk * 8 + e) * 72 + i] = f2bf(oi); } }
	v_fmac_f32_e32 v49, 0x3f3504f3, v41
	v_fmac_f32_e32 v49, 0x3ec3ef15, v42
	v_sub_f32_e32 v49, v49, v43
	v_fmac_f32_e32 v49, 0x3ec3ef15, v44
	v_fmac_f32_e32 v49, 0x3f3504f3, v45
	v_fmac_f32_e32 v49, 0xbf6c835e, v46
	v_mul_f32_e32 v50, v49, v220
	v_fmac_f32_e32 v50, v48, v212
	v_mul_f32_e32 v51, v48, v220
	v_fma_f32 v51, v49, v212, -v51
	v_cvt_pk_bf16_f32 v52, v50, v51
	ds_write_b16 v4, v52 offset:8976
	ds_write_b16_d16_hi v4, v52 offset:13328
	v_add_f32_e32 v48, v16, v24
	v_fmac_f32_e32 v48, 0xbf3504f3, v32
	v_fmac_f32_e32 v48, 0x3f3504f3, v34
	v_sub_f32_e32 v48, v48, v35
	v_fmac_f32_e32 v48, 0x3f3504f3, v36
	v_fmac_f32_e32 v48, 0xbf3504f3, v38
	v_mul_f32_e32 v49, 0xbf3504f3, v40
	v_add_f32_e32 v49, v49, v41
	v_fmac_f32_e32 v49, 0xbf3504f3, v42
	v_fmac_f32_e32 v49, 0x3f3504f3, v44
	v_sub_f32_e32 v49, v49, v45
	v_fmac_f32_e32 v49, 0x3f3504f3, v46
	v_mul_f32_e32 v50, v49, v221
	v_fmac_f32_e32 v50, v48, v213
	v_mul_f32_e32 v51, v48, v221
	v_fma_f32 v51, v49, v213, -v51
	v_cvt_pk_bf16_f32 v52, v50, v51
	ds_write_b16 v4, v52 offset:17680
	ds_write_b16_d16_hi v4, v52 offset:22032
	v_sub_f32_e32 v48, v16, v24
	v_fmac_f32_e32 v48, 0xbf6c835e, v32
	v_fmac_f32_e32 v48, 0x3f3504f3, v33
	v_fmac_f32_e32 v48, 0xbec3ef15, v34
	v_fmac_f32_e32 v48, 0x3ec3ef15, v36
	v_fmac_f32_e32 v48, 0xbf3504f3, v37
	v_fmac_f32_e32 v48, 0x3f6c835e, v38
	v_mul_f32_e32 v49, 0xbec3ef15, v40
	v_fmac_f32_e32 v49, 0x3f3504f3, v41
	v_fmac_f32_e32 v49, 0xbf6c835e, v42
	v_add_f32_e32 v49, v49, v43
	v_fmac_f32_e32 v49, 0xbf6c835e, v44
	v_fmac_f32_e32 v49, 0x3f3504f3, v45
	v_fmac_f32_e32 v49, 0xbec3ef15, v46
	v_mul_f32_e32 v50, v49, v222
	v_fmac_f32_e32 v50, v48, v214
	v_mul_f32_e32 v51, v48, v222
	v_fma_f32 v51, v49, v214, -v51
	v_cvt_pk_bf16_f32 v52, v50, v51
	ds_write_b16 v4, v52 offset:26384
	ds_write_b16_d16_hi v4, v52 offset:30736
	v_add_f32_e32 v48, v16, v24
	v_sub_f32_e32 v48, v48, v32
	v_add_f32_e32 v48, v48, v33
	v_sub_f32_e32 v48, v48, v34
	v_add_f32_e32 v48, v48, v35
	v_sub_f32_e32 v48, v48, v36
	v_add_f32_e32 v48, v48, v37
	v_sub_f32_e32 v48, v48, v38
	v_mul_f32_e32 v50, v48, v215
	v_mul_f32_e32 v51, v48, v223
	v_sub_f32_e32 v51, 0, v51
	v_cvt_pk_bf16_f32 v52, v50, v51
	ds_write_b16 v4, v52 offset:35088
	ds_write_b16_d16_hi v4, v52 offset:39440
	v_and_b32_e32 v16, 0xffff0000, v65
	v_and_b32_e32 v17, 0xffff0000, v69
	v_and_b32_e32 v18, 0xffff0000, v73
	v_and_b32_e32 v19, 0xffff0000, v77
	v_and_b32_e32 v20, 0xffff0000, v81
	v_and_b32_e32 v21, 0xffff0000, v85
	v_and_b32_e32 v22, 0xffff0000, v89
	v_and_b32_e32 v23, 0xffff0000, v93
	v_and_b32_e32 v24, 0xffff0000, v97
	v_and_b32_e32 v25, 0xffff0000, v101
	v_and_b32_e32 v26, 0xffff0000, v105
	v_and_b32_e32 v27, 0xffff0000, v109
	v_and_b32_e32 v28, 0xffff0000, v113
	v_and_b32_e32 v29, 0xffff0000, v117
	v_and_b32_e32 v30, 0xffff0000, v121
	v_and_b32_e32 v31, 0xffff0000, v125
	v_add_f32_e32 v32, v17, v31
	v_sub_f32_e32 v40, v17, v31
	v_add_f32_e32 v33, v18, v30
	v_sub_f32_e32 v41, v18, v30
	v_add_f32_e32 v34, v19, v29
	v_sub_f32_e32 v42, v19, v29
	v_add_f32_e32 v35, v20, v28
	v_sub_f32_e32 v43, v20, v28
	v_add_f32_e32 v36, v21, v27
	v_sub_f32_e32 v44, v21, v27
	v_add_f32_e32 v37, v22, v26
	v_sub_f32_e32 v45, v22, v26
	v_add_f32_e32 v38, v23, v25
	v_sub_f32_e32 v46, v23, v25
	v_add_f32_e32 v48, v16, v24
	v_add_f32_e32 v48, v48, v32
	v_add_f32_e32 v48, v48, v33
	v_add_f32_e32 v48, v48, v34
	v_add_f32_e32 v48, v48, v35
	v_add_f32_e32 v48, v48, v36
	v_add_f32_e32 v48, v48, v37
	v_add_f32_e32 v48, v48, v38
	v_cvt_pk_bf16_f32 v52, v48, 0
	ds_write_b16 v3, v52 offset:408
	ds_write_b16_d16_hi v3, v52 offset:4760
	v_sub_f32_e32 v48, v16, v24
	v_fmac_f32_e32 v48, 0x3f6c835e, v32
	v_fmac_f32_e32 v48, 0x3f3504f3, v33
	v_fmac_f32_e32 v48, 0x3ec3ef15, v34
	v_fmac_f32_e32 v48, 0xbec3ef15, v36
	v_fmac_f32_e32 v48, 0xbf3504f3, v37
	v_fmac_f32_e32 v48, 0xbf6c835e, v38
	v_mul_f32_e32 v49, 0xbec3ef15, v40
	v_fmac_f32_e32 v49, 0xbf3504f3, v41
	v_fmac_f32_e32 v49, 0xbf6c835e, v42
	v_sub_f32_e32 v49, v49, v43
	v_fmac_f32_e32 v49, 0xbf6c835e, v44
	v_fmac_f32_e32 v49, 0xbf3504f3, v45
	v_fmac_f32_e32 v49, 0xbec3ef15, v46
	v_mul_f32_e32 v50, v49, v216
	v_fmac_f32_e32 v50, v48, v208
	v_mul_f32_e32 v51, v48, v216
	v_fma_f32 v51, v49, v208, -v51
	v_cvt_pk_bf16_f32 v52, v50, v51
	ds_write_b16 v3, v52 offset:9112
	ds_write_b16_d16_hi v3, v52 offset:13464
	v_add_f32_e32 v48, v16, v24
	v_fmac_f32_e32 v48, 0x3f3504f3, v32
	v_fmac_f32_e32 v48, 0xbf3504f3, v34
	v_sub_f32_e32 v48, v48, v35
	v_fmac_f32_e32 v48, 0xbf3504f3, v36
	v_fmac_f32_e32 v48, 0x3f3504f3, v38
	v_mul_f32_e32 v49, 0xbf3504f3, v40
	v_sub_f32_e32 v49, v49, v41
	v_fmac_f32_e32 v49, 0xbf3504f3, v42
	v_fmac_f32_e32 v49, 0x3f3504f3, v44
	v_add_f32_e32 v49, v49, v45
	v_fmac_f32_e32 v49, 0x3f3504f3, v46
	v_mul_f32_e32 v50, v49, v217
	v_fmac_f32_e32 v50, v48, v209
	v_mul_f32_e32 v51, v48, v217
	v_fma_f32 v51, v49, v209, -v51
	v_cvt_pk_bf16_f32 v52, v50, v51
	ds_write_b16 v3, v52 offset:17816
	ds_write_b16_d16_hi v3, v52 offset:22168
	v_sub_f32_e32 v48, v16, v24
	v_fmac_f32_e32 v48, 0x3ec3ef15, v32
	v_fmac_f32_e32 v48, 0xbf3504f3, v33
	v_fmac_f32_e32 v48, 0xbf6c835e, v34
	v_fmac_f32_e32 v48, 0x3f6c835e, v36
	v_fmac_f32_e32 v48, 0x3f3504f3, v37
	v_fmac_f32_e32 v48, 0xbec3ef15, v38
	v_mul_f32_e32 v49, 0xbf6c835e, v40
	v_fmac_f32_e32 v49, 0xbf3504f3, v41
	v_fmac_f32_e32 v49, 0x3ec3ef15, v42
	v_add_f32_e32 v49, v49, v43
	v_fmac_f32_e32 v49, 0x3ec3ef15, v44
	v_fmac_f32_e32 v49, 0xbf3504f3, v45
	v_fmac_f32_e32 v49, 0xbf6c835e, v46
	v_mul_f32_e32 v50, v49, v218
	v_fmac_f32_e32 v50, v48, v210
	v_mul_f32_e32 v51, v48, v218
	v_fma_f32 v51, v49, v210, -v51
	v_cvt_pk_bf16_f32 v52, v50, v51
	ds_write_b16 v3, v52 offset:26520
; __device__ __forceinline__ bf16_t f2bf(float f) { return (bf16_t)(cvt_pk_bf16(f, 0.f) & 0xffffu); }
; __device__ __forceinline__ void dft16_phase(const Ctx& X, const bf16_t* HN, bf16_t* GT) {
;     ...
;                 for (int e = 0; e < 8; ++e) { float re = 0.f, im = 0.f;
; #pragma unroll
;                     for (int a = 0; a < 16; ++a) { const unsigned wv = xin[a][e >> 1]; const float x = (e & 1) ? bf2f(wv >> 16) : bf2f(wv & 0xffffu); re += x * cw[a]; im -= x * sw[a]; }
;                     const float orr = re * tc - im * ts, oi = re * ts + im * tc;
;                     tile[((kl * 2 + 0) * 64 + cchunk * 8 + e) * 72 + i] = f2bf(orr); tile[((kl * 2 + 1) * 64 + cchunk * 8 + e) * 72 + i] = f2bf(oi); } }
;             __syncthreads();
; #pragma unroll
;             for (int q = 0; q < 8; ++q) { const int cid = q * 512 + X.tid, row = cid >> 3, c8 = cid & 7, kl = row >> 7, ri = (row >> 6) & 1, ch = row & 63;
;                 if (kq * 4 + kl > 8) continue;
;                 const u32x4 v = *(const u32x4*)(tile + row * 72 + c8 * 8);
;                 *(u32x4*)(GT + ((size_t)(b * 9 + kq * 4 + kl) * 1024 + ch0 + ch) * 512 + ri * 256 + b0 + c8 * 8) = v; }
	ds_write_b16_d16_hi v3, v52 offset:30872
	v_add_f32_e32 v48, v16, v24
	v_sub_f32_e32 v48, v48, v33
	v_add_f32_e32 v48, v48, v35
	v_sub_f32_e32 v48, v48, v37
	v_sub_f32_e32 v49, 0, v40
	v_add_f32_e32 v49, v49, v42
	v_sub_f32_e32 v49, v49, v44
	v_add_f32_e32 v49, v49, v46
	v_mul_f32_e32 v50, v49, v219
	v_fmac_f32_e32 v50, v48, v211
	v_mul_f32_e32 v51, v48, v219
	v_fma_f32 v51, v49, v211, -v51
	v_cvt_pk_bf16_f32 v52, v50, v51
	ds_write_b16 v4, v52 offset:408
	ds_write_b16_d16_hi v4, v52 offset:4760
	v_sub_f32_e32 v48, v16, v24
	v_fmac_f32_e32 v48, 0xbec3ef15, v32
	v_fmac_f32_e32 v48, 0xbf3504f3, v33
	v_fmac_f32_e32 v48, 0x3f6c835e, v34
	v_fmac_f32_e32 v48, 0xbf6c835e, v36
	v_fmac_f32_e32 v48, 0x3f3504f3, v37
	v_fmac_f32_e32 v48, 0x3ec3ef15, v38
	v_mul_f32_e32 v49, 0xbf6c835e, v40
	v_fmac_f32_e32 v49, 0x3f3504f3, v41
	v_fmac_f32_e32 v49, 0x3ec3ef15, v42
	v_sub_f32_e32 v49, v49, v43
	v_fmac_f32_e32 v49, 0x3ec3ef15, v44
	v_fmac_f32_e32 v49, 0x3f3504f3, v45
	v_fmac_f32_e32 v49, 0xbf6c835e, v46
	v_mul_f32_e32 v50, v49, v220
	v_fmac_f32_e32 v50, v48, v212
	v_mul_f32_e32 v51, v48, v220
	v_fma_f32 v51, v49, v212, -v51
	v_cvt_pk_bf16_f32 v52, v50, v51
	ds_write_b16 v4, v52 offset:9112
	ds_write_b16_d16_hi v4, v52 offset:13464
	v_add_f32_e32 v48, v16, v24
	v_fmac_f32_e32 v48, 0xbf3504f3, v32
	v_fmac_f32_e32 v48, 0x3f3504f3, v34
	v_sub_f32_e32 v48, v48, v35
	v_fmac_f32_e32 v48, 0x3f3504f3, v36
	v_fmac_f32_e32 v48, 0xbf3504f3, v38
	v_mul_f32_e32 v49, 0xbf3504f3, v40
	v_add_f32_e32 v49, v49, v41
	v_fmac_f32_e32 v49, 0xbf3504f3, v42
	v_fmac_f32_e32 v49, 0x3f3504f3, v44
	v_sub_f32_e32 v49, v49, v45
	v_fmac_f32_e32 v49, 0x3f3504f3, v46
	v_mul_f32_e32 v50, v49, v221
	v_fmac_f32_e32 v50, v48, v213
	v_mul_f32_e32 v51, v48, v221
	v_fma_f32 v51, v49, v213, -v51
	v_cvt_pk_bf16_f32 v52, v50, v51
	ds_write_b16 v4, v52 offset:17816
	ds_write_b16_d16_hi v4, v52 offset:22168
	v_sub_f32_e32 v48, v16, v24
	v_fmac_f32_e32 v48, 0xbf6c835e, v32
	v_fmac_f32_e32 v48, 0x3f3504f3, v33
	v_fmac_f32_e32 v48, 0xbec3ef15, v34
	v_fmac_f32_e32 v48, 0x3ec3ef15, v36
	v_fmac_f32_e32 v48, 0xbf3504f3, v37
	v_fmac_f32_e32 v48, 0x3f6c835e, v38
	v_mul_f32_e32 v49, 0xbec3ef15, v40
	v_fmac_f32_e32 v49, 0x3f3504f3, v41
	v_fmac_f32_e32 v49, 0xbf6c835e, v42
	v_add_f32_e32 v49, v49, v43
	v_fmac_f32_e32 v49, 0xbf6c835e, v44
	v_fmac_f32_e32 v49, 0x3f3504f3, v45
	v_fmac_f32_e32 v49, 0xbec3ef15, v46
	v_mul_f32_e32 v50, v49, v222
	v_fmac_f32_e32 v50, v48, v214
	v_mul_f32_e32 v51, v48, v222
	v_fma_f32 v51, v49, v214, -v51
	v_cvt_pk_bf16_f32 v52, v50, v51
	ds_write_b16 v4, v52 offset:26520
	ds_write_b16_d16_hi v4, v52 offset:30872
	v_add_f32_e32 v48, v16, v24
	v_sub_f32_e32 v48, v48, v32
	v_add_f32_e32 v48, v48, v33
	v_sub_f32_e32 v48, v48, v34
	v_add_f32_e32 v48, v48, v35
	v_sub_f32_e32 v48, v48, v36
	v_add_f32_e32 v48, v48, v37
	v_sub_f32_e32 v48, v48, v38
	v_mul_f32_e32 v50, v48, v215
	v_mul_f32_e32 v51, v48, v223
	v_sub_f32_e32 v51, 0, v51
	v_cvt_pk_bf16_f32 v52, v50, v51
	ds_write_b16 v4, v52 offset:35224
	ds_write_b16_d16_hi v4, v52 offset:39576
	s_waitcnt lgkmcnt(0)
	s_barrier
	s_add_u32 s8, s26, 0
	s_addc_u32 s9, s27, 0
	ds_read_b64 v[20:21], v5 offset:0
	ds_read_b64 v[22:23], v5 offset:8
	ds_read_b64 v[24:25], v5 offset:8704
	ds_read_b64 v[26:27], v5 offset:8712
	ds_read_b64 v[28:29], v5 offset:17408
	ds_read_b64 v[30:31], v5 offset:17416
	s_waitcnt lgkmcnt(4)
	global_store_dwordx4 v7, v[20:23], s[8:9]
	s_add_u32 s8, s8, 0x100000
	s_addc_u32 s9, s9, 0
	ds_read_b64 v[20:21], v5 offset:26112
	ds_read_b64 v[22:23], v5 offset:26120
	s_waitcnt lgkmcnt(4)
	global_store_dwordx4 v7, v[24:27], s[8:9]
	s_add_u32 s8, s8, 0x100000
	s_addc_u32 s9, s9, 0
	ds_read_b64 v[24:25], v6 offset:0
	ds_read_b64 v[26:27], v6 offset:8
	s_waitcnt lgkmcnt(4)
	global_store_dwordx4 v7, v[28:31], s[8:9]
	s_add_u32 s8, s8, 0x100000
	s_addc_u32 s9, s9, 0
	ds_read_b64 v[28:29], v6 offset:8704
	ds_read_b64 v[30:31], v6 offset:8712
	s_waitcnt lgkmcnt(4)
	global_store_dwordx4 v7, v[20:23], s[8:9]
	s_add_u32 s8, s8, 0x100000
	s_addc_u32 s9, s9, 0
	ds_read_b64 v[20:21], v6 offset:17408
	ds_read_b64 v[22:23], v6 offset:17416
	s_waitcnt lgkmcnt(4)
	global_store_dwordx4 v7, v[24:27], s[8:9]
	s_add_u32 s8, s8, 0x100000
	s_addc_u32 s9, s9, 0
	ds_read_b64 v[24:25], v6 offset:26112
	ds_read_b64 v[26:27], v6 offset:26120
	s_waitcnt lgkmcnt(4)
	global_store_dwordx4 v7, v[28:31], s[8:9]
	s_add_u32 s8, s8, 0x100000
	s_addc_u32 s9, s9, 0
	ds_read_b64 v[28:29], v6 offset:34816
	ds_read_b64 v[30:31], v6 offset:34824
	s_waitcnt lgkmcnt(4)
	global_store_dwordx4 v7, v[20:23], s[8:9]
	s_add_u32 s8, s8, 0x100000
	s_addc_u32 s9, s9, 0
	s_waitcnt lgkmcnt(2)
	global_store_dwordx4 v7, v[24:27], s[8:9]
	s_add_u32 s8, s8, 0x100000
	s_addc_u32 s9, s9, 0
	s_waitcnt lgkmcnt(0)
	global_store_dwordx4 v7, v[28:31], s[8:9]
	s_barrier
; __device__ __forceinline__ bf16_t f2bf(float f) { return (bf16_t)(cvt_pk_bf16(f, 0.f) & 0xffffu); }
; __device__ __forceinline__ void dft16_phase(const Ctx& X, const bf16_t* HN, bf16_t* GT) {
;     ...
;                 for (int e = 0; e < 8; ++e) { float re = 0.f, im = 0.f;
; #pragma unroll
;                     for (int a = 0; a < 16; ++a) { const unsigned wv = xin[a][e >> 1]; const float x = (e & 1) ? bf2f(wv >> 16) : bf2f(wv & 0xffffu); re += x * cw[a]; im -= x * sw[a]; }
;                     const float orr = re * tc - im * ts, oi = re * ts + im * tc;
;                     tile[((kl * 2 + 0) * 64 + cchunk * 8 + e) * 72 + i] = f2bf(orr); tile[((kl * 2 + 1) * 64 + cchunk * 8 + e) * 72 + i] = f2bf(oi); } }
	v_lshlrev_b32_e32 v16, 16, v66
	v_lshlrev_b32_e32 v17, 16, v70
	v_lshlrev_b32_e32 v18, 16, v74
	v_lshlrev_b32_e32 v19, 16, v78
	v_lshlrev_b32_e32 v20, 16, v82
	v_lshlrev_b32_e32 v21, 16, v86
	v_lshlrev_b32_e32 v22, 16, v90
	v_lshlrev_b32_e32 v23, 16, v94
	v_lshlrev_b32_e32 v24, 16, v98
	v_lshlrev_b32_e32 v25, 16, v102
	v_lshlrev_b32_e32 v26, 16, v106
	v_lshlrev_b32_e32 v27, 16, v110
	v_lshlrev_b32_e32 v28, 16, v114
	v_lshlrev_b32_e32 v29, 16, v118
	v_lshlrev_b32_e32 v30, 16, v122
	v_lshlrev_b32_e32 v31, 16, v126
	v_add_f32_e32 v32, v17, v31
	v_sub_f32_e32 v40, v17, v31
	v_add_f32_e32 v33, v18, v30
	v_sub_f32_e32 v41, v18, v30
	v_add_f32_e32 v34, v19, v29
	v_sub_f32_e32 v42, v19, v29
	v_add_f32_e32 v35, v20, v28
	v_sub_f32_e32 v43, v20, v28
	v_add_f32_e32 v36, v21, v27
	v_sub_f32_e32 v44, v21, v27
	v_add_f32_e32 v37, v22, v26
	v_sub_f32_e32 v45, v22, v26
	v_add_f32_e32 v38, v23, v25
	v_sub_f32_e32 v46, v23, v25
	v_add_f32_e32 v48, v16, v24
	v_add_f32_e32 v48, v48, v32
	v_add_f32_e32 v48, v48, v33
	v_add_f32_e32 v48, v48, v34
	v_add_f32_e32 v48, v48, v35
	v_add_f32_e32 v48, v48, v36
	v_add_f32_e32 v48, v48, v37
	v_add_f32_e32 v48, v48, v38
	v_cvt_pk_bf16_f32 v52, v48, 0
	ds_write_b16 v3, v52 offset:0
	ds_write_b16_d16_hi v3, v52 offset:4352
	v_sub_f32_e32 v48, v16, v24
	v_fmac_f32_e32 v48, 0x3f6c835e, v32
	v_fmac_f32_e32 v48, 0x3f3504f3, v33
	v_fmac_f32_e32 v48, 0x3ec3ef15, v34
	v_fmac_f32_e32 v48, 0xbec3ef15, v36
	v_fmac_f32_e32 v48, 0xbf3504f3, v37
	v_fmac_f32_e32 v48, 0xbf6c835e, v38
	v_mul_f32_e32 v49, 0xbec3ef15, v40
	v_fmac_f32_e32 v49, 0xbf3504f3, v41
	v_fmac_f32_e32 v49, 0xbf6c835e, v42
	v_sub_f32_e32 v49, v49, v43
	v_fmac_f32_e32 v49, 0xbf6c835e, v44
	v_fmac_f32_e32 v49, 0xbf3504f3, v45
	v_fmac_f32_e32 v49, 0xbec3ef15, v46
	v_mul_f32_e32 v50, v49, v216
	v_fmac_f32_e32 v50, v48, v208
	v_mul_f32_e32 v51, v48, v216
	v_fma_f32 v51, v49, v208, -v51
	v_cvt_pk_bf16_f32 v52, v50, v51
	ds_write_b16 v3, v52 offset:8704
	ds_write_b16_d16_hi v3, v52 offset:13056
	v_add_f32_e32 v48, v16, v24
	v_fmac_f32_e32 v48, 0x3f3504f3, v32
	v_fmac_f32_e32 v48, 0xbf3504f3, v34
	v_sub_f32_e32 v48, v48, v35
	v_fmac_f32_e32 v48, 0xbf3504f3, v36
	v_fmac_f32_e32 v48, 0x3f3504f3, v38
	v_mul_f32_e32 v49, 0xbf3504f3, v40
	v_sub_f32_e32 v49, v49, v41
	v_fmac_f32_e32 v49, 0xbf3504f3, v42
	v_fmac_f32_e32 v49, 0x3f3504f3, v44
	v_add_f32_e32 v49, v49, v45
	v_fmac_f32_e32 v49, 0x3f3504f3, v46
	v_mul_f32_e32 v50, v49, v217
	v_fmac_f32_e32 v50, v48, v209
	v_mul_f32_e32 v51, v48, v217
	v_fma_f32 v51, v49, v209, -v51
	v_cvt_pk_bf16_f32 v52, v50, v51
	ds_write_b16 v3, v52 offset:17408
	ds_write_b16_d16_hi v3, v52 offset:21760
	v_sub_f32_e32 v48, v16, v24
	v_fmac_f32_e32 v48, 0x3ec3ef15, v32
	v_fmac_f32_e32 v48, 0xbf3504f3, v33
	v_fmac_f32_e32 v48, 0xbf6c835e, v34
	v_fmac_f32_e32 v48, 0x3f6c835e, v36
	v_fmac_f32_e32 v48, 0x3f3504f3, v37
	v_fmac_f32_e32 v48, 0xbec3ef15, v38
	v_mul_f32_e32 v49, 0xbf6c835e, v40
	v_fmac_f32_e32 v49, 0xbf3504f3, v41
	v_fmac_f32_e32 v49, 0x3ec3ef15, v42
	v_add_f32_e32 v49, v49, v43
	v_fmac_f32_e32 v49, 0x3ec3ef15, v44
	v_fmac_f32_e32 v49, 0xbf3504f3, v45
	v_fmac_f32_e32 v49, 0xbf6c835e, v46
	v_mul_f32_e32 v50, v49, v218
	v_fmac_f32_e32 v50, v48, v210
	v_mul_f32_e32 v51, v48, v218
	v_fma_f32 v51, v49, v210, -v51
	v_cvt_pk_bf16_f32 v52, v50, v51
	ds_write_b16 v3, v52 offset:26112
	ds_write_b16_d16_hi v3, v52 offset:30464
	v_add_f32_e32 v48, v16, v24
	v_sub_f32_e32 v48, v48, v33
	v_add_f32_e32 v48, v48, v35
	v_sub_f32_e32 v48, v48, v37
	v_sub_f32_e32 v49, 0, v40
	v_add_f32_e32 v49, v49, v42
	v_sub_f32_e32 v49, v49, v44
	v_add_f32_e32 v49, v49, v46
	v_mul_f32_e32 v50, v49, v219
	v_fmac_f32_e32 v50, v48, v211
	v_mul_f32_e32 v51, v48, v219
	v_fma_f32 v51, v49, v211, -v51
	v_cvt_pk_bf16_f32 v52, v50, v51
	ds_write_b16 v4, v52 offset:0
	ds_write_b16_d16_hi v4, v52 offset:4352
	v_sub_f32_e32 v48, v16, v24
	v_fmac_f32_e32 v48, 0xbec3ef15, v32
	v_fmac_f32_e32 v48, 0xbf3504f3, v33
	v_fmac_f32_e32 v48, 0x3f6c835e, v34
	v_fmac_f32_e32 v48, 0xbf6c835e, v36
	v_fmac_f32_e32 v48, 0x3f3504f3, v37
	v_fmac_f32_e32 v48, 0x3ec3ef15, v38
	v_mul_f32_e32 v49, 0xbf6c835e, v40
	v_fmac_f32_e32 v49, 0x3f3504f3, v41
	v_fmac_f32_e32 v49, 0x3ec3ef15, v42
	v_sub_f32_e32 v49, v49, v43
	v_fmac_f32_e32 v49, 0x3ec3ef15, v44
	v_fmac_f32_e32 v49, 0x3f3504f3, v45
	v_fmac_f32_e32 v49, 0xbf6c835e, v46
	v_mul_f32_e32 v50, v49, v220
	v_fmac_f32_e32 v50, v48, v212
	v_mul_f32_e32 v51, v48, v220
	v_fma_f32 v51, v49, v212, -v51
	v_cvt_pk_bf16_f32 v52, v50, v51
	ds_write_b16 v4, v52 offset:8704
	ds_write_b16_d16_hi v4, v52 offset:13056
	v_add_f32_e32 v48, v16, v24
	v_fmac_f32_e32 v48, 0xbf3504f3, v32
	v_fmac_f32_e32 v48, 0x3f3504f3, v34
	v_sub_f32_e32 v48, v48, v35
	v_fmac_f32_e32 v48, 0x3f3504f3, v36
	v_fmac_f32_e32 v48, 0xbf3504f3, v38
	v_mul_f32_e32 v49, 0xbf3504f3, v40
	v_add_f32_e32 v49, v49, v41
	v_fmac_f32_e32 v49, 0xbf3504f3, v42
	v_fmac_f32_e32 v49, 0x3f3504f3, v44
	v_sub_f32_e32 v49, v49, v45
	v_fmac_f32_e32 v49, 0x3f3504f3, v46
	v_mul_f32_e32 v50, v49, v221
	v_fmac_f32_e32 v50, v48, v213
	v_mul_f32_e32 v51, v48, v221
	v_fma_f32 v51, v49, v213, -v51
	v_cvt_pk_bf16_f32 v52, v50, v51
	ds_write_b16 v4, v52 offset:17408
	ds_write_b16_d16_hi v4, v52 offset:21760
	v_sub_f32_e32 v48, v16, v24
	v_fmac_f32_e32 v48, 0xbf6c835e, v32
	v_fmac_f32_e32 v48, 0x3f3504f3, v33
	v_fmac_f32_e32 v48, 0xbec3ef15, v34
	v_fmac_f32_e32 v48, 0x3ec3ef15, v36
	v_fmac_f32_e32 v48, 0xbf3504f3, v37
	v_fmac_f32_e32 v48, 0x3f6c835e, v38
	v_mul_f32_e32 v49, 0xbec3ef15, v40
	v_fmac_f32_e32 v49, 0x3f3504f3, v41
	v_fmac_f32_e32 v49, 0xbf6c835e, v42
	v_add_f32_e32 v49, v49, v43
	v_fmac_f32_e32 v49, 0xbf6c835e, v44
; __device__ __forceinline__ bf16_t f2bf(float f) { return (bf16_t)(cvt_pk_bf16(f, 0.f) & 0xffffu); }
; __device__ __forceinline__ void dft16_phase(const Ctx& X, const bf16_t* HN, bf16_t* GT) {
;     ...
;                 for (int e = 0; e < 8; ++e) { float re = 0.f, im = 0.f;
; #pragma unroll
;                     for (int a = 0; a < 16; ++a) { const unsigned wv = xin[a][e >> 1]; const float x = (e & 1) ? bf2f(wv >> 16) : bf2f(wv & 0xffffu); re += x * cw[a]; im -= x * sw[a]; }
;                     const float orr = re * tc - im * ts, oi = re * ts + im * tc;
;                     tile[((kl * 2 + 0) * 64 + cchunk * 8 + e) * 72 + i] = f2bf(orr); tile[((kl * 2 + 1) * 64 + cchunk * 8 + e) * 72 + i] = f2bf(oi); } }
	v_fmac_f32_e32 v49, 0x3f3504f3, v45
	v_fmac_f32_e32 v49, 0xbec3ef15, v46
	v_mul_f32_e32 v50, v49, v222
	v_fmac_f32_e32 v50, v48, v214
	v_mul_f32_e32 v51, v48, v222
	v_fma_f32 v51, v49, v214, -v51
	v_cvt_pk_bf16_f32 v52, v50, v51
	ds_write_b16 v4, v52 offset:26112
	ds_write_b16_d16_hi v4, v52 offset:30464
	v_add_f32_e32 v48, v16, v24
	v_sub_f32_e32 v48, v48, v32
	v_add_f32_e32 v48, v48, v33
	v_sub_f32_e32 v48, v48, v34
	v_add_f32_e32 v48, v48, v35
	v_sub_f32_e32 v48, v48, v36
	v_add_f32_e32 v48, v48, v37
	v_sub_f32_e32 v48, v48, v38
	v_mul_f32_e32 v50, v48, v215
	v_mul_f32_e32 v51, v48, v223
	v_sub_f32_e32 v51, 0, v51
	v_cvt_pk_bf16_f32 v52, v50, v51
	ds_write_b16 v4, v52 offset:34816
	ds_write_b16_d16_hi v4, v52 offset:39168
	v_and_b32_e32 v16, 0xffff0000, v66
	v_and_b32_e32 v17, 0xffff0000, v70
	v_and_b32_e32 v18, 0xffff0000, v74
	v_and_b32_e32 v19, 0xffff0000, v78
	v_and_b32_e32 v20, 0xffff0000, v82
	v_and_b32_e32 v21, 0xffff0000, v86
	v_and_b32_e32 v22, 0xffff0000, v90
	v_and_b32_e32 v23, 0xffff0000, v94
	v_and_b32_e32 v24, 0xffff0000, v98
	v_and_b32_e32 v25, 0xffff0000, v102
	v_and_b32_e32 v26, 0xffff0000, v106
	v_and_b32_e32 v27, 0xffff0000, v110
	v_and_b32_e32 v28, 0xffff0000, v114
	v_and_b32_e32 v29, 0xffff0000, v118
	v_and_b32_e32 v30, 0xffff0000, v122
	v_and_b32_e32 v31, 0xffff0000, v126
	v_add_f32_e32 v32, v17, v31
	v_sub_f32_e32 v40, v17, v31
	v_add_f32_e32 v33, v18, v30
	v_sub_f32_e32 v41, v18, v30
	v_add_f32_e32 v34, v19, v29
	v_sub_f32_e32 v42, v19, v29
	v_add_f32_e32 v35, v20, v28
	v_sub_f32_e32 v43, v20, v28
	v_add_f32_e32 v36, v21, v27
	v_sub_f32_e32 v44, v21, v27
	v_add_f32_e32 v37, v22, v26
	v_sub_f32_e32 v45, v22, v26
	v_add_f32_e32 v38, v23, v25
	v_sub_f32_e32 v46, v23, v25
	v_add_f32_e32 v48, v16, v24
	v_add_f32_e32 v48, v48, v32
	v_add_f32_e32 v48, v48, v33
	v_add_f32_e32 v48, v48, v34
	v_add_f32_e32 v48, v48, v35
	v_add_f32_e32 v48, v48, v36
	v_add_f32_e32 v48, v48, v37
	v_add_f32_e32 v48, v48, v38
	v_cvt_pk_bf16_f32 v52, v48, 0
	ds_write_b16 v3, v52 offset:136
	ds_write_b16_d16_hi v3, v52 offset:4488
	v_sub_f32_e32 v48, v16, v24
	v_fmac_f32_e32 v48, 0x3f6c835e, v32
	v_fmac_f32_e32 v48, 0x3f3504f3, v33
	v_fmac_f32_e32 v48, 0x3ec3ef15, v34
	v_fmac_f32_e32 v48, 0xbec3ef15, v36
	v_fmac_f32_e32 v48, 0xbf3504f3, v37
	v_fmac_f32_e32 v48, 0xbf6c835e, v38
	v_mul_f32_e32 v49, 0xbec3ef15, v40
	v_fmac_f32_e32 v49, 0xbf3504f3, v41
	v_fmac_f32_e32 v49, 0xbf6c835e, v42
	v_sub_f32_e32 v49, v49, v43
	v_fmac_f32_e32 v49, 0xbf6c835e, v44
	v_fmac_f32_e32 v49, 0xbf3504f3, v45
	v_fmac_f32_e32 v49, 0xbec3ef15, v46
	v_mul_f32_e32 v50, v49, v216
	v_fmac_f32_e32 v50, v48, v208
	v_mul_f32_e32 v51, v48, v216
	v_fma_f32 v51, v49, v208, -v51
	v_cvt_pk_bf16_f32 v52, v50, v51
	ds_write_b16 v3, v52 offset:8840
	ds_write_b16_d16_hi v3, v52 offset:13192
	v_add_f32_e32 v48, v16, v24
	v_fmac_f32_e32 v48, 0x3f3504f3, v32
	v_fmac_f32_e32 v48, 0xbf3504f3, v34
	v_sub_f32_e32 v48, v48, v35
	v_fmac_f32_e32 v48, 0xbf3504f3, v36
	v_fmac_f32_e32 v48, 0x3f3504f3, v38
	v_mul_f32_e32 v49, 0xbf3504f3, v40
	v_sub_f32_e32 v49, v49, v41
	v_fmac_f32_e32 v49, 0xbf3504f3, v42
	v_fmac_f32_e32 v49, 0x3f3504f3, v44
	v_add_f32_e32 v49, v49, v45
	v_fmac_f32_e32 v49, 0x3f3504f3, v46
	v_mul_f32_e32 v50, v49, v217
	v_fmac_f32_e32 v50, v48, v209
	v_mul_f32_e32 v51, v48, v217
	v_fma_f32 v51, v49, v209, -v51
	v_cvt_pk_bf16_f32 v52, v50, v51
	ds_write_b16 v3, v52 offset:17544
	ds_write_b16_d16_hi v3, v52 offset:21896
	v_sub_f32_e32 v48, v16, v24
	v_fmac_f32_e32 v48, 0x3ec3ef15, v32
	v_fmac_f32_e32 v48, 0xbf3504f3, v33
	v_fmac_f32_e32 v48, 0xbf6c835e, v34
	v_fmac_f32_e32 v48, 0x3f6c835e, v36
	v_fmac_f32_e32 v48, 0x3f3504f3, v37
	v_fmac_f32_e32 v48, 0xbec3ef15, v38
	v_mul_f32_e32 v49, 0xbf6c835e, v40
	v_fmac_f32_e32 v49, 0xbf3504f3, v41
	v_fmac_f32_e32 v49, 0x3ec3ef15, v42
	v_add_f32_e32 v49, v49, v43
	v_fmac_f32_e32 v49, 0x3ec3ef15, v44
	v_fmac_f32_e32 v49, 0xbf3504f3, v45
	v_fmac_f32_e32 v49, 0xbf6c835e, v46
	v_mul_f32_e32 v50, v49, v218
	v_fmac_f32_e32 v50, v48, v210
	v_mul_f32_e32 v51, v48, v218
	v_fma_f32 v51, v49, v210, -v51
	v_cvt_pk_bf16_f32 v52, v50, v51
	ds_write_b16 v3, v52 offset:26248
	ds_write_b16_d16_hi v3, v52 offset:30600
	v_add_f32_e32 v48, v16, v24
	v_sub_f32_e32 v48, v48, v33
	v_add_f32_e32 v48, v48, v35
	v_sub_f32_e32 v48, v48, v37
	v_sub_f32_e32 v49, 0, v40
	v_add_f32_e32 v49, v49, v42
	v_sub_f32_e32 v49, v49, v44
	v_add_f32_e32 v49, v49, v46
	v_mul_f32_e32 v50, v49, v219
	v_fmac_f32_e32 v50, v48, v211
	v_mul_f32_e32 v51, v48, v219
	v_fma_f32 v51, v49, v211, -v51
	v_cvt_pk_bf16_f32 v52, v50, v51
	ds_write_b16 v4, v52 offset:136
	ds_write_b16_d16_hi v4, v52 offset:4488
	v_sub_f32_e32 v48, v16, v24
	v_fmac_f32_e32 v48, 0xbec3ef15, v32
	v_fmac_f32_e32 v48, 0xbf3504f3, v33
	v_fmac_f32_e32 v48, 0x3f6c835e, v34
	v_fmac_f32_e32 v48, 0xbf6c835e, v36
	v_fmac_f32_e32 v48, 0x3f3504f3, v37
	v_fmac_f32_e32 v48, 0x3ec3ef15, v38
	v_mul_f32_e32 v49, 0xbf6c835e, v40
	v_fmac_f32_e32 v49, 0x3f3504f3, v41
	v_fmac_f32_e32 v49, 0x3ec3ef15, v42
	v_sub_f32_e32 v49, v49, v43
	v_fmac_f32_e32 v49, 0x3ec3ef15, v44
	v_fmac_f32_e32 v49, 0x3f3504f3, v45
	v_fmac_f32_e32 v49, 0xbf6c835e, v46
	v_mul_f32_e32 v50, v49, v220
	v_fmac_f32_e32 v50, v48, v212
	v_mul_f32_e32 v51, v48, v220
	v_fma_f32 v51, v49, v212, -v51
	v_cvt_pk_bf16_f32 v52, v50, v51
	ds_write_b16 v4, v52 offset:8840
	ds_write_b16_d16_hi v4, v52 offset:13192
	v_add_f32_e32 v48, v16, v24
	v_fmac_f32_e32 v48, 0xbf3504f3, v32
	v_fmac_f32_e32 v48, 0x3f3504f3, v34
	v_sub_f32_e32 v48, v48, v35
	v_fmac_f32_e32 v48, 0x3f3504f3, v36
	v_fmac_f32_e32 v48, 0xbf3504f3, v38
	v_mul_f32_e32 v49, 0xbf3504f3, v40
	v_add_f32_e32 v49, v49, v41
; __device__ __forceinline__ bf16_t f2bf(float f) { return (bf16_t)(cvt_pk_bf16(f, 0.f) & 0xffffu); }
; __device__ __forceinline__ void dft16_phase(const Ctx& X, const bf16_t* HN, bf16_t* GT) {
;     ...
;                 for (int e = 0; e < 8; ++e) { float re = 0.f, im = 0.f;
; #pragma unroll
;                     for (int a = 0; a < 16; ++a) { const unsigned wv = xin[a][e >> 1]; const float x = (e & 1) ? bf2f(wv >> 16) : bf2f(wv & 0xffffu); re += x * cw[a]; im -= x * sw[a]; }
;                     const float orr = re * tc - im * ts, oi = re * ts + im * tc;
;                     tile[((kl * 2 + 0) * 64 + cchunk * 8 + e) * 72 + i] = f2bf(orr); tile[((kl * 2 + 1) * 64 + cchunk * 8 + e) * 72 + i] = f2bf(oi); } }
	v_fmac_f32_e32 v49, 0xbf3504f3, v42
	v_fmac_f32_e32 v49, 0x3f3504f3, v44
	v_sub_f32_e32 v49, v49, v45
	v_fmac_f32_e32 v49, 0x3f3504f3, v46
	v_mul_f32_e32 v50, v49, v221
	v_fmac_f32_e32 v50, v48, v213
	v_mul_f32_e32 v51, v48, v221
	v_fma_f32 v51, v49, v213, -v51
	v_cvt_pk_bf16_f32 v52, v50, v51
	ds_write_b16 v4, v52 offset:17544
	ds_write_b16_d16_hi v4, v52 offset:21896
	v_sub_f32_e32 v48, v16, v24
	v_fmac_f32_e32 v48, 0xbf6c835e, v32
	v_fmac_f32_e32 v48, 0x3f3504f3, v33
	v_fmac_f32_e32 v48, 0xbec3ef15, v34
	v_fmac_f32_e32 v48, 0x3ec3ef15, v36
	v_fmac_f32_e32 v48, 0xbf3504f3, v37
	v_fmac_f32_e32 v48, 0x3f6c835e, v38
	v_mul_f32_e32 v49, 0xbec3ef15, v40
	v_fmac_f32_e32 v49, 0x3f3504f3, v41
	v_fmac_f32_e32 v49, 0xbf6c835e, v42
	v_add_f32_e32 v49, v49, v43
	v_fmac_f32_e32 v49, 0xbf6c835e, v44
	v_fmac_f32_e32 v49, 0x3f3504f3, v45
	v_fmac_f32_e32 v49, 0xbec3ef15, v46
	v_mul_f32_e32 v50, v49, v222
	v_fmac_f32_e32 v50, v48, v214
	v_mul_f32_e32 v51, v48, v222
	v_fma_f32 v51, v49, v214, -v51
	v_cvt_pk_bf16_f32 v52, v50, v51
	ds_write_b16 v4, v52 offset:26248
	ds_write_b16_d16_hi v4, v52 offset:30600
	v_add_f32_e32 v48, v16, v24
	v_sub_f32_e32 v48, v48, v32
	v_add_f32_e32 v48, v48, v33
	v_sub_f32_e32 v48, v48, v34
	v_add_f32_e32 v48, v48, v35
	v_sub_f32_e32 v48, v48, v36
	v_add_f32_e32 v48, v48, v37
	v_sub_f32_e32 v48, v48, v38
	v_mul_f32_e32 v50, v48, v215
	v_mul_f32_e32 v51, v48, v223
	v_sub_f32_e32 v51, 0, v51
	v_cvt_pk_bf16_f32 v52, v50, v51
	ds_write_b16 v4, v52 offset:34952
	ds_write_b16_d16_hi v4, v52 offset:39304
	v_lshlrev_b32_e32 v16, 16, v67
	v_lshlrev_b32_e32 v17, 16, v71
	v_lshlrev_b32_e32 v18, 16, v75
	v_lshlrev_b32_e32 v19, 16, v79
	v_lshlrev_b32_e32 v20, 16, v83
	v_lshlrev_b32_e32 v21, 16, v87
	v_lshlrev_b32_e32 v22, 16, v91
	v_lshlrev_b32_e32 v23, 16, v95
	v_lshlrev_b32_e32 v24, 16, v99
	v_lshlrev_b32_e32 v25, 16, v103
	v_lshlrev_b32_e32 v26, 16, v107
	v_lshlrev_b32_e32 v27, 16, v111
	v_lshlrev_b32_e32 v28, 16, v115
	v_lshlrev_b32_e32 v29, 16, v119
	v_lshlrev_b32_e32 v30, 16, v123
	v_lshlrev_b32_e32 v31, 16, v127
	v_add_f32_e32 v32, v17, v31
	v_sub_f32_e32 v40, v17, v31
	v_add_f32_e32 v33, v18, v30
	v_sub_f32_e32 v41, v18, v30
	v_add_f32_e32 v34, v19, v29
	v_sub_f32_e32 v42, v19, v29
	v_add_f32_e32 v35, v20, v28
	v_sub_f32_e32 v43, v20, v28
	v_add_f32_e32 v36, v21, v27
	v_sub_f32_e32 v44, v21, v27
	v_add_f32_e32 v37, v22, v26
	v_sub_f32_e32 v45, v22, v26
	v_add_f32_e32 v38, v23, v25
	v_sub_f32_e32 v46, v23, v25
	v_add_f32_e32 v48, v16, v24
	v_add_f32_e32 v48, v48, v32
	v_add_f32_e32 v48, v48, v33
	v_add_f32_e32 v48, v48, v34
	v_add_f32_e32 v48, v48, v35
	v_add_f32_e32 v48, v48, v36
	v_add_f32_e32 v48, v48, v37
	v_add_f32_e32 v48, v48, v38
	v_cvt_pk_bf16_f32 v52, v48, 0
	ds_write_b16 v3, v52 offset:272
	ds_write_b16_d16_hi v3, v52 offset:4624
	v_sub_f32_e32 v48, v16, v24
	v_fmac_f32_e32 v48, 0x3f6c835e, v32
	v_fmac_f32_e32 v48, 0x3f3504f3, v33
	v_fmac_f32_e32 v48, 0x3ec3ef15, v34
	v_fmac_f32_e32 v48, 0xbec3ef15, v36
	v_fmac_f32_e32 v48, 0xbf3504f3, v37
	v_fmac_f32_e32 v48, 0xbf6c835e, v38
	v_mul_f32_e32 v49, 0xbec3ef15, v40
	v_fmac_f32_e32 v49, 0xbf3504f3, v41
	v_fmac_f32_e32 v49, 0xbf6c835e, v42
	v_sub_f32_e32 v49, v49, v43
	v_fmac_f32_e32 v49, 0xbf6c835e, v44
	v_fmac_f32_e32 v49, 0xbf3504f3, v45
	v_fmac_f32_e32 v49, 0xbec3ef15, v46
	v_mul_f32_e32 v50, v49, v216
	v_fmac_f32_e32 v50, v48, v208
	v_mul_f32_e32 v51, v48, v216
	v_fma_f32 v51, v49, v208, -v51
	v_cvt_pk_bf16_f32 v52, v50, v51
	ds_write_b16 v3, v52 offset:8976
	ds_write_b16_d16_hi v3, v52 offset:13328
	v_add_f32_e32 v48, v16, v24
	v_fmac_f32_e32 v48, 0x3f3504f3, v32
	v_fmac_f32_e32 v48, 0xbf3504f3, v34
	v_sub_f32_e32 v48, v48, v35
	v_fmac_f32_e32 v48, 0xbf3504f3, v36
	v_fmac_f32_e32 v48, 0x3f3504f3, v38
	v_mul_f32_e32 v49, 0xbf3504f3, v40
	v_sub_f32_e32 v49, v49, v41
	v_fmac_f32_e32 v49, 0xbf3504f3, v42
	v_fmac_f32_e32 v49, 0x3f3504f3, v44
	v_add_f32_e32 v49, v49, v45
	v_fmac_f32_e32 v49, 0x3f3504f3, v46
	v_mul_f32_e32 v50, v49, v217
	v_fmac_f32_e32 v50, v48, v209
	v_mul_f32_e32 v51, v48, v217
	v_fma_f32 v51, v49, v209, -v51
	v_cvt_pk_bf16_f32 v52, v50, v51
	ds_write_b16 v3, v52 offset:17680
	ds_write_b16_d16_hi v3, v52 offset:22032
	v_sub_f32_e32 v48, v16, v24
	v_fmac_f32_e32 v48, 0x3ec3ef15, v32
	v_fmac_f32_e32 v48, 0xbf3504f3, v33
	v_fmac_f32_e32 v48, 0xbf6c835e, v34
	v_fmac_f32_e32 v48, 0x3f6c835e, v36
	v_fmac_f32_e32 v48, 0x3f3504f3, v37
	v_fmac_f32_e32 v48, 0xbec3ef15, v38
	v_mul_f32_e32 v49, 0xbf6c835e, v40
	v_fmac_f32_e32 v49, 0xbf3504f3, v41
	v_fmac_f32_e32 v49, 0x3ec3ef15, v42
	v_add_f32_e32 v49, v49, v43
	v_fmac_f32_e32 v49, 0x3ec3ef15, v44
	v_fmac_f32_e32 v49, 0xbf3504f3, v45
	v_fmac_f32_e32 v49, 0xbf6c835e, v46
	v_mul_f32_e32 v50, v49, v218
	v_fmac_f32_e32 v50, v48, v210
	v_mul_f32_e32 v51, v48, v218
	v_fma_f32 v51, v49, v210, -v51
	v_cvt_pk_bf16_f32 v52, v50, v51
	ds_write_b16 v3, v52 offset:26384
	ds_write_b16_d16_hi v3, v52 offset:30736
	v_add_f32_e32 v48, v16, v24
	v_sub_f32_e32 v48, v48, v33
	v_add_f32_e32 v48, v48, v35
	v_sub_f32_e32 v48, v48, v37
	v_sub_f32_e32 v49, 0, v40
	v_add_f32_e32 v49, v49, v42
	v_sub_f32_e32 v49, v49, v44
	v_add_f32_e32 v49, v49, v46
	v_mul_f32_e32 v50, v49, v219
	v_fmac_f32_e32 v50, v48, v211
	v_mul_f32_e32 v51, v48, v219
	v_fma_f32 v51, v49, v211, -v51
	v_cvt_pk_bf16_f32 v52, v50, v51
	ds_write_b16 v4, v52 offset:272
	ds_write_b16_d16_hi v4, v52 offset:4624
	v_sub_f32_e32 v48, v16, v24
	v_fmac_f32_e32 v48, 0xbec3ef15, v32
	v_fmac_f32_e32 v48, 0xbf3504f3, v33
	v_fmac_f32_e32 v48, 0x3f6c835e, v34
	v_fmac_f32_e32 v48, 0xbf6c835e, v36
	v_fmac_f32_e32 v48, 0x3f3504f3, v37
	v_fmac_f32_e32 v48, 0x3ec3ef15, v38
	v_mul_f32_e32 v49, 0xbf6c835e, v40
; __device__ __forceinline__ bf16_t f2bf(float f) { return (bf16_t)(cvt_pk_bf16(f, 0.f) & 0xffffu); }
; __device__ __forceinline__ void dft16_phase(const Ctx& X, const bf16_t* HN, bf16_t* GT) {
;     ...
;                 for (int e = 0; e < 8; ++e) { float re = 0.f, im = 0.f;
; #pragma unroll
;                     for (int a = 0; a < 16; ++a) { const unsigned wv = xin[a][e >> 1]; const float x = (e & 1) ? bf2f(wv >> 16) : bf2f(wv & 0xffffu); re += x * cw[a]; im -= x * sw[a]; }
;                     const float orr = re * tc - im * ts, oi = re * ts + im * tc;
;                     tile[((kl * 2 + 0) * 64 + cchunk * 8 + e) * 72 + i] = f2bf(orr); tile[((kl * 2 + 1) * 64 + cchunk * 8 + e) * 72 + i] = f2bf(oi); } }
	v_fmac_f32_e32 v49, 0x3f3504f3, v41
	v_fmac_f32_e32 v49, 0x3ec3ef15, v42
	v_sub_f32_e32 v49, v49, v43
	v_fmac_f32_e32 v49, 0x3ec3ef15, v44
	v_fmac_f32_e32 v49, 0x3f3504f3, v45
	v_fmac_f32_e32 v49, 0xbf6c835e, v46
	v_mul_f32_e32 v50, v49, v220
	v_fmac_f32_e32 v50, v48, v212
	v_mul_f32_e32 v51, v48, v220
	v_fma_f32 v51, v49, v212, -v51
	v_cvt_pk_bf16_f32 v52, v50, v51
	ds_write_b16 v4, v52 offset:8976
	ds_write_b16_d16_hi v4, v52 offset:13328
	v_add_f32_e32 v48, v16, v24
	v_fmac_f32_e32 v48, 0xbf3504f3, v32
	v_fmac_f32_e32 v48, 0x3f3504f3, v34
	v_sub_f32_e32 v48, v48, v35
	v_fmac_f32_e32 v48, 0x3f3504f3, v36
	v_fmac_f32_e32 v48, 0xbf3504f3, v38
	v_mul_f32_e32 v49, 0xbf3504f3, v40
	v_add_f32_e32 v49, v49, v41
	v_fmac_f32_e32 v49, 0xbf3504f3, v42
	v_fmac_f32_e32 v49, 0x3f3504f3, v44
	v_sub_f32_e32 v49, v49, v45
	v_fmac_f32_e32 v49, 0x3f3504f3, v46
	v_mul_f32_e32 v50, v49, v221
	v_fmac_f32_e32 v50, v48, v213
	v_mul_f32_e32 v51, v48, v221
	v_fma_f32 v51, v49, v213, -v51
	v_cvt_pk_bf16_f32 v52, v50, v51
	ds_write_b16 v4, v52 offset:17680
	ds_write_b16_d16_hi v4, v52 offset:22032
	v_sub_f32_e32 v48, v16, v24
	v_fmac_f32_e32 v48, 0xbf6c835e, v32
	v_fmac_f32_e32 v48, 0x3f3504f3, v33
	v_fmac_f32_e32 v48, 0xbec3ef15, v34
	v_fmac_f32_e32 v48, 0x3ec3ef15, v36
	v_fmac_f32_e32 v48, 0xbf3504f3, v37
	v_fmac_f32_e32 v48, 0x3f6c835e, v38
	v_mul_f32_e32 v49, 0xbec3ef15, v40
	v_fmac_f32_e32 v49, 0x3f3504f3, v41
	v_fmac_f32_e32 v49, 0xbf6c835e, v42
	v_add_f32_e32 v49, v49, v43
	v_fmac_f32_e32 v49, 0xbf6c835e, v44
	v_fmac_f32_e32 v49, 0x3f3504f3, v45
	v_fmac_f32_e32 v49, 0xbec3ef15, v46
	v_mul_f32_e32 v50, v49, v222
	v_fmac_f32_e32 v50, v48, v214
	v_mul_f32_e32 v51, v48, v222
	v_fma_f32 v51, v49, v214, -v51
	v_cvt_pk_bf16_f32 v52, v50, v51
	ds_write_b16 v4, v52 offset:26384
	ds_write_b16_d16_hi v4, v52 offset:30736
	v_add_f32_e32 v48, v16, v24
	v_sub_f32_e32 v48, v48, v32
	v_add_f32_e32 v48, v48, v33
	v_sub_f32_e32 v48, v48, v34
	v_add_f32_e32 v48, v48, v35
	v_sub_f32_e32 v48, v48, v36
	v_add_f32_e32 v48, v48, v37
	v_sub_f32_e32 v48, v48, v38
	v_mul_f32_e32 v50, v48, v215
	v_mul_f32_e32 v51, v48, v223
	v_sub_f32_e32 v51, 0, v51
	v_cvt_pk_bf16_f32 v52, v50, v51
	ds_write_b16 v4, v52 offset:35088
	ds_write_b16_d16_hi v4, v52 offset:39440
	v_and_b32_e32 v16, 0xffff0000, v67
	v_and_b32_e32 v17, 0xffff0000, v71
	v_and_b32_e32 v18, 0xffff0000, v75
	v_and_b32_e32 v19, 0xffff0000, v79
	v_and_b32_e32 v20, 0xffff0000, v83
	v_and_b32_e32 v21, 0xffff0000, v87
	v_and_b32_e32 v22, 0xffff0000, v91
	v_and_b32_e32 v23, 0xffff0000, v95
	v_and_b32_e32 v24, 0xffff0000, v99
	v_and_b32_e32 v25, 0xffff0000, v103
	v_and_b32_e32 v26, 0xffff0000, v107
	v_and_b32_e32 v27, 0xffff0000, v111
	v_and_b32_e32 v28, 0xffff0000, v115
	v_and_b32_e32 v29, 0xffff0000, v119
	v_and_b32_e32 v30, 0xffff0000, v123
	v_and_b32_e32 v31, 0xffff0000, v127
	v_add_f32_e32 v32, v17, v31
	v_sub_f32_e32 v40, v17, v31
	v_add_f32_e32 v33, v18, v30
	v_sub_f32_e32 v41, v18, v30
	v_add_f32_e32 v34, v19, v29
	v_sub_f32_e32 v42, v19, v29
	v_add_f32_e32 v35, v20, v28
	v_sub_f32_e32 v43, v20, v28
	v_add_f32_e32 v36, v21, v27
	v_sub_f32_e32 v44, v21, v27
	v_add_f32_e32 v37, v22, v26
	v_sub_f32_e32 v45, v22, v26
	v_add_f32_e32 v38, v23, v25
	v_sub_f32_e32 v46, v23, v25
	v_add_f32_e32 v48, v16, v24
	v_add_f32_e32 v48, v48, v32
	v_add_f32_e32 v48, v48, v33
	v_add_f32_e32 v48, v48, v34
	v_add_f32_e32 v48, v48, v35
	v_add_f32_e32 v48, v48, v36
	v_add_f32_e32 v48, v48, v37
	v_add_f32_e32 v48, v48, v38
	v_cvt_pk_bf16_f32 v52, v48, 0
	ds_write_b16 v3, v52 offset:408
	ds_write_b16_d16_hi v3, v52 offset:4760
	v_sub_f32_e32 v48, v16, v24
	v_fmac_f32_e32 v48, 0x3f6c835e, v32
	v_fmac_f32_e32 v48, 0x3f3504f3, v33
	v_fmac_f32_e32 v48, 0x3ec3ef15, v34
	v_fmac_f32_e32 v48, 0xbec3ef15, v36
	v_fmac_f32_e32 v48, 0xbf3504f3, v37
	v_fmac_f32_e32 v48, 0xbf6c835e, v38
	v_mul_f32_e32 v49, 0xbec3ef15, v40
	v_fmac_f32_e32 v49, 0xbf3504f3, v41
	v_fmac_f32_e32 v49, 0xbf6c835e, v42
	v_sub_f32_e32 v49, v49, v43
	v_fmac_f32_e32 v49, 0xbf6c835e, v44
	v_fmac_f32_e32 v49, 0xbf3504f3, v45
	v_fmac_f32_e32 v49, 0xbec3ef15, v46
	v_mul_f32_e32 v50, v49, v216
	v_fmac_f32_e32 v50, v48, v208
	v_mul_f32_e32 v51, v48, v216
	v_fma_f32 v51, v49, v208, -v51
	v_cvt_pk_bf16_f32 v52, v50, v51
	ds_write_b16 v3, v52 offset:9112
	ds_write_b16_d16_hi v3, v52 offset:13464
	v_add_f32_e32 v48, v16, v24
	v_fmac_f32_e32 v48, 0x3f3504f3, v32
	v_fmac_f32_e32 v48, 0xbf3504f3, v34
	v_sub_f32_e32 v48, v48, v35
	v_fmac_f32_e32 v48, 0xbf3504f3, v36
	v_fmac_f32_e32 v48, 0x3f3504f3, v38
	v_mul_f32_e32 v49, 0xbf3504f3, v40
	v_sub_f32_e32 v49, v49, v41
	v_fmac_f32_e32 v49, 0xbf3504f3, v42
	v_fmac_f32_e32 v49, 0x3f3504f3, v44
	v_add_f32_e32 v49, v49, v45
	v_fmac_f32_e32 v49, 0x3f3504f3, v46
	v_mul_f32_e32 v50, v49, v217
	v_fmac_f32_e32 v50, v48, v209
	v_mul_f32_e32 v51, v48, v217
	v_fma_f32 v51, v49, v209, -v51
	v_cvt_pk_bf16_f32 v52, v50, v51
	ds_write_b16 v3, v52 offset:17816
	ds_write_b16_d16_hi v3, v52 offset:22168
	v_sub_f32_e32 v48, v16, v24
	v_fmac_f32_e32 v48, 0x3ec3ef15, v32
	v_fmac_f32_e32 v48, 0xbf3504f3, v33
	v_fmac_f32_e32 v48, 0xbf6c835e, v34
	v_fmac_f32_e32 v48, 0x3f6c835e, v36
	v_fmac_f32_e32 v48, 0x3f3504f3, v37
	v_fmac_f32_e32 v48, 0xbec3ef15, v38
	v_mul_f32_e32 v49, 0xbf6c835e, v40
	v_fmac_f32_e32 v49, 0xbf3504f3, v41
	v_fmac_f32_e32 v49, 0x3ec3ef15, v42
	v_add_f32_e32 v49, v49, v43
	v_fmac_f32_e32 v49, 0x3ec3ef15, v44
	v_fmac_f32_e32 v49, 0xbf3504f3, v45
	v_fmac_f32_e32 v49, 0xbf6c835e, v46
	v_mul_f32_e32 v50, v49, v218
	v_fmac_f32_e32 v50, v48, v210
	v_mul_f32_e32 v51, v48, v218
	v_fma_f32 v51, v49, v210, -v51
	v_cvt_pk_bf16_f32 v52, v50, v51
	ds_write_b16 v3, v52 offset:26520
; __device__ __forceinline__ bf16_t f2bf(float f) { return (bf16_t)(cvt_pk_bf16(f, 0.f) & 0xffffu); }
; __device__ __forceinline__ void dft16_phase(const Ctx& X, const bf16_t* HN, bf16_t* GT) {
;     ...
;                 const float tang = (float)(bp * ka) * (1.0f / 2048.0f); const float tc = cospif(tang), ts = -sinpif(tang);
;                 float cw[16], sw[16];
; #pragma unroll
;                 for (int a = 0; a < 16; ++a) { const int m = (a * ka) & 15; cw[a] = T16[m]; sw[a] = T16[16 + m]; }
; #pragma unroll
;                 for (int e = 0; e < 8; ++e) { float re = 0.f, im = 0.f;
; #pragma unroll
;                     for (int a = 0; a < 16; ++a) { const unsigned wv = xin[a][e >> 1]; const float x = (e & 1) ? bf2f(wv >> 16) : bf2f(wv & 0xffffu); re += x * cw[a]; im -= x * sw[a]; }
;                     const float orr = re * tc - im * ts, oi = re * ts + im * tc;
;                     tile[((kl * 2 + 0) * 64 + cchunk * 8 + e) * 72 + i] = f2bf(orr); tile[((kl * 2 + 1) * 64 + cchunk * 8 + e) * 72 + i] = f2bf(oi); } }
;             __syncthreads();
; #pragma unroll
;             for (int q = 0; q < 8; ++q) { const int cid = q * 512 + X.tid, row = cid >> 3, c8 = cid & 7, kl = row >> 7, ri = (row >> 6) & 1, ch = row & 63;
;                 if (kq * 4 + kl > 8) continue;
;                 const u32x4 v = *(const u32x4*)(tile + row * 72 + c8 * 8);
;                 *(u32x4*)(GT + ((size_t)(b * 9 + kq * 4 + kl) * 1024 + ch0 + ch) * 512 + ri * 256 + b0 + c8 * 8) = v; }
	ds_write_b16_d16_hi v3, v52 offset:30872
	v_add_f32_e32 v48, v16, v24
	v_sub_f32_e32 v48, v48, v33
	v_add_f32_e32 v48, v48, v35
	v_sub_f32_e32 v48, v48, v37
	v_sub_f32_e32 v49, 0, v40
	v_add_f32_e32 v49, v49, v42
	v_sub_f32_e32 v49, v49, v44
	v_add_f32_e32 v49, v49, v46
	v_mul_f32_e32 v50, v49, v219
	v_fmac_f32_e32 v50, v48, v211
	v_mul_f32_e32 v51, v48, v219
	v_fma_f32 v51, v49, v211, -v51
	v_cvt_pk_bf16_f32 v52, v50, v51
	ds_write_b16 v4, v52 offset:408
	ds_write_b16_d16_hi v4, v52 offset:4760
	v_sub_f32_e32 v48, v16, v24
	v_fmac_f32_e32 v48, 0xbec3ef15, v32
	v_fmac_f32_e32 v48, 0xbf3504f3, v33
	v_fmac_f32_e32 v48, 0x3f6c835e, v34
	v_fmac_f32_e32 v48, 0xbf6c835e, v36
	v_fmac_f32_e32 v48, 0x3f3504f3, v37
	v_fmac_f32_e32 v48, 0x3ec3ef15, v38
	v_mul_f32_e32 v49, 0xbf6c835e, v40
	v_fmac_f32_e32 v49, 0x3f3504f3, v41
	v_fmac_f32_e32 v49, 0x3ec3ef15, v42
	v_sub_f32_e32 v49, v49, v43
	v_fmac_f32_e32 v49, 0x3ec3ef15, v44
	v_fmac_f32_e32 v49, 0x3f3504f3, v45
	v_fmac_f32_e32 v49, 0xbf6c835e, v46
	v_mul_f32_e32 v50, v49, v220
	v_fmac_f32_e32 v50, v48, v212
	v_mul_f32_e32 v51, v48, v220
	v_fma_f32 v51, v49, v212, -v51
	v_cvt_pk_bf16_f32 v52, v50, v51
	ds_write_b16 v4, v52 offset:9112
	ds_write_b16_d16_hi v4, v52 offset:13464
	v_add_f32_e32 v48, v16, v24
	v_fmac_f32_e32 v48, 0xbf3504f3, v32
	v_fmac_f32_e32 v48, 0x3f3504f3, v34
	v_sub_f32_e32 v48, v48, v35
	v_fmac_f32_e32 v48, 0x3f3504f3, v36
	v_fmac_f32_e32 v48, 0xbf3504f3, v38
	v_mul_f32_e32 v49, 0xbf3504f3, v40
	v_add_f32_e32 v49, v49, v41
	v_fmac_f32_e32 v49, 0xbf3504f3, v42
	v_fmac_f32_e32 v49, 0x3f3504f3, v44
	v_sub_f32_e32 v49, v49, v45
	v_fmac_f32_e32 v49, 0x3f3504f3, v46
	v_mul_f32_e32 v50, v49, v221
	v_fmac_f32_e32 v50, v48, v213
	v_mul_f32_e32 v51, v48, v221
	v_fma_f32 v51, v49, v213, -v51
	v_cvt_pk_bf16_f32 v52, v50, v51
	ds_write_b16 v4, v52 offset:17816
	ds_write_b16_d16_hi v4, v52 offset:22168
	v_sub_f32_e32 v48, v16, v24
	v_fmac_f32_e32 v48, 0xbf6c835e, v32
	v_fmac_f32_e32 v48, 0x3f3504f3, v33
	v_fmac_f32_e32 v48, 0xbec3ef15, v34
	v_fmac_f32_e32 v48, 0x3ec3ef15, v36
	v_fmac_f32_e32 v48, 0xbf3504f3, v37
	v_fmac_f32_e32 v48, 0x3f6c835e, v38
	v_mul_f32_e32 v49, 0xbec3ef15, v40
	v_fmac_f32_e32 v49, 0x3f3504f3, v41
	v_fmac_f32_e32 v49, 0xbf6c835e, v42
	v_add_f32_e32 v49, v49, v43
	v_fmac_f32_e32 v49, 0xbf6c835e, v44
	v_fmac_f32_e32 v49, 0x3f3504f3, v45
	v_fmac_f32_e32 v49, 0xbec3ef15, v46
	v_mul_f32_e32 v50, v49, v222
	v_fmac_f32_e32 v50, v48, v214
	v_mul_f32_e32 v51, v48, v222
	v_fma_f32 v51, v49, v214, -v51
	v_cvt_pk_bf16_f32 v52, v50, v51
	ds_write_b16 v4, v52 offset:26520
	ds_write_b16_d16_hi v4, v52 offset:30872
	v_add_f32_e32 v48, v16, v24
	v_sub_f32_e32 v48, v48, v32
	v_add_f32_e32 v48, v48, v33
	v_sub_f32_e32 v48, v48, v34
	v_add_f32_e32 v48, v48, v35
	v_sub_f32_e32 v48, v48, v36
	v_add_f32_e32 v48, v48, v37
	v_sub_f32_e32 v48, v48, v38
	v_mul_f32_e32 v50, v48, v215
	v_mul_f32_e32 v51, v48, v223
	v_sub_f32_e32 v51, 0, v51
	v_cvt_pk_bf16_f32 v52, v50, v51
	ds_write_b16 v4, v52 offset:35224
	ds_write_b16_d16_hi v4, v52 offset:39576
	s_waitcnt lgkmcnt(0)
	s_barrier
	s_add_u32 s8, s26, 4096
	s_addc_u32 s9, s27, 0
	ds_read_b64 v[20:21], v5 offset:0
	ds_read_b64 v[22:23], v5 offset:8
	ds_read_b64 v[24:25], v5 offset:8704
	ds_read_b64 v[26:27], v5 offset:8712
	ds_read_b64 v[28:29], v5 offset:17408
	ds_read_b64 v[30:31], v5 offset:17416
	s_waitcnt lgkmcnt(4)
	global_store_dwordx4 v7, v[20:23], s[8:9]
	s_add_u32 s8, s8, 0x100000
	s_addc_u32 s9, s9, 0
	ds_read_b64 v[20:21], v5 offset:26112
	ds_read_b64 v[22:23], v5 offset:26120
	s_waitcnt lgkmcnt(4)
	global_store_dwordx4 v7, v[24:27], s[8:9]
	s_add_u32 s8, s8, 0x100000
	s_addc_u32 s9, s9, 0
	ds_read_b64 v[24:25], v6 offset:0
	ds_read_b64 v[26:27], v6 offset:8
	s_waitcnt lgkmcnt(4)
	global_store_dwordx4 v7, v[28:31], s[8:9]
	s_add_u32 s8, s8, 0x100000
	s_addc_u32 s9, s9, 0
	ds_read_b64 v[28:29], v6 offset:8704
	ds_read_b64 v[30:31], v6 offset:8712
	s_waitcnt lgkmcnt(4)
	global_store_dwordx4 v7, v[20:23], s[8:9]
	s_add_u32 s8, s8, 0x100000
	s_addc_u32 s9, s9, 0
	ds_read_b64 v[20:21], v6 offset:17408
	ds_read_b64 v[22:23], v6 offset:17416
	s_waitcnt lgkmcnt(4)
	global_store_dwordx4 v7, v[24:27], s[8:9]
	s_add_u32 s8, s8, 0x100000
	s_addc_u32 s9, s9, 0
	ds_read_b64 v[24:25], v6 offset:26112
	ds_read_b64 v[26:27], v6 offset:26120
	s_waitcnt lgkmcnt(4)
	global_store_dwordx4 v7, v[28:31], s[8:9]
	s_add_u32 s8, s8, 0x100000
	s_addc_u32 s9, s9, 0
	ds_read_b64 v[28:29], v6 offset:34816
	ds_read_b64 v[30:31], v6 offset:34824
	s_waitcnt lgkmcnt(4)
	global_store_dwordx4 v7, v[20:23], s[8:9]
	s_add_u32 s8, s8, 0x100000
	s_addc_u32 s9, s9, 0
	s_waitcnt lgkmcnt(2)
	global_store_dwordx4 v7, v[24:27], s[8:9]
	s_add_u32 s8, s8, 0x100000
	s_addc_u32 s9, s9, 0
	s_waitcnt lgkmcnt(0)
	global_store_dwordx4 v7, v[28:31], s[8:9]
	s_waitcnt vmcnt(18)
	v_add_u32_e32 v10, s38, v14
	v_cvt_f32_u32_e32 v10, v10
	v_mul_f32_e32 v11, 0x39800000, v10
	v_cos_f32_e32 v208, v11
	v_sin_f32_e32 v216, v11
	v_mul_f32_e32 v11, 0x3a000000, v10
	v_cos_f32_e32 v209, v11
	v_sin_f32_e32 v217, v11
	v_mul_f32_e32 v11, 0x3a400000, v10
	v_cos_f32_e32 v210, v11
	v_sin_f32_e32 v218, v11
	v_mul_f32_e32 v11, 0x3a800000, v10
	v_cos_f32_e32 v211, v11
	v_sin_f32_e32 v219, v11
	v_mul_f32_e32 v11, 0x3aa00000, v10
	v_cos_f32_e32 v212, v11
	v_sin_f32_e32 v220, v11
	v_mul_f32_e32 v11, 0x3ac00000, v10
	v_cos_f32_e32 v213, v11
	v_sin_f32_e32 v221, v11
	v_mul_f32_e32 v11, 0x3ae00000, v10
	v_cos_f32_e32 v214, v11
	v_sin_f32_e32 v222, v11
	v_mul_f32_e32 v11, 0x3b000000, v10
	v_cos_f32_e32 v215, v11
	v_sin_f32_e32 v223, v11
	s_barrier
; __device__ __forceinline__ bf16_t f2bf(float f) { return (bf16_t)(cvt_pk_bf16(f, 0.f) & 0xffffu); }
; __device__ __forceinline__ void dft16_phase(const Ctx& X, const bf16_t* HN, bf16_t* GT) {
;     ...
;                 for (int e = 0; e < 8; ++e) { float re = 0.f, im = 0.f;
; #pragma unroll
;                     for (int a = 0; a < 16; ++a) { const unsigned wv = xin[a][e >> 1]; const float x = (e & 1) ? bf2f(wv >> 16) : bf2f(wv & 0xffffu); re += x * cw[a]; im -= x * sw[a]; }
;                     const float orr = re * tc - im * ts, oi = re * ts + im * tc;
;                     tile[((kl * 2 + 0) * 64 + cchunk * 8 + e) * 72 + i] = f2bf(orr); tile[((kl * 2 + 1) * 64 + cchunk * 8 + e) * 72 + i] = f2bf(oi); } }
	v_lshlrev_b32_e32 v16, 16, v128
	v_lshlrev_b32_e32 v17, 16, v132
	v_lshlrev_b32_e32 v18, 16, v136
	v_lshlrev_b32_e32 v19, 16, v140
	v_lshlrev_b32_e32 v20, 16, v144
	v_lshlrev_b32_e32 v21, 16, v148
	v_lshlrev_b32_e32 v22, 16, v152
	v_lshlrev_b32_e32 v23, 16, v156
	v_lshlrev_b32_e32 v24, 16, v160
	v_lshlrev_b32_e32 v25, 16, v164
	v_lshlrev_b32_e32 v26, 16, v168
	v_lshlrev_b32_e32 v27, 16, v172
	v_lshlrev_b32_e32 v28, 16, v176
	v_lshlrev_b32_e32 v29, 16, v180
	v_lshlrev_b32_e32 v30, 16, v184
	v_lshlrev_b32_e32 v31, 16, v188
	v_add_f32_e32 v32, v17, v31
	v_sub_f32_e32 v40, v17, v31
	v_add_f32_e32 v33, v18, v30
	v_sub_f32_e32 v41, v18, v30
	v_add_f32_e32 v34, v19, v29
	v_sub_f32_e32 v42, v19, v29
	v_add_f32_e32 v35, v20, v28
	v_sub_f32_e32 v43, v20, v28
	v_add_f32_e32 v36, v21, v27
	v_sub_f32_e32 v44, v21, v27
	v_add_f32_e32 v37, v22, v26
	v_sub_f32_e32 v45, v22, v26
	v_add_f32_e32 v38, v23, v25
	v_sub_f32_e32 v46, v23, v25
	v_add_f32_e32 v48, v16, v24
	v_add_f32_e32 v48, v48, v32
	v_add_f32_e32 v48, v48, v33
	v_add_f32_e32 v48, v48, v34
	v_add_f32_e32 v48, v48, v35
	v_add_f32_e32 v48, v48, v36
	v_add_f32_e32 v48, v48, v37
	v_add_f32_e32 v48, v48, v38
	v_cvt_pk_bf16_f32 v52, v48, 0
	ds_write_b16 v3, v52 offset:0
	ds_write_b16_d16_hi v3, v52 offset:4352
	v_sub_f32_e32 v48, v16, v24
	v_fmac_f32_e32 v48, 0x3f6c835e, v32
	v_fmac_f32_e32 v48, 0x3f3504f3, v33
	v_fmac_f32_e32 v48, 0x3ec3ef15, v34
	v_fmac_f32_e32 v48, 0xbec3ef15, v36
	v_fmac_f32_e32 v48, 0xbf3504f3, v37
	v_fmac_f32_e32 v48, 0xbf6c835e, v38
	v_mul_f32_e32 v49, 0xbec3ef15, v40
	v_fmac_f32_e32 v49, 0xbf3504f3, v41
	v_fmac_f32_e32 v49, 0xbf6c835e, v42
	v_sub_f32_e32 v49, v49, v43
	v_fmac_f32_e32 v49, 0xbf6c835e, v44
	v_fmac_f32_e32 v49, 0xbf3504f3, v45
	v_fmac_f32_e32 v49, 0xbec3ef15, v46
	v_mul_f32_e32 v50, v49, v216
	v_fmac_f32_e32 v50, v48, v208
	v_mul_f32_e32 v51, v48, v216
	v_fma_f32 v51, v49, v208, -v51
	v_cvt_pk_bf16_f32 v52, v50, v51
	ds_write_b16 v3, v52 offset:8704
	ds_write_b16_d16_hi v3, v52 offset:13056
	v_add_f32_e32 v48, v16, v24
	v_fmac_f32_e32 v48, 0x3f3504f3, v32
	v_fmac_f32_e32 v48, 0xbf3504f3, v34
	v_sub_f32_e32 v48, v48, v35
	v_fmac_f32_e32 v48, 0xbf3504f3, v36
	v_fmac_f32_e32 v48, 0x3f3504f3, v38
	v_mul_f32_e32 v49, 0xbf3504f3, v40
	v_sub_f32_e32 v49, v49, v41
	v_fmac_f32_e32 v49, 0xbf3504f3, v42
	v_fmac_f32_e32 v49, 0x3f3504f3, v44
	v_add_f32_e32 v49, v49, v45
	v_fmac_f32_e32 v49, 0x3f3504f3, v46
	v_mul_f32_e32 v50, v49, v217
	v_fmac_f32_e32 v50, v48, v209
	v_mul_f32_e32 v51, v48, v217
	v_fma_f32 v51, v49, v209, -v51
	v_cvt_pk_bf16_f32 v52, v50, v51
	ds_write_b16 v3, v52 offset:17408
	ds_write_b16_d16_hi v3, v52 offset:21760
	v_sub_f32_e32 v48, v16, v24
	v_fmac_f32_e32 v48, 0x3ec3ef15, v32
	v_fmac_f32_e32 v48, 0xbf3504f3, v33
	v_fmac_f32_e32 v48, 0xbf6c835e, v34
	v_fmac_f32_e32 v48, 0x3f6c835e, v36
	v_fmac_f32_e32 v48, 0x3f3504f3, v37
	v_fmac_f32_e32 v48, 0xbec3ef15, v38
	v_mul_f32_e32 v49, 0xbf6c835e, v40
	v_fmac_f32_e32 v49, 0xbf3504f3, v41
	v_fmac_f32_e32 v49, 0x3ec3ef15, v42
	v_add_f32_e32 v49, v49, v43
	v_fmac_f32_e32 v49, 0x3ec3ef15, v44
	v_fmac_f32_e32 v49, 0xbf3504f3, v45
	v_fmac_f32_e32 v49, 0xbf6c835e, v46
	v_mul_f32_e32 v50, v49, v218
	v_fmac_f32_e32 v50, v48, v210
	v_mul_f32_e32 v51, v48, v218
	v_fma_f32 v51, v49, v210, -v51
	v_cvt_pk_bf16_f32 v52, v50, v51
	ds_write_b16 v3, v52 offset:26112
	ds_write_b16_d16_hi v3, v52 offset:30464
	v_add_f32_e32 v48, v16, v24
	v_sub_f32_e32 v48, v48, v33
	v_add_f32_e32 v48, v48, v35
	v_sub_f32_e32 v48, v48, v37
	v_sub_f32_e32 v49, 0, v40
	v_add_f32_e32 v49, v49, v42
	v_sub_f32_e32 v49, v49, v44
	v_add_f32_e32 v49, v49, v46
	v_mul_f32_e32 v50, v49, v219
	v_fmac_f32_e32 v50, v48, v211
	v_mul_f32_e32 v51, v48, v219
	v_fma_f32 v51, v49, v211, -v51
	v_cvt_pk_bf16_f32 v52, v50, v51
	ds_write_b16 v4, v52 offset:0
	ds_write_b16_d16_hi v4, v52 offset:4352
	v_sub_f32_e32 v48, v16, v24
	v_fmac_f32_e32 v48, 0xbec3ef15, v32
	v_fmac_f32_e32 v48, 0xbf3504f3, v33
	v_fmac_f32_e32 v48, 0x3f6c835e, v34
	v_fmac_f32_e32 v48, 0xbf6c835e, v36
	v_fmac_f32_e32 v48, 0x3f3504f3, v37
	v_fmac_f32_e32 v48, 0x3ec3ef15, v38
	v_mul_f32_e32 v49, 0xbf6c835e, v40
	v_fmac_f32_e32 v49, 0x3f3504f3, v41
	v_fmac_f32_e32 v49, 0x3ec3ef15, v42
	v_sub_f32_e32 v49, v49, v43
	v_fmac_f32_e32 v49, 0x3ec3ef15, v44
	v_fmac_f32_e32 v49, 0x3f3504f3, v45
	v_fmac_f32_e32 v49, 0xbf6c835e, v46
	v_mul_f32_e32 v50, v49, v220
	v_fmac_f32_e32 v50, v48, v212
	v_mul_f32_e32 v51, v48, v220
	v_fma_f32 v51, v49, v212, -v51
	v_cvt_pk_bf16_f32 v52, v50, v51
	ds_write_b16 v4, v52 offset:8704
	ds_write_b16_d16_hi v4, v52 offset:13056
	v_add_f32_e32 v48, v16, v24
	v_fmac_f32_e32 v48, 0xbf3504f3, v32
	v_fmac_f32_e32 v48, 0x3f3504f3, v34
	v_sub_f32_e32 v48, v48, v35
	v_fmac_f32_e32 v48, 0x3f3504f3, v36
	v_fmac_f32_e32 v48, 0xbf3504f3, v38
	v_mul_f32_e32 v49, 0xbf3504f3, v40
	v_add_f32_e32 v49, v49, v41
	v_fmac_f32_e32 v49, 0xbf3504f3, v42
	v_fmac_f32_e32 v49, 0x3f3504f3, v44
	v_sub_f32_e32 v49, v49, v45
	v_fmac_f32_e32 v49, 0x3f3504f3, v46
	v_mul_f32_e32 v50, v49, v221
	v_fmac_f32_e32 v50, v48, v213
	v_mul_f32_e32 v51, v48, v221
	v_fma_f32 v51, v49, v213, -v51
	v_cvt_pk_bf16_f32 v52, v50, v51
	ds_write_b16 v4, v52 offset:17408
	ds_write_b16_d16_hi v4, v52 offset:21760
	v_sub_f32_e32 v48, v16, v24
	v_fmac_f32_e32 v48, 0xbf6c835e, v32
	v_fmac_f32_e32 v48, 0x3f3504f3, v33
	v_fmac_f32_e32 v48, 0xbec3ef15, v34
	v_fmac_f32_e32 v48, 0x3ec3ef15, v36
	v_fmac_f32_e32 v48, 0xbf3504f3, v37
	v_fmac_f32_e32 v48, 0x3f6c835e, v38
	v_mul_f32_e32 v49, 0xbec3ef15, v40
	v_fmac_f32_e32 v49, 0x3f3504f3, v41
	v_fmac_f32_e32 v49, 0xbf6c835e, v42
	v_add_f32_e32 v49, v49, v43
	v_fmac_f32_e32 v49, 0xbf6c835e, v44
; __device__ __forceinline__ bf16_t f2bf(float f) { return (bf16_t)(cvt_pk_bf16(f, 0.f) & 0xffffu); }
; __device__ __forceinline__ void dft16_phase(const Ctx& X, const bf16_t* HN, bf16_t* GT) {
;     ...
;                 for (int e = 0; e < 8; ++e) { float re = 0.f, im = 0.f;
; #pragma unroll
;                     for (int a = 0; a < 16; ++a) { const unsigned wv = xin[a][e >> 1]; const float x = (e & 1) ? bf2f(wv >> 16) : bf2f(wv & 0xffffu); re += x * cw[a]; im -= x * sw[a]; }
;                     const float orr = re * tc - im * ts, oi = re * ts + im * tc;
;                     tile[((kl * 2 + 0) * 64 + cchunk * 8 + e) * 72 + i] = f2bf(orr); tile[((kl * 2 + 1) * 64 + cchunk * 8 + e) * 72 + i] = f2bf(oi); } }
	v_fmac_f32_e32 v49, 0x3f3504f3, v45
	v_fmac_f32_e32 v49, 0xbec3ef15, v46
	v_mul_f32_e32 v50, v49, v222
	v_fmac_f32_e32 v50, v48, v214
	v_mul_f32_e32 v51, v48, v222
	v_fma_f32 v51, v49, v214, -v51
	v_cvt_pk_bf16_f32 v52, v50, v51
	ds_write_b16 v4, v52 offset:26112
	ds_write_b16_d16_hi v4, v52 offset:30464
	v_add_f32_e32 v48, v16, v24
	v_sub_f32_e32 v48, v48, v32
	v_add_f32_e32 v48, v48, v33
	v_sub_f32_e32 v48, v48, v34
	v_add_f32_e32 v48, v48, v35
	v_sub_f32_e32 v48, v48, v36
	v_add_f32_e32 v48, v48, v37
	v_sub_f32_e32 v48, v48, v38
	v_mul_f32_e32 v50, v48, v215
	v_mul_f32_e32 v51, v48, v223
	v_sub_f32_e32 v51, 0, v51
	v_cvt_pk_bf16_f32 v52, v50, v51
	ds_write_b16 v4, v52 offset:34816
	ds_write_b16_d16_hi v4, v52 offset:39168
	v_and_b32_e32 v16, 0xffff0000, v128
	v_and_b32_e32 v17, 0xffff0000, v132
	v_and_b32_e32 v18, 0xffff0000, v136
	v_and_b32_e32 v19, 0xffff0000, v140
	v_and_b32_e32 v20, 0xffff0000, v144
	v_and_b32_e32 v21, 0xffff0000, v148
	v_and_b32_e32 v22, 0xffff0000, v152
	v_and_b32_e32 v23, 0xffff0000, v156
	v_and_b32_e32 v24, 0xffff0000, v160
	v_and_b32_e32 v25, 0xffff0000, v164
	v_and_b32_e32 v26, 0xffff0000, v168
	v_and_b32_e32 v27, 0xffff0000, v172
	v_and_b32_e32 v28, 0xffff0000, v176
	v_and_b32_e32 v29, 0xffff0000, v180
	v_and_b32_e32 v30, 0xffff0000, v184
	v_and_b32_e32 v31, 0xffff0000, v188
	v_add_f32_e32 v32, v17, v31
	v_sub_f32_e32 v40, v17, v31
	v_add_f32_e32 v33, v18, v30
	v_sub_f32_e32 v41, v18, v30
	v_add_f32_e32 v34, v19, v29
	v_sub_f32_e32 v42, v19, v29
	v_add_f32_e32 v35, v20, v28
	v_sub_f32_e32 v43, v20, v28
	v_add_f32_e32 v36, v21, v27
	v_sub_f32_e32 v44, v21, v27
	v_add_f32_e32 v37, v22, v26
	v_sub_f32_e32 v45, v22, v26
	v_add_f32_e32 v38, v23, v25
	v_sub_f32_e32 v46, v23, v25
	v_add_f32_e32 v48, v16, v24
	v_add_f32_e32 v48, v48, v32
	v_add_f32_e32 v48, v48, v33
	v_add_f32_e32 v48, v48, v34
	v_add_f32_e32 v48, v48, v35
	v_add_f32_e32 v48, v48, v36
	v_add_f32_e32 v48, v48, v37
	v_add_f32_e32 v48, v48, v38
	v_cvt_pk_bf16_f32 v52, v48, 0
	ds_write_b16 v3, v52 offset:136
	ds_write_b16_d16_hi v3, v52 offset:4488
	v_sub_f32_e32 v48, v16, v24
	v_fmac_f32_e32 v48, 0x3f6c835e, v32
	v_fmac_f32_e32 v48, 0x3f3504f3, v33
	v_fmac_f32_e32 v48, 0x3ec3ef15, v34
	v_fmac_f32_e32 v48, 0xbec3ef15, v36
	v_fmac_f32_e32 v48, 0xbf3504f3, v37
	v_fmac_f32_e32 v48, 0xbf6c835e, v38
	v_mul_f32_e32 v49, 0xbec3ef15, v40
	v_fmac_f32_e32 v49, 0xbf3504f3, v41
	v_fmac_f32_e32 v49, 0xbf6c835e, v42
	v_sub_f32_e32 v49, v49, v43
	v_fmac_f32_e32 v49, 0xbf6c835e, v44
	v_fmac_f32_e32 v49, 0xbf3504f3, v45
	v_fmac_f32_e32 v49, 0xbec3ef15, v46
	v_mul_f32_e32 v50, v49, v216
	v_fmac_f32_e32 v50, v48, v208
	v_mul_f32_e32 v51, v48, v216
	v_fma_f32 v51, v49, v208, -v51
	v_cvt_pk_bf16_f32 v52, v50, v51
	ds_write_b16 v3, v52 offset:8840
	ds_write_b16_d16_hi v3, v52 offset:13192
	v_add_f32_e32 v48, v16, v24
	v_fmac_f32_e32 v48, 0x3f3504f3, v32
	v_fmac_f32_e32 v48, 0xbf3504f3, v34
	v_sub_f32_e32 v48, v48, v35
	v_fmac_f32_e32 v48, 0xbf3504f3, v36
	v_fmac_f32_e32 v48, 0x3f3504f3, v38
	v_mul_f32_e32 v49, 0xbf3504f3, v40
	v_sub_f32_e32 v49, v49, v41
	v_fmac_f32_e32 v49, 0xbf3504f3, v42
	v_fmac_f32_e32 v49, 0x3f3504f3, v44
	v_add_f32_e32 v49, v49, v45
	v_fmac_f32_e32 v49, 0x3f3504f3, v46
	v_mul_f32_e32 v50, v49, v217
	v_fmac_f32_e32 v50, v48, v209
	v_mul_f32_e32 v51, v48, v217
	v_fma_f32 v51, v49, v209, -v51
	v_cvt_pk_bf16_f32 v52, v50, v51
	ds_write_b16 v3, v52 offset:17544
	ds_write_b16_d16_hi v3, v52 offset:21896
	v_sub_f32_e32 v48, v16, v24
	v_fmac_f32_e32 v48, 0x3ec3ef15, v32
	v_fmac_f32_e32 v48, 0xbf3504f3, v33
	v_fmac_f32_e32 v48, 0xbf6c835e, v34
	v_fmac_f32_e32 v48, 0x3f6c835e, v36
	v_fmac_f32_e32 v48, 0x3f3504f3, v37
	v_fmac_f32_e32 v48, 0xbec3ef15, v38
	v_mul_f32_e32 v49, 0xbf6c835e, v40
	v_fmac_f32_e32 v49, 0xbf3504f3, v41
	v_fmac_f32_e32 v49, 0x3ec3ef15, v42
	v_add_f32_e32 v49, v49, v43
	v_fmac_f32_e32 v49, 0x3ec3ef15, v44
	v_fmac_f32_e32 v49, 0xbf3504f3, v45
	v_fmac_f32_e32 v49, 0xbf6c835e, v46
	v_mul_f32_e32 v50, v49, v218
	v_fmac_f32_e32 v50, v48, v210
	v_mul_f32_e32 v51, v48, v218
	v_fma_f32 v51, v49, v210, -v51
	v_cvt_pk_bf16_f32 v52, v50, v51
	ds_write_b16 v3, v52 offset:26248
	ds_write_b16_d16_hi v3, v52 offset:30600
	v_add_f32_e32 v48, v16, v24
	v_sub_f32_e32 v48, v48, v33
	v_add_f32_e32 v48, v48, v35
	v_sub_f32_e32 v48, v48, v37
	v_sub_f32_e32 v49, 0, v40
	v_add_f32_e32 v49, v49, v42
	v_sub_f32_e32 v49, v49, v44
	v_add_f32_e32 v49, v49, v46
	v_mul_f32_e32 v50, v49, v219
	v_fmac_f32_e32 v50, v48, v211
	v_mul_f32_e32 v51, v48, v219
	v_fma_f32 v51, v49, v211, -v51
	v_cvt_pk_bf16_f32 v52, v50, v51
	ds_write_b16 v4, v52 offset:136
	ds_write_b16_d16_hi v4, v52 offset:4488
	v_sub_f32_e32 v48, v16, v24
	v_fmac_f32_e32 v48, 0xbec3ef15, v32
	v_fmac_f32_e32 v48, 0xbf3504f3, v33
	v_fmac_f32_e32 v48, 0x3f6c835e, v34
	v_fmac_f32_e32 v48, 0xbf6c835e, v36
	v_fmac_f32_e32 v48, 0x3f3504f3, v37
	v_fmac_f32_e32 v48, 0x3ec3ef15, v38
	v_mul_f32_e32 v49, 0xbf6c835e, v40
	v_fmac_f32_e32 v49, 0x3f3504f3, v41
	v_fmac_f32_e32 v49, 0x3ec3ef15, v42
	v_sub_f32_e32 v49, v49, v43
	v_fmac_f32_e32 v49, 0x3ec3ef15, v44
	v_fmac_f32_e32 v49, 0x3f3504f3, v45
	v_fmac_f32_e32 v49, 0xbf6c835e, v46
	v_mul_f32_e32 v50, v49, v220
	v_fmac_f32_e32 v50, v48, v212
	v_mul_f32_e32 v51, v48, v220
	v_fma_f32 v51, v49, v212, -v51
	v_cvt_pk_bf16_f32 v52, v50, v51
	ds_write_b16 v4, v52 offset:8840
	ds_write_b16_d16_hi v4, v52 offset:13192
	v_add_f32_e32 v48, v16, v24
	v_fmac_f32_e32 v48, 0xbf3504f3, v32
	v_fmac_f32_e32 v48, 0x3f3504f3, v34
	v_sub_f32_e32 v48, v48, v35
	v_fmac_f32_e32 v48, 0x3f3504f3, v36
	v_fmac_f32_e32 v48, 0xbf3504f3, v38
	v_mul_f32_e32 v49, 0xbf3504f3, v40
	v_add_f32_e32 v49, v49, v41
; __device__ __forceinline__ bf16_t f2bf(float f) { return (bf16_t)(cvt_pk_bf16(f, 0.f) & 0xffffu); }
; __device__ __forceinline__ void dft16_phase(const Ctx& X, const bf16_t* HN, bf16_t* GT) {
;     ...
;                 for (int e = 0; e < 8; ++e) { float re = 0.f, im = 0.f;
; #pragma unroll
;                     for (int a = 0; a < 16; ++a) { const unsigned wv = xin[a][e >> 1]; const float x = (e & 1) ? bf2f(wv >> 16) : bf2f(wv & 0xffffu); re += x * cw[a]; im -= x * sw[a]; }
;                     const float orr = re * tc - im * ts, oi = re * ts + im * tc;
;                     tile[((kl * 2 + 0) * 64 + cchunk * 8 + e) * 72 + i] = f2bf(orr); tile[((kl * 2 + 1) * 64 + cchunk * 8 + e) * 72 + i] = f2bf(oi); } }
	v_fmac_f32_e32 v49, 0xbf3504f3, v42
	v_fmac_f32_e32 v49, 0x3f3504f3, v44
	v_sub_f32_e32 v49, v49, v45
	v_fmac_f32_e32 v49, 0x3f3504f3, v46
	v_mul_f32_e32 v50, v49, v221
	v_fmac_f32_e32 v50, v48, v213
	v_mul_f32_e32 v51, v48, v221
	v_fma_f32 v51, v49, v213, -v51
	v_cvt_pk_bf16_f32 v52, v50, v51
	ds_write_b16 v4, v52 offset:17544
	ds_write_b16_d16_hi v4, v52 offset:21896
	v_sub_f32_e32 v48, v16, v24
	v_fmac_f32_e32 v48, 0xbf6c835e, v32
	v_fmac_f32_e32 v48, 0x3f3504f3, v33
	v_fmac_f32_e32 v48, 0xbec3ef15, v34
	v_fmac_f32_e32 v48, 0x3ec3ef15, v36
	v_fmac_f32_e32 v48, 0xbf3504f3, v37
	v_fmac_f32_e32 v48, 0x3f6c835e, v38
	v_mul_f32_e32 v49, 0xbec3ef15, v40
	v_fmac_f32_e32 v49, 0x3f3504f3, v41
	v_fmac_f32_e32 v49, 0xbf6c835e, v42
	v_add_f32_e32 v49, v49, v43
	v_fmac_f32_e32 v49, 0xbf6c835e, v44
	v_fmac_f32_e32 v49, 0x3f3504f3, v45
	v_fmac_f32_e32 v49, 0xbec3ef15, v46
	v_mul_f32_e32 v50, v49, v222
	v_fmac_f32_e32 v50, v48, v214
	v_mul_f32_e32 v51, v48, v222
	v_fma_f32 v51, v49, v214, -v51
	v_cvt_pk_bf16_f32 v52, v50, v51
	ds_write_b16 v4, v52 offset:26248
	ds_write_b16_d16_hi v4, v52 offset:30600
	v_add_f32_e32 v48, v16, v24
	v_sub_f32_e32 v48, v48, v32
	v_add_f32_e32 v48, v48, v33
	v_sub_f32_e32 v48, v48, v34
	v_add_f32_e32 v48, v48, v35
	v_sub_f32_e32 v48, v48, v36
	v_add_f32_e32 v48, v48, v37
	v_sub_f32_e32 v48, v48, v38
	v_mul_f32_e32 v50, v48, v215
	v_mul_f32_e32 v51, v48, v223
	v_sub_f32_e32 v51, 0, v51
	v_cvt_pk_bf16_f32 v52, v50, v51
	ds_write_b16 v4, v52 offset:34952
	ds_write_b16_d16_hi v4, v52 offset:39304
	v_lshlrev_b32_e32 v16, 16, v129
	v_lshlrev_b32_e32 v17, 16, v133
	v_lshlrev_b32_e32 v18, 16, v137
	v_lshlrev_b32_e32 v19, 16, v141
	v_lshlrev_b32_e32 v20, 16, v145
	v_lshlrev_b32_e32 v21, 16, v149
	v_lshlrev_b32_e32 v22, 16, v153
	v_lshlrev_b32_e32 v23, 16, v157
	v_lshlrev_b32_e32 v24, 16, v161
	v_lshlrev_b32_e32 v25, 16, v165
	v_lshlrev_b32_e32 v26, 16, v169
	v_lshlrev_b32_e32 v27, 16, v173
	v_lshlrev_b32_e32 v28, 16, v177
	v_lshlrev_b32_e32 v29, 16, v181
	v_lshlrev_b32_e32 v30, 16, v185
	v_lshlrev_b32_e32 v31, 16, v189
	v_add_f32_e32 v32, v17, v31
	v_sub_f32_e32 v40, v17, v31
	v_add_f32_e32 v33, v18, v30
	v_sub_f32_e32 v41, v18, v30
	v_add_f32_e32 v34, v19, v29
	v_sub_f32_e32 v42, v19, v29
	v_add_f32_e32 v35, v20, v28
	v_sub_f32_e32 v43, v20, v28
	v_add_f32_e32 v36, v21, v27
	v_sub_f32_e32 v44, v21, v27
	v_add_f32_e32 v37, v22, v26
	v_sub_f32_e32 v45, v22, v26
	v_add_f32_e32 v38, v23, v25
	v_sub_f32_e32 v46, v23, v25
	v_add_f32_e32 v48, v16, v24
	v_add_f32_e32 v48, v48, v32
	v_add_f32_e32 v48, v48, v33
	v_add_f32_e32 v48, v48, v34
	v_add_f32_e32 v48, v48, v35
	v_add_f32_e32 v48, v48, v36
	v_add_f32_e32 v48, v48, v37
	v_add_f32_e32 v48, v48, v38
	v_cvt_pk_bf16_f32 v52, v48, 0
	ds_write_b16 v3, v52 offset:272
	ds_write_b16_d16_hi v3, v52 offset:4624
	v_sub_f32_e32 v48, v16, v24
	v_fmac_f32_e32 v48, 0x3f6c835e, v32
	v_fmac_f32_e32 v48, 0x3f3504f3, v33
	v_fmac_f32_e32 v48, 0x3ec3ef15, v34
	v_fmac_f32_e32 v48, 0xbec3ef15, v36
	v_fmac_f32_e32 v48, 0xbf3504f3, v37
	v_fmac_f32_e32 v48, 0xbf6c835e, v38
	v_mul_f32_e32 v49, 0xbec3ef15, v40
	v_fmac_f32_e32 v49, 0xbf3504f3, v41
	v_fmac_f32_e32 v49, 0xbf6c835e, v42
	v_sub_f32_e32 v49, v49, v43
	v_fmac_f32_e32 v49, 0xbf6c835e, v44
	v_fmac_f32_e32 v49, 0xbf3504f3, v45
	v_fmac_f32_e32 v49, 0xbec3ef15, v46
	v_mul_f32_e32 v50, v49, v216
	v_fmac_f32_e32 v50, v48, v208
	v_mul_f32_e32 v51, v48, v216
	v_fma_f32 v51, v49, v208, -v51
	v_cvt_pk_bf16_f32 v52, v50, v51
	ds_write_b16 v3, v52 offset:8976
	ds_write_b16_d16_hi v3, v52 offset:13328
	v_add_f32_e32 v48, v16, v24
	v_fmac_f32_e32 v48, 0x3f3504f3, v32
	v_fmac_f32_e32 v48, 0xbf3504f3, v34
	v_sub_f32_e32 v48, v48, v35
	v_fmac_f32_e32 v48, 0xbf3504f3, v36
	v_fmac_f32_e32 v48, 0x3f3504f3, v38
	v_mul_f32_e32 v49, 0xbf3504f3, v40
	v_sub_f32_e32 v49, v49, v41
	v_fmac_f32_e32 v49, 0xbf3504f3, v42
	v_fmac_f32_e32 v49, 0x3f3504f3, v44
	v_add_f32_e32 v49, v49, v45
	v_fmac_f32_e32 v49, 0x3f3504f3, v46
	v_mul_f32_e32 v50, v49, v217
	v_fmac_f32_e32 v50, v48, v209
	v_mul_f32_e32 v51, v48, v217
	v_fma_f32 v51, v49, v209, -v51
	v_cvt_pk_bf16_f32 v52, v50, v51
	ds_write_b16 v3, v52 offset:17680
	ds_write_b16_d16_hi v3, v52 offset:22032
	v_sub_f32_e32 v48, v16, v24
	v_fmac_f32_e32 v48, 0x3ec3ef15, v32
	v_fmac_f32_e32 v48, 0xbf3504f3, v33
	v_fmac_f32_e32 v48, 0xbf6c835e, v34
	v_fmac_f32_e32 v48, 0x3f6c835e, v36
	v_fmac_f32_e32 v48, 0x3f3504f3, v37
	v_fmac_f32_e32 v48, 0xbec3ef15, v38
	v_mul_f32_e32 v49, 0xbf6c835e, v40
	v_fmac_f32_e32 v49, 0xbf3504f3, v41
	v_fmac_f32_e32 v49, 0x3ec3ef15, v42
	v_add_f32_e32 v49, v49, v43
	v_fmac_f32_e32 v49, 0x3ec3ef15, v44
	v_fmac_f32_e32 v49, 0xbf3504f3, v45
	v_fmac_f32_e32 v49, 0xbf6c835e, v46
	v_mul_f32_e32 v50, v49, v218
	v_fmac_f32_e32 v50, v48, v210
	v_mul_f32_e32 v51, v48, v218
	v_fma_f32 v51, v49, v210, -v51
	v_cvt_pk_bf16_f32 v52, v50, v51
	ds_write_b16 v3, v52 offset:26384
	ds_write_b16_d16_hi v3, v52 offset:30736
	v_add_f32_e32 v48, v16, v24
	v_sub_f32_e32 v48, v48, v33
	v_add_f32_e32 v48, v48, v35
	v_sub_f32_e32 v48, v48, v37
	v_sub_f32_e32 v49, 0, v40
	v_add_f32_e32 v49, v49, v42
	v_sub_f32_e32 v49, v49, v44
	v_add_f32_e32 v49, v49, v46
	v_mul_f32_e32 v50, v49, v219
	v_fmac_f32_e32 v50, v48, v211
	v_mul_f32_e32 v51, v48, v219
	v_fma_f32 v51, v49, v211, -v51
	v_cvt_pk_bf16_f32 v52, v50, v51
	ds_write_b16 v4, v52 offset:272
	ds_write_b16_d16_hi v4, v52 offset:4624
	v_sub_f32_e32 v48, v16, v24
	v_fmac_f32_e32 v48, 0xbec3ef15, v32
	v_fmac_f32_e32 v48, 0xbf3504f3, v33
	v_fmac_f32_e32 v48, 0x3f6c835e, v34
	v_fmac_f32_e32 v48, 0xbf6c835e, v36
	v_fmac_f32_e32 v48, 0x3f3504f3, v37
	v_fmac_f32_e32 v48, 0x3ec3ef15, v38
; __device__ __forceinline__ bf16_t f2bf(float f) { return (bf16_t)(cvt_pk_bf16(f, 0.f) & 0xffffu); }
; __device__ __forceinline__ void dft16_phase(const Ctx& X, const bf16_t* HN, bf16_t* GT) {
;     ...
;                 for (int e = 0; e < 8; ++e) { float re = 0.f, im = 0.f;
; #pragma unroll
;                     for (int a = 0; a < 16; ++a) { const unsigned wv = xin[a][e >> 1]; const float x = (e & 1) ? bf2f(wv >> 16) : bf2f(wv & 0xffffu); re += x * cw[a]; im -= x * sw[a]; }
;                     const float orr = re * tc - im * ts, oi = re * ts + im * tc;
;                     tile[((kl * 2 + 0) * 64 + cchunk * 8 + e) * 72 + i] = f2bf(orr); tile[((kl * 2 + 1) * 64 + cchunk * 8 + e) * 72 + i] = f2bf(oi); } }
	v_mul_f32_e32 v49, 0xbf6c835e, v40
	v_fmac_f32_e32 v49, 0x3f3504f3, v41
	v_fmac_f32_e32 v49, 0x3ec3ef15, v42
	v_sub_f32_e32 v49, v49, v43
	v_fmac_f32_e32 v49, 0x3ec3ef15, v44
	v_fmac_f32_e32 v49, 0x3f3504f3, v45
	v_fmac_f32_e32 v49, 0xbf6c835e, v46
	v_mul_f32_e32 v50, v49, v220
	v_fmac_f32_e32 v50, v48, v212
	v_mul_f32_e32 v51, v48, v220
	v_fma_f32 v51, v49, v212, -v51
	v_cvt_pk_bf16_f32 v52, v50, v51
	ds_write_b16 v4, v52 offset:8976
	ds_write_b16_d16_hi v4, v52 offset:13328
	v_add_f32_e32 v48, v16, v24
	v_fmac_f32_e32 v48, 0xbf3504f3, v32
	v_fmac_f32_e32 v48, 0x3f3504f3, v34
	v_sub_f32_e32 v48, v48, v35
	v_fmac_f32_e32 v48, 0x3f3504f3, v36
	v_fmac_f32_e32 v48, 0xbf3504f3, v38
	v_mul_f32_e32 v49, 0xbf3504f3, v40
	v_add_f32_e32 v49, v49, v41
	v_fmac_f32_e32 v49, 0xbf3504f3, v42
	v_fmac_f32_e32 v49, 0x3f3504f3, v44
	v_sub_f32_e32 v49, v49, v45
	v_fmac_f32_e32 v49, 0x3f3504f3, v46
	v_mul_f32_e32 v50, v49, v221
	v_fmac_f32_e32 v50, v48, v213
	v_mul_f32_e32 v51, v48, v221
	v_fma_f32 v51, v49, v213, -v51
	v_cvt_pk_bf16_f32 v52, v50, v51
	ds_write_b16 v4, v52 offset:17680
	ds_write_b16_d16_hi v4, v52 offset:22032
	v_sub_f32_e32 v48, v16, v24
	v_fmac_f32_e32 v48, 0xbf6c835e, v32
	v_fmac_f32_e32 v48, 0x3f3504f3, v33
	v_fmac_f32_e32 v48, 0xbec3ef15, v34
	v_fmac_f32_e32 v48, 0x3ec3ef15, v36
	v_fmac_f32_e32 v48, 0xbf3504f3, v37
	v_fmac_f32_e32 v48, 0x3f6c835e, v38
	v_mul_f32_e32 v49, 0xbec3ef15, v40
	v_fmac_f32_e32 v49, 0x3f3504f3, v41
	v_fmac_f32_e32 v49, 0xbf6c835e, v42
	v_add_f32_e32 v49, v49, v43
	v_fmac_f32_e32 v49, 0xbf6c835e, v44
	v_fmac_f32_e32 v49, 0x3f3504f3, v45
	v_fmac_f32_e32 v49, 0xbec3ef15, v46
	v_mul_f32_e32 v50, v49, v222
	v_fmac_f32_e32 v50, v48, v214
	v_mul_f32_e32 v51, v48, v222
	v_fma_f32 v51, v49, v214, -v51
	v_cvt_pk_bf16_f32 v52, v50, v51
	ds_write_b16 v4, v52 offset:26384
	ds_write_b16_d16_hi v4, v52 offset:30736
	v_add_f32_e32 v48, v16, v24
	v_sub_f32_e32 v48, v48, v32
	v_add_f32_e32 v48, v48, v33
	v_sub_f32_e32 v48, v48, v34
	v_add_f32_e32 v48, v48, v35
	v_sub_f32_e32 v48, v48, v36
	v_add_f32_e32 v48, v48, v37
	v_sub_f32_e32 v48, v48, v38
	v_mul_f32_e32 v50, v48, v215
	v_mul_f32_e32 v51, v48, v223
	v_sub_f32_e32 v51, 0, v51
	v_cvt_pk_bf16_f32 v52, v50, v51
	ds_write_b16 v4, v52 offset:35088
	ds_write_b16_d16_hi v4, v52 offset:39440
	v_and_b32_e32 v16, 0xffff0000, v129
	v_and_b32_e32 v17, 0xffff0000, v133
	v_and_b32_e32 v18, 0xffff0000, v137
	v_and_b32_e32 v19, 0xffff0000, v141
	v_and_b32_e32 v20, 0xffff0000, v145
	v_and_b32_e32 v21, 0xffff0000, v149
	v_and_b32_e32 v22, 0xffff0000, v153
	v_and_b32_e32 v23, 0xffff0000, v157
	v_and_b32_e32 v24, 0xffff0000, v161
	v_and_b32_e32 v25, 0xffff0000, v165
	v_and_b32_e32 v26, 0xffff0000, v169
	v_and_b32_e32 v27, 0xffff0000, v173
	v_and_b32_e32 v28, 0xffff0000, v177
	v_and_b32_e32 v29, 0xffff0000, v181
	v_and_b32_e32 v30, 0xffff0000, v185
	v_and_b32_e32 v31, 0xffff0000, v189
	v_add_f32_e32 v32, v17, v31
	v_sub_f32_e32 v40, v17, v31
	v_add_f32_e32 v33, v18, v30
	v_sub_f32_e32 v41, v18, v30
	v_add_f32_e32 v34, v19, v29
	v_sub_f32_e32 v42, v19, v29
	v_add_f32_e32 v35, v20, v28
	v_sub_f32_e32 v43, v20, v28
	v_add_f32_e32 v36, v21, v27
	v_sub_f32_e32 v44, v21, v27
	v_add_f32_e32 v37, v22, v26
	v_sub_f32_e32 v45, v22, v26
	v_add_f32_e32 v38, v23, v25
	v_sub_f32_e32 v46, v23, v25
	v_add_f32_e32 v48, v16, v24
	v_add_f32_e32 v48, v48, v32
	v_add_f32_e32 v48, v48, v33
	v_add_f32_e32 v48, v48, v34
	v_add_f32_e32 v48, v48, v35
	v_add_f32_e32 v48, v48, v36
	v_add_f32_e32 v48, v48, v37
	v_add_f32_e32 v48, v48, v38
	v_cvt_pk_bf16_f32 v52, v48, 0
	ds_write_b16 v3, v52 offset:408
	ds_write_b16_d16_hi v3, v52 offset:4760
	v_sub_f32_e32 v48, v16, v24
	v_fmac_f32_e32 v48, 0x3f6c835e, v32
	v_fmac_f32_e32 v48, 0x3f3504f3, v33
	v_fmac_f32_e32 v48, 0x3ec3ef15, v34
	v_fmac_f32_e32 v48, 0xbec3ef15, v36
	v_fmac_f32_e32 v48, 0xbf3504f3, v37
	v_fmac_f32_e32 v48, 0xbf6c835e, v38
	v_mul_f32_e32 v49, 0xbec3ef15, v40
	v_fmac_f32_e32 v49, 0xbf3504f3, v41
	v_fmac_f32_e32 v49, 0xbf6c835e, v42
	v_sub_f32_e32 v49, v49, v43
	v_fmac_f32_e32 v49, 0xbf6c835e, v44
	v_fmac_f32_e32 v49, 0xbf3504f3, v45
	v_fmac_f32_e32 v49, 0xbec3ef15, v46
	v_mul_f32_e32 v50, v49, v216
	v_fmac_f32_e32 v50, v48, v208
	v_mul_f32_e32 v51, v48, v216
	v_fma_f32 v51, v49, v208, -v51
	v_cvt_pk_bf16_f32 v52, v50, v51
	ds_write_b16 v3, v52 offset:9112
	ds_write_b16_d16_hi v3, v52 offset:13464
	v_add_f32_e32 v48, v16, v24
	v_fmac_f32_e32 v48, 0x3f3504f3, v32
	v_fmac_f32_e32 v48, 0xbf3504f3, v34
	v_sub_f32_e32 v48, v48, v35
	v_fmac_f32_e32 v48, 0xbf3504f3, v36
	v_fmac_f32_e32 v48, 0x3f3504f3, v38
	v_mul_f32_e32 v49, 0xbf3504f3, v40
	v_sub_f32_e32 v49, v49, v41
	v_fmac_f32_e32 v49, 0xbf3504f3, v42
	v_fmac_f32_e32 v49, 0x3f3504f3, v44
	v_add_f32_e32 v49, v49, v45
	v_fmac_f32_e32 v49, 0x3f3504f3, v46
	v_mul_f32_e32 v50, v49, v217
	v_fmac_f32_e32 v50, v48, v209
	v_mul_f32_e32 v51, v48, v217
	v_fma_f32 v51, v49, v209, -v51
	v_cvt_pk_bf16_f32 v52, v50, v51
	ds_write_b16 v3, v52 offset:17816
	ds_write_b16_d16_hi v3, v52 offset:22168
	v_sub_f32_e32 v48, v16, v24
	v_fmac_f32_e32 v48, 0x3ec3ef15, v32
	v_fmac_f32_e32 v48, 0xbf3504f3, v33
	v_fmac_f32_e32 v48, 0xbf6c835e, v34
	v_fmac_f32_e32 v48, 0x3f6c835e, v36
	v_fmac_f32_e32 v48, 0x3f3504f3, v37
	v_fmac_f32_e32 v48, 0xbec3ef15, v38
	v_mul_f32_e32 v49, 0xbf6c835e, v40
	v_fmac_f32_e32 v49, 0xbf3504f3, v41
	v_fmac_f32_e32 v49, 0x3ec3ef15, v42
	v_add_f32_e32 v49, v49, v43
	v_fmac_f32_e32 v49, 0x3ec3ef15, v44
	v_fmac_f32_e32 v49, 0xbf3504f3, v45
	v_fmac_f32_e32 v49, 0xbf6c835e, v46
	v_mul_f32_e32 v50, v49, v218
	v_fmac_f32_e32 v50, v48, v210
	v_mul_f32_e32 v51, v48, v218
	v_fma_f32 v51, v49, v210, -v51
; __device__ __forceinline__ bf16_t f2bf(float f) { return (bf16_t)(cvt_pk_bf16(f, 0.f) & 0xffffu); }
; __device__ __forceinline__ void dft16_phase(const Ctx& X, const bf16_t* HN, bf16_t* GT) {
;     ...
;                 for (int e = 0; e < 8; ++e) { float re = 0.f, im = 0.f;
; #pragma unroll
;                     for (int a = 0; a < 16; ++a) { const unsigned wv = xin[a][e >> 1]; const float x = (e & 1) ? bf2f(wv >> 16) : bf2f(wv & 0xffffu); re += x * cw[a]; im -= x * sw[a]; }
;                     const float orr = re * tc - im * ts, oi = re * ts + im * tc;
;                     tile[((kl * 2 + 0) * 64 + cchunk * 8 + e) * 72 + i] = f2bf(orr); tile[((kl * 2 + 1) * 64 + cchunk * 8 + e) * 72 + i] = f2bf(oi); } }
;             __syncthreads();
; #pragma unroll
;             for (int q = 0; q < 8; ++q) { const int cid = q * 512 + X.tid, row = cid >> 3, c8 = cid & 7, kl = row >> 7, ri = (row >> 6) & 1, ch = row & 63;
;                 if (kq * 4 + kl > 8) continue;
;                 const u32x4 v = *(const u32x4*)(tile + row * 72 + c8 * 8);
;                 *(u32x4*)(GT + ((size_t)(b * 9 + kq * 4 + kl) * 1024 + ch0 + ch) * 512 + ri * 256 + b0 + c8 * 8) = v; }
	v_cvt_pk_bf16_f32 v52, v50, v51
	ds_write_b16 v3, v52 offset:26520
	ds_write_b16_d16_hi v3, v52 offset:30872
	v_add_f32_e32 v48, v16, v24
	v_sub_f32_e32 v48, v48, v33
	v_add_f32_e32 v48, v48, v35
	v_sub_f32_e32 v48, v48, v37
	v_sub_f32_e32 v49, 0, v40
	v_add_f32_e32 v49, v49, v42
	v_sub_f32_e32 v49, v49, v44
	v_add_f32_e32 v49, v49, v46
	v_mul_f32_e32 v50, v49, v219
	v_fmac_f32_e32 v50, v48, v211
	v_mul_f32_e32 v51, v48, v219
	v_fma_f32 v51, v49, v211, -v51
	v_cvt_pk_bf16_f32 v52, v50, v51
	ds_write_b16 v4, v52 offset:408
	ds_write_b16_d16_hi v4, v52 offset:4760
	v_sub_f32_e32 v48, v16, v24
	v_fmac_f32_e32 v48, 0xbec3ef15, v32
	v_fmac_f32_e32 v48, 0xbf3504f3, v33
	v_fmac_f32_e32 v48, 0x3f6c835e, v34
	v_fmac_f32_e32 v48, 0xbf6c835e, v36
	v_fmac_f32_e32 v48, 0x3f3504f3, v37
	v_fmac_f32_e32 v48, 0x3ec3ef15, v38
	v_mul_f32_e32 v49, 0xbf6c835e, v40
	v_fmac_f32_e32 v49, 0x3f3504f3, v41
	v_fmac_f32_e32 v49, 0x3ec3ef15, v42
	v_sub_f32_e32 v49, v49, v43
	v_fmac_f32_e32 v49, 0x3ec3ef15, v44
	v_fmac_f32_e32 v49, 0x3f3504f3, v45
	v_fmac_f32_e32 v49, 0xbf6c835e, v46
	v_mul_f32_e32 v50, v49, v220
	v_fmac_f32_e32 v50, v48, v212
	v_mul_f32_e32 v51, v48, v220
	v_fma_f32 v51, v49, v212, -v51
	v_cvt_pk_bf16_f32 v52, v50, v51
	ds_write_b16 v4, v52 offset:9112
	ds_write_b16_d16_hi v4, v52 offset:13464
	v_add_f32_e32 v48, v16, v24
	v_fmac_f32_e32 v48, 0xbf3504f3, v32
	v_fmac_f32_e32 v48, 0x3f3504f3, v34
	v_sub_f32_e32 v48, v48, v35
	v_fmac_f32_e32 v48, 0x3f3504f3, v36
	v_fmac_f32_e32 v48, 0xbf3504f3, v38
	v_mul_f32_e32 v49, 0xbf3504f3, v40
	v_add_f32_e32 v49, v49, v41
	v_fmac_f32_e32 v49, 0xbf3504f3, v42
	v_fmac_f32_e32 v49, 0x3f3504f3, v44
	v_sub_f32_e32 v49, v49, v45
	v_fmac_f32_e32 v49, 0x3f3504f3, v46
	v_mul_f32_e32 v50, v49, v221
	v_fmac_f32_e32 v50, v48, v213
	v_mul_f32_e32 v51, v48, v221
	v_fma_f32 v51, v49, v213, -v51
	v_cvt_pk_bf16_f32 v52, v50, v51
	ds_write_b16 v4, v52 offset:17816
	ds_write_b16_d16_hi v4, v52 offset:22168
	v_sub_f32_e32 v48, v16, v24
	v_fmac_f32_e32 v48, 0xbf6c835e, v32
	v_fmac_f32_e32 v48, 0x3f3504f3, v33
	v_fmac_f32_e32 v48, 0xbec3ef15, v34
	v_fmac_f32_e32 v48, 0x3ec3ef15, v36
	v_fmac_f32_e32 v48, 0xbf3504f3, v37
	v_fmac_f32_e32 v48, 0x3f6c835e, v38
	v_mul_f32_e32 v49, 0xbec3ef15, v40
	v_fmac_f32_e32 v49, 0x3f3504f3, v41
	v_fmac_f32_e32 v49, 0xbf6c835e, v42
	v_add_f32_e32 v49, v49, v43
	v_fmac_f32_e32 v49, 0xbf6c835e, v44
	v_fmac_f32_e32 v49, 0x3f3504f3, v45
	v_fmac_f32_e32 v49, 0xbec3ef15, v46
	v_mul_f32_e32 v50, v49, v222
	v_fmac_f32_e32 v50, v48, v214
	v_mul_f32_e32 v51, v48, v222
	v_fma_f32 v51, v49, v214, -v51
	v_cvt_pk_bf16_f32 v52, v50, v51
	ds_write_b16 v4, v52 offset:26520
	ds_write_b16_d16_hi v4, v52 offset:30872
	v_add_f32_e32 v48, v16, v24
	v_sub_f32_e32 v48, v48, v32
	v_add_f32_e32 v48, v48, v33
	v_sub_f32_e32 v48, v48, v34
	v_add_f32_e32 v48, v48, v35
	v_sub_f32_e32 v48, v48, v36
	v_add_f32_e32 v48, v48, v37
	v_sub_f32_e32 v48, v48, v38
	v_mul_f32_e32 v50, v48, v215
	v_mul_f32_e32 v51, v48, v223
	v_sub_f32_e32 v51, 0, v51
	v_cvt_pk_bf16_f32 v52, v50, v51
	ds_write_b16 v4, v52 offset:35224
	ds_write_b16_d16_hi v4, v52 offset:39576
	s_waitcnt lgkmcnt(0)
	s_barrier
	s_add_u32 s8, s36, 0
	s_addc_u32 s9, s37, 0
	ds_read_b64 v[20:21], v5 offset:0
	ds_read_b64 v[22:23], v5 offset:8
	ds_read_b64 v[24:25], v5 offset:8704
	ds_read_b64 v[26:27], v5 offset:8712
	ds_read_b64 v[28:29], v5 offset:17408
	ds_read_b64 v[30:31], v5 offset:17416
	s_waitcnt lgkmcnt(4)
	global_store_dwordx4 v7, v[20:23], s[8:9]
	s_add_u32 s8, s8, 0x100000
	s_addc_u32 s9, s9, 0
	ds_read_b64 v[20:21], v5 offset:26112
	ds_read_b64 v[22:23], v5 offset:26120
	s_waitcnt lgkmcnt(4)
	global_store_dwordx4 v7, v[24:27], s[8:9]
	s_add_u32 s8, s8, 0x100000
	s_addc_u32 s9, s9, 0
	ds_read_b64 v[24:25], v6 offset:0
	ds_read_b64 v[26:27], v6 offset:8
	s_waitcnt lgkmcnt(4)
	global_store_dwordx4 v7, v[28:31], s[8:9]
	s_add_u32 s8, s8, 0x100000
	s_addc_u32 s9, s9, 0
	ds_read_b64 v[28:29], v6 offset:8704
	ds_read_b64 v[30:31], v6 offset:8712
	s_waitcnt lgkmcnt(4)
	global_store_dwordx4 v7, v[20:23], s[8:9]
	s_add_u32 s8, s8, 0x100000
	s_addc_u32 s9, s9, 0
	ds_read_b64 v[20:21], v6 offset:17408
	ds_read_b64 v[22:23], v6 offset:17416
	s_waitcnt lgkmcnt(4)
	global_store_dwordx4 v7, v[24:27], s[8:9]
	s_add_u32 s8, s8, 0x100000
	s_addc_u32 s9, s9, 0
	ds_read_b64 v[24:25], v6 offset:26112
	ds_read_b64 v[26:27], v6 offset:26120
	s_waitcnt lgkmcnt(4)
	global_store_dwordx4 v7, v[28:31], s[8:9]
	s_add_u32 s8, s8, 0x100000
	s_addc_u32 s9, s9, 0
	ds_read_b64 v[28:29], v6 offset:34816
	ds_read_b64 v[30:31], v6 offset:34824
	s_waitcnt lgkmcnt(4)
	global_store_dwordx4 v7, v[20:23], s[8:9]
	s_add_u32 s8, s8, 0x100000
	s_addc_u32 s9, s9, 0
	s_waitcnt lgkmcnt(2)
	global_store_dwordx4 v7, v[24:27], s[8:9]
	s_add_u32 s8, s8, 0x100000
	s_addc_u32 s9, s9, 0
	s_waitcnt lgkmcnt(0)
	global_store_dwordx4 v7, v[28:31], s[8:9]
	s_barrier
; __device__ __forceinline__ bf16_t f2bf(float f) { return (bf16_t)(cvt_pk_bf16(f, 0.f) & 0xffffu); }
; __device__ __forceinline__ void dft16_phase(const Ctx& X, const bf16_t* HN, bf16_t* GT) {
;     ...
;             for (int kl = 0; kl < 4; ++kl) { const int ka = kq * 4 + kl; if (ka > 8) break;
;                 const float tang = (float)(bp * ka) * (1.0f / 2048.0f); const float tc = cospif(tang), ts = -sinpif(tang);
;                 float cw[16], sw[16];
; #pragma unroll
;                 for (int a = 0; a < 16; ++a) { const int m = (a * ka) & 15; cw[a] = T16[m]; sw[a] = T16[16 + m]; }
; #pragma unroll
;                 for (int e = 0; e < 8; ++e) { float re = 0.f, im = 0.f;
; #pragma unroll
;                     for (int a = 0; a < 16; ++a) { const unsigned wv = xin[a][e >> 1]; const float x = (e & 1) ? bf2f(wv >> 16) : bf2f(wv & 0xffffu); re += x * cw[a]; im -= x * sw[a]; }
;                     const float orr = re * tc - im * ts, oi = re * ts + im * tc;
;                     tile[((kl * 2 + 0) * 64 + cchunk * 8 + e) * 72 + i] = f2bf(orr); tile[((kl * 2 + 1) * 64 + cchunk * 8 + e) * 72 + i] = f2bf(oi); } }
	v_lshlrev_b32_e32 v16, 16, v130
	v_lshlrev_b32_e32 v17, 16, v134
	v_lshlrev_b32_e32 v18, 16, v138
	v_lshlrev_b32_e32 v19, 16, v142
	v_lshlrev_b32_e32 v20, 16, v146
	v_lshlrev_b32_e32 v21, 16, v150
	v_lshlrev_b32_e32 v22, 16, v154
	v_lshlrev_b32_e32 v23, 16, v158
	v_lshlrev_b32_e32 v24, 16, v162
	v_lshlrev_b32_e32 v25, 16, v166
	v_lshlrev_b32_e32 v26, 16, v170
	v_lshlrev_b32_e32 v27, 16, v174
	v_lshlrev_b32_e32 v28, 16, v178
	v_lshlrev_b32_e32 v29, 16, v182
	v_lshlrev_b32_e32 v30, 16, v186
	v_lshlrev_b32_e32 v31, 16, v190
	v_add_f32_e32 v32, v17, v31
	v_sub_f32_e32 v40, v17, v31
	v_add_f32_e32 v33, v18, v30
	v_sub_f32_e32 v41, v18, v30
	v_add_f32_e32 v34, v19, v29
	v_sub_f32_e32 v42, v19, v29
	v_add_f32_e32 v35, v20, v28
	v_sub_f32_e32 v43, v20, v28
	v_add_f32_e32 v36, v21, v27
	v_sub_f32_e32 v44, v21, v27
	v_add_f32_e32 v37, v22, v26
	v_sub_f32_e32 v45, v22, v26
	v_add_f32_e32 v38, v23, v25
	v_sub_f32_e32 v46, v23, v25
	v_add_f32_e32 v48, v16, v24
	v_add_f32_e32 v48, v48, v32
	v_add_f32_e32 v48, v48, v33
	v_add_f32_e32 v48, v48, v34
	v_add_f32_e32 v48, v48, v35
	v_add_f32_e32 v48, v48, v36
	v_add_f32_e32 v48, v48, v37
	v_add_f32_e32 v48, v48, v38
	v_cvt_pk_bf16_f32 v52, v48, 0
	ds_write_b16 v3, v52 offset:0
	ds_write_b16_d16_hi v3, v52 offset:4352
	v_sub_f32_e32 v48, v16, v24
	v_fmac_f32_e32 v48, 0x3f6c835e, v32
	v_fmac_f32_e32 v48, 0x3f3504f3, v33
	v_fmac_f32_e32 v48, 0x3ec3ef15, v34
	v_fmac_f32_e32 v48, 0xbec3ef15, v36
	v_fmac_f32_e32 v48, 0xbf3504f3, v37
	v_fmac_f32_e32 v48, 0xbf6c835e, v38
	v_mul_f32_e32 v49, 0xbec3ef15, v40
	v_fmac_f32_e32 v49, 0xbf3504f3, v41
	v_fmac_f32_e32 v49, 0xbf6c835e, v42
	v_sub_f32_e32 v49, v49, v43
	v_fmac_f32_e32 v49, 0xbf6c835e, v44
	v_fmac_f32_e32 v49, 0xbf3504f3, v45
	v_fmac_f32_e32 v49, 0xbec3ef15, v46
	v_mul_f32_e32 v50, v49, v216
	v_fmac_f32_e32 v50, v48, v208
	v_mul_f32_e32 v51, v48, v216
	v_fma_f32 v51, v49, v208, -v51
	v_cvt_pk_bf16_f32 v52, v50, v51
	ds_write_b16 v3, v52 offset:8704
	ds_write_b16_d16_hi v3, v52 offset:13056
	v_add_f32_e32 v48, v16, v24
	v_fmac_f32_e32 v48, 0x3f3504f3, v32
	v_fmac_f32_e32 v48, 0xbf3504f3, v34
	v_sub_f32_e32 v48, v48, v35
	v_fmac_f32_e32 v48, 0xbf3504f3, v36
	v_fmac_f32_e32 v48, 0x3f3504f3, v38
	v_mul_f32_e32 v49, 0xbf3504f3, v40
	v_sub_f32_e32 v49, v49, v41
	v_fmac_f32_e32 v49, 0xbf3504f3, v42
	v_fmac_f32_e32 v49, 0x3f3504f3, v44
	v_add_f32_e32 v49, v49, v45
	v_fmac_f32_e32 v49, 0x3f3504f3, v46
	v_mul_f32_e32 v50, v49, v217
	v_fmac_f32_e32 v50, v48, v209
	v_mul_f32_e32 v51, v48, v217
	v_fma_f32 v51, v49, v209, -v51
	v_cvt_pk_bf16_f32 v52, v50, v51
	ds_write_b16 v3, v52 offset:17408
	ds_write_b16_d16_hi v3, v52 offset:21760
	v_sub_f32_e32 v48, v16, v24
	v_fmac_f32_e32 v48, 0x3ec3ef15, v32
	v_fmac_f32_e32 v48, 0xbf3504f3, v33
	v_fmac_f32_e32 v48, 0xbf6c835e, v34
	v_fmac_f32_e32 v48, 0x3f6c835e, v36
	v_fmac_f32_e32 v48, 0x3f3504f3, v37
	v_fmac_f32_e32 v48, 0xbec3ef15, v38
	v_mul_f32_e32 v49, 0xbf6c835e, v40
	v_fmac_f32_e32 v49, 0xbf3504f3, v41
	v_fmac_f32_e32 v49, 0x3ec3ef15, v42
	v_add_f32_e32 v49, v49, v43
	v_fmac_f32_e32 v49, 0x3ec3ef15, v44
	v_fmac_f32_e32 v49, 0xbf3504f3, v45
	v_fmac_f32_e32 v49, 0xbf6c835e, v46
	v_mul_f32_e32 v50, v49, v218
	v_fmac_f32_e32 v50, v48, v210
	v_mul_f32_e32 v51, v48, v218
	v_fma_f32 v51, v49, v210, -v51
	v_cvt_pk_bf16_f32 v52, v50, v51
	ds_write_b16 v3, v52 offset:26112
	ds_write_b16_d16_hi v3, v52 offset:30464
	v_add_f32_e32 v48, v16, v24
	v_sub_f32_e32 v48, v48, v33
	v_add_f32_e32 v48, v48, v35
	v_sub_f32_e32 v48, v48, v37
	v_sub_f32_e32 v49, 0, v40
	v_add_f32_e32 v49, v49, v42
	v_sub_f32_e32 v49, v49, v44
	v_add_f32_e32 v49, v49, v46
	v_mul_f32_e32 v50, v49, v219
	v_fmac_f32_e32 v50, v48, v211
	v_mul_f32_e32 v51, v48, v219
	v_fma_f32 v51, v49, v211, -v51
	v_cvt_pk_bf16_f32 v52, v50, v51
	ds_write_b16 v4, v52 offset:0
	ds_write_b16_d16_hi v4, v52 offset:4352
	v_sub_f32_e32 v48, v16, v24
	v_fmac_f32_e32 v48, 0xbec3ef15, v32
	v_fmac_f32_e32 v48, 0xbf3504f3, v33
	v_fmac_f32_e32 v48, 0x3f6c835e, v34
	v_fmac_f32_e32 v48, 0xbf6c835e, v36
	v_fmac_f32_e32 v48, 0x3f3504f3, v37
	v_fmac_f32_e32 v48, 0x3ec3ef15, v38
	v_mul_f32_e32 v49, 0xbf6c835e, v40
	v_fmac_f32_e32 v49, 0x3f3504f3, v41
	v_fmac_f32_e32 v49, 0x3ec3ef15, v42
	v_sub_f32_e32 v49, v49, v43
	v_fmac_f32_e32 v49, 0x3ec3ef15, v44
	v_fmac_f32_e32 v49, 0x3f3504f3, v45
	v_fmac_f32_e32 v49, 0xbf6c835e, v46
	v_mul_f32_e32 v50, v49, v220
	v_fmac_f32_e32 v50, v48, v212
	v_mul_f32_e32 v51, v48, v220
	v_fma_f32 v51, v49, v212, -v51
	v_cvt_pk_bf16_f32 v52, v50, v51
	ds_write_b16 v4, v52 offset:8704
	ds_write_b16_d16_hi v4, v52 offset:13056
	v_add_f32_e32 v48, v16, v24
	v_fmac_f32_e32 v48, 0xbf3504f3, v32
	v_fmac_f32_e32 v48, 0x3f3504f3, v34
	v_sub_f32_e32 v48, v48, v35
	v_fmac_f32_e32 v48, 0x3f3504f3, v36
	v_fmac_f32_e32 v48, 0xbf3504f3, v38
	v_mul_f32_e32 v49, 0xbf3504f3, v40
	v_add_f32_e32 v49, v49, v41
	v_fmac_f32_e32 v49, 0xbf3504f3, v42
	v_fmac_f32_e32 v49, 0x3f3504f3, v44
	v_sub_f32_e32 v49, v49, v45
	v_fmac_f32_e32 v49, 0x3f3504f3, v46
	v_mul_f32_e32 v50, v49, v221
	v_fmac_f32_e32 v50, v48, v213
	v_mul_f32_e32 v51, v48, v221
	v_fma_f32 v51, v49, v213, -v51
	v_cvt_pk_bf16_f32 v52, v50, v51
	ds_write_b16 v4, v52 offset:17408
	ds_write_b16_d16_hi v4, v52 offset:21760
	v_sub_f32_e32 v48, v16, v24
	v_fmac_f32_e32 v48, 0xbf6c835e, v32
	v_fmac_f32_e32 v48, 0x3f3504f3, v33
	v_fmac_f32_e32 v48, 0xbec3ef15, v34
	v_fmac_f32_e32 v48, 0x3ec3ef15, v36
	v_fmac_f32_e32 v48, 0xbf3504f3, v37
	v_fmac_f32_e32 v48, 0x3f6c835e, v38
	v_mul_f32_e32 v49, 0xbec3ef15, v40
	v_fmac_f32_e32 v49, 0x3f3504f3, v41
	v_fmac_f32_e32 v49, 0xbf6c835e, v42
	v_add_f32_e32 v49, v49, v43
	v_fmac_f32_e32 v49, 0xbf6c835e, v44
; __device__ __forceinline__ bf16_t f2bf(float f) { return (bf16_t)(cvt_pk_bf16(f, 0.f) & 0xffffu); }
; __device__ __forceinline__ void dft16_phase(const Ctx& X, const bf16_t* HN, bf16_t* GT) {
;     ...
;             for (int kl = 0; kl < 4; ++kl) { const int ka = kq * 4 + kl; if (ka > 8) break;
;                 const float tang = (float)(bp * ka) * (1.0f / 2048.0f); const float tc = cospif(tang), ts = -sinpif(tang);
;                 float cw[16], sw[16];
; #pragma unroll
;                 for (int a = 0; a < 16; ++a) { const int m = (a * ka) & 15; cw[a] = T16[m]; sw[a] = T16[16 + m]; }
; #pragma unroll
;                 for (int e = 0; e < 8; ++e) { float re = 0.f, im = 0.f;
; #pragma unroll
;                     for (int a = 0; a < 16; ++a) { const unsigned wv = xin[a][e >> 1]; const float x = (e & 1) ? bf2f(wv >> 16) : bf2f(wv & 0xffffu); re += x * cw[a]; im -= x * sw[a]; }
;                     const float orr = re * tc - im * ts, oi = re * ts + im * tc;
;                     tile[((kl * 2 + 0) * 64 + cchunk * 8 + e) * 72 + i] = f2bf(orr); tile[((kl * 2 + 1) * 64 + cchunk * 8 + e) * 72 + i] = f2bf(oi); } }
	v_fmac_f32_e32 v49, 0x3f3504f3, v45
	v_fmac_f32_e32 v49, 0xbec3ef15, v46
	v_mul_f32_e32 v50, v49, v222
	v_fmac_f32_e32 v50, v48, v214
	v_mul_f32_e32 v51, v48, v222
	v_fma_f32 v51, v49, v214, -v51
	v_cvt_pk_bf16_f32 v52, v50, v51
	ds_write_b16 v4, v52 offset:26112
	ds_write_b16_d16_hi v4, v52 offset:30464
	v_add_f32_e32 v48, v16, v24
	v_sub_f32_e32 v48, v48, v32
	v_add_f32_e32 v48, v48, v33
	v_sub_f32_e32 v48, v48, v34
	v_add_f32_e32 v48, v48, v35
	v_sub_f32_e32 v48, v48, v36
	v_add_f32_e32 v48, v48, v37
	v_sub_f32_e32 v48, v48, v38
	v_mul_f32_e32 v50, v48, v215
	v_mul_f32_e32 v51, v48, v223
	v_sub_f32_e32 v51, 0, v51
	v_cvt_pk_bf16_f32 v52, v50, v51
	ds_write_b16 v4, v52 offset:34816
	ds_write_b16_d16_hi v4, v52 offset:39168
	v_and_b32_e32 v16, 0xffff0000, v130
	v_and_b32_e32 v17, 0xffff0000, v134
	v_and_b32_e32 v18, 0xffff0000, v138
	v_and_b32_e32 v19, 0xffff0000, v142
	v_and_b32_e32 v20, 0xffff0000, v146
	v_and_b32_e32 v21, 0xffff0000, v150
	v_and_b32_e32 v22, 0xffff0000, v154
	v_and_b32_e32 v23, 0xffff0000, v158
	v_and_b32_e32 v24, 0xffff0000, v162
	v_and_b32_e32 v25, 0xffff0000, v166
	v_and_b32_e32 v26, 0xffff0000, v170
	v_and_b32_e32 v27, 0xffff0000, v174
	v_and_b32_e32 v28, 0xffff0000, v178
	v_and_b32_e32 v29, 0xffff0000, v182
	v_and_b32_e32 v30, 0xffff0000, v186
	v_and_b32_e32 v31, 0xffff0000, v190
	v_add_f32_e32 v32, v17, v31
	v_sub_f32_e32 v40, v17, v31
	v_add_f32_e32 v33, v18, v30
	v_sub_f32_e32 v41, v18, v30
	v_add_f32_e32 v34, v19, v29
	v_sub_f32_e32 v42, v19, v29
	v_add_f32_e32 v35, v20, v28
	v_sub_f32_e32 v43, v20, v28
	v_add_f32_e32 v36, v21, v27
	v_sub_f32_e32 v44, v21, v27
	v_add_f32_e32 v37, v22, v26
	v_sub_f32_e32 v45, v22, v26
	v_add_f32_e32 v38, v23, v25
	v_sub_f32_e32 v46, v23, v25
	v_add_f32_e32 v48, v16, v24
	v_add_f32_e32 v48, v48, v32
	v_add_f32_e32 v48, v48, v33
	v_add_f32_e32 v48, v48, v34
	v_add_f32_e32 v48, v48, v35
	v_add_f32_e32 v48, v48, v36
	v_add_f32_e32 v48, v48, v37
	v_add_f32_e32 v48, v48, v38
	v_cvt_pk_bf16_f32 v52, v48, 0
	ds_write_b16 v3, v52 offset:136
	ds_write_b16_d16_hi v3, v52 offset:4488
	v_sub_f32_e32 v48, v16, v24
	v_fmac_f32_e32 v48, 0x3f6c835e, v32
	v_fmac_f32_e32 v48, 0x3f3504f3, v33
	v_fmac_f32_e32 v48, 0x3ec3ef15, v34
	v_fmac_f32_e32 v48, 0xbec3ef15, v36
	v_fmac_f32_e32 v48, 0xbf3504f3, v37
	v_fmac_f32_e32 v48, 0xbf6c835e, v38
	v_mul_f32_e32 v49, 0xbec3ef15, v40
	v_fmac_f32_e32 v49, 0xbf3504f3, v41
	v_fmac_f32_e32 v49, 0xbf6c835e, v42
	v_sub_f32_e32 v49, v49, v43
	v_fmac_f32_e32 v49, 0xbf6c835e, v44
	v_fmac_f32_e32 v49, 0xbf3504f3, v45
	v_fmac_f32_e32 v49, 0xbec3ef15, v46
	v_mul_f32_e32 v50, v49, v216
	v_fmac_f32_e32 v50, v48, v208
	v_mul_f32_e32 v51, v48, v216
	v_fma_f32 v51, v49, v208, -v51
	v_cvt_pk_bf16_f32 v52, v50, v51
	ds_write_b16 v3, v52 offset:8840
	ds_write_b16_d16_hi v3, v52 offset:13192
	v_add_f32_e32 v48, v16, v24
	v_fmac_f32_e32 v48, 0x3f3504f3, v32
	v_fmac_f32_e32 v48, 0xbf3504f3, v34
	v_sub_f32_e32 v48, v48, v35
	v_fmac_f32_e32 v48, 0xbf3504f3, v36
	v_fmac_f32_e32 v48, 0x3f3504f3, v38
	v_mul_f32_e32 v49, 0xbf3504f3, v40
	v_sub_f32_e32 v49, v49, v41
	v_fmac_f32_e32 v49, 0xbf3504f3, v42
	v_fmac_f32_e32 v49, 0x3f3504f3, v44
	v_add_f32_e32 v49, v49, v45
	v_fmac_f32_e32 v49, 0x3f3504f3, v46
	v_mul_f32_e32 v50, v49, v217
	v_fmac_f32_e32 v50, v48, v209
	v_mul_f32_e32 v51, v48, v217
	v_fma_f32 v51, v49, v209, -v51
	v_cvt_pk_bf16_f32 v52, v50, v51
	ds_write_b16 v3, v52 offset:17544
	ds_write_b16_d16_hi v3, v52 offset:21896
	v_sub_f32_e32 v48, v16, v24
	v_fmac_f32_e32 v48, 0x3ec3ef15, v32
	v_fmac_f32_e32 v48, 0xbf3504f3, v33
	v_fmac_f32_e32 v48, 0xbf6c835e, v34
	v_fmac_f32_e32 v48, 0x3f6c835e, v36
	v_fmac_f32_e32 v48, 0x3f3504f3, v37
	v_fmac_f32_e32 v48, 0xbec3ef15, v38
	v_mul_f32_e32 v49, 0xbf6c835e, v40
	v_fmac_f32_e32 v49, 0xbf3504f3, v41
	v_fmac_f32_e32 v49, 0x3ec3ef15, v42
	v_add_f32_e32 v49, v49, v43
	v_fmac_f32_e32 v49, 0x3ec3ef15, v44
	v_fmac_f32_e32 v49, 0xbf3504f3, v45
	v_fmac_f32_e32 v49, 0xbf6c835e, v46
	v_mul_f32_e32 v50, v49, v218
	v_fmac_f32_e32 v50, v48, v210
	v_mul_f32_e32 v51, v48, v218
	v_fma_f32 v51, v49, v210, -v51
	v_cvt_pk_bf16_f32 v52, v50, v51
	ds_write_b16 v3, v52 offset:26248
	ds_write_b16_d16_hi v3, v52 offset:30600
	v_add_f32_e32 v48, v16, v24
	v_sub_f32_e32 v48, v48, v33
	v_add_f32_e32 v48, v48, v35
	v_sub_f32_e32 v48, v48, v37
	v_sub_f32_e32 v49, 0, v40
	v_add_f32_e32 v49, v49, v42
	v_sub_f32_e32 v49, v49, v44
	v_add_f32_e32 v49, v49, v46
	v_mul_f32_e32 v50, v49, v219
	v_fmac_f32_e32 v50, v48, v211
	v_mul_f32_e32 v51, v48, v219
	v_fma_f32 v51, v49, v211, -v51
	v_cvt_pk_bf16_f32 v52, v50, v51
	ds_write_b16 v4, v52 offset:136
	ds_write_b16_d16_hi v4, v52 offset:4488
	v_sub_f32_e32 v48, v16, v24
	v_fmac_f32_e32 v48, 0xbec3ef15, v32
	v_fmac_f32_e32 v48, 0xbf3504f3, v33
	v_fmac_f32_e32 v48, 0x3f6c835e, v34
	v_fmac_f32_e32 v48, 0xbf6c835e, v36
	v_fmac_f32_e32 v48, 0x3f3504f3, v37
	v_fmac_f32_e32 v48, 0x3ec3ef15, v38
	v_mul_f32_e32 v49, 0xbf6c835e, v40
	v_fmac_f32_e32 v49, 0x3f3504f3, v41
	v_fmac_f32_e32 v49, 0x3ec3ef15, v42
	v_sub_f32_e32 v49, v49, v43
	v_fmac_f32_e32 v49, 0x3ec3ef15, v44
	v_fmac_f32_e32 v49, 0x3f3504f3, v45
	v_fmac_f32_e32 v49, 0xbf6c835e, v46
	v_mul_f32_e32 v50, v49, v220
	v_fmac_f32_e32 v50, v48, v212
	v_mul_f32_e32 v51, v48, v220
	v_fma_f32 v51, v49, v212, -v51
	v_cvt_pk_bf16_f32 v52, v50, v51
	ds_write_b16 v4, v52 offset:8840
	ds_write_b16_d16_hi v4, v52 offset:13192
	v_add_f32_e32 v48, v16, v24
	v_fmac_f32_e32 v48, 0xbf3504f3, v32
	v_fmac_f32_e32 v48, 0x3f3504f3, v34
	v_sub_f32_e32 v48, v48, v35
	v_fmac_f32_e32 v48, 0x3f3504f3, v36
	v_fmac_f32_e32 v48, 0xbf3504f3, v38
	v_mul_f32_e32 v49, 0xbf3504f3, v40
	v_add_f32_e32 v49, v49, v41
; __device__ __forceinline__ bf16_t f2bf(float f) { return (bf16_t)(cvt_pk_bf16(f, 0.f) & 0xffffu); }
; __device__ __forceinline__ void dft16_phase(const Ctx& X, const bf16_t* HN, bf16_t* GT) {
;     ...
;             for (int kl = 0; kl < 4; ++kl) { const int ka = kq * 4 + kl; if (ka > 8) break;
;                 const float tang = (float)(bp * ka) * (1.0f / 2048.0f); const float tc = cospif(tang), ts = -sinpif(tang);
;                 float cw[16], sw[16];
; #pragma unroll
;                 for (int a = 0; a < 16; ++a) { const int m = (a * ka) & 15; cw[a] = T16[m]; sw[a] = T16[16 + m]; }
; #pragma unroll
;                 for (int e = 0; e < 8; ++e) { float re = 0.f, im = 0.f;
; #pragma unroll
;                     for (int a = 0; a < 16; ++a) { const unsigned wv = xin[a][e >> 1]; const float x = (e & 1) ? bf2f(wv >> 16) : bf2f(wv & 0xffffu); re += x * cw[a]; im -= x * sw[a]; }
;                     const float orr = re * tc - im * ts, oi = re * ts + im * tc;
;                     tile[((kl * 2 + 0) * 64 + cchunk * 8 + e) * 72 + i] = f2bf(orr); tile[((kl * 2 + 1) * 64 + cchunk * 8 + e) * 72 + i] = f2bf(oi); } }
	v_fmac_f32_e32 v49, 0xbf3504f3, v42
	v_fmac_f32_e32 v49, 0x3f3504f3, v44
	v_sub_f32_e32 v49, v49, v45
	v_fmac_f32_e32 v49, 0x3f3504f3, v46
	v_mul_f32_e32 v50, v49, v221
	v_fmac_f32_e32 v50, v48, v213
	v_mul_f32_e32 v51, v48, v221
	v_fma_f32 v51, v49, v213, -v51
	v_cvt_pk_bf16_f32 v52, v50, v51
	ds_write_b16 v4, v52 offset:17544
	ds_write_b16_d16_hi v4, v52 offset:21896
	v_sub_f32_e32 v48, v16, v24
	v_fmac_f32_e32 v48, 0xbf6c835e, v32
	v_fmac_f32_e32 v48, 0x3f3504f3, v33
	v_fmac_f32_e32 v48, 0xbec3ef15, v34
	v_fmac_f32_e32 v48, 0x3ec3ef15, v36
	v_fmac_f32_e32 v48, 0xbf3504f3, v37
	v_fmac_f32_e32 v48, 0x3f6c835e, v38
	v_mul_f32_e32 v49, 0xbec3ef15, v40
	v_fmac_f32_e32 v49, 0x3f3504f3, v41
	v_fmac_f32_e32 v49, 0xbf6c835e, v42
	v_add_f32_e32 v49, v49, v43
	v_fmac_f32_e32 v49, 0xbf6c835e, v44
	v_fmac_f32_e32 v49, 0x3f3504f3, v45
	v_fmac_f32_e32 v49, 0xbec3ef15, v46
	v_mul_f32_e32 v50, v49, v222
	v_fmac_f32_e32 v50, v48, v214
	v_mul_f32_e32 v51, v48, v222
	v_fma_f32 v51, v49, v214, -v51
	v_cvt_pk_bf16_f32 v52, v50, v51
	ds_write_b16 v4, v52 offset:26248
	ds_write_b16_d16_hi v4, v52 offset:30600
	v_add_f32_e32 v48, v16, v24
	v_sub_f32_e32 v48, v48, v32
	v_add_f32_e32 v48, v48, v33
	v_sub_f32_e32 v48, v48, v34
	v_add_f32_e32 v48, v48, v35
	v_sub_f32_e32 v48, v48, v36
	v_add_f32_e32 v48, v48, v37
	v_sub_f32_e32 v48, v48, v38
	v_mul_f32_e32 v50, v48, v215
	v_mul_f32_e32 v51, v48, v223
	v_sub_f32_e32 v51, 0, v51
	v_cvt_pk_bf16_f32 v52, v50, v51
	ds_write_b16 v4, v52 offset:34952
	ds_write_b16_d16_hi v4, v52 offset:39304
	v_lshlrev_b32_e32 v16, 16, v131
	v_lshlrev_b32_e32 v17, 16, v135
	v_lshlrev_b32_e32 v18, 16, v139
	v_lshlrev_b32_e32 v19, 16, v143
	v_lshlrev_b32_e32 v20, 16, v147
	v_lshlrev_b32_e32 v21, 16, v151
	v_lshlrev_b32_e32 v22, 16, v155
	v_lshlrev_b32_e32 v23, 16, v159
	v_lshlrev_b32_e32 v24, 16, v163
	v_lshlrev_b32_e32 v25, 16, v167
	v_lshlrev_b32_e32 v26, 16, v171
	v_lshlrev_b32_e32 v27, 16, v175
	v_lshlrev_b32_e32 v28, 16, v179
	v_lshlrev_b32_e32 v29, 16, v183
	v_lshlrev_b32_e32 v30, 16, v187
	v_lshlrev_b32_e32 v31, 16, v191
	v_add_f32_e32 v32, v17, v31
	v_sub_f32_e32 v40, v17, v31
	v_add_f32_e32 v33, v18, v30
	v_sub_f32_e32 v41, v18, v30
	v_add_f32_e32 v34, v19, v29
	v_sub_f32_e32 v42, v19, v29
	v_add_f32_e32 v35, v20, v28
	v_sub_f32_e32 v43, v20, v28
	v_add_f32_e32 v36, v21, v27
	v_sub_f32_e32 v44, v21, v27
	v_add_f32_e32 v37, v22, v26
	v_sub_f32_e32 v45, v22, v26
	v_add_f32_e32 v38, v23, v25
	v_sub_f32_e32 v46, v23, v25
	v_add_f32_e32 v48, v16, v24
	v_add_f32_e32 v48, v48, v32
	v_add_f32_e32 v48, v48, v33
	v_add_f32_e32 v48, v48, v34
	v_add_f32_e32 v48, v48, v35
	v_add_f32_e32 v48, v48, v36
	v_add_f32_e32 v48, v48, v37
	v_add_f32_e32 v48, v48, v38
	v_cvt_pk_bf16_f32 v52, v48, 0
	ds_write_b16 v3, v52 offset:272
	ds_write_b16_d16_hi v3, v52 offset:4624
	v_sub_f32_e32 v48, v16, v24
	v_fmac_f32_e32 v48, 0x3f6c835e, v32
	v_fmac_f32_e32 v48, 0x3f3504f3, v33
	v_fmac_f32_e32 v48, 0x3ec3ef15, v34
	v_fmac_f32_e32 v48, 0xbec3ef15, v36
	v_fmac_f32_e32 v48, 0xbf3504f3, v37
	v_fmac_f32_e32 v48, 0xbf6c835e, v38
	v_mul_f32_e32 v49, 0xbec3ef15, v40
	v_fmac_f32_e32 v49, 0xbf3504f3, v41
	v_fmac_f32_e32 v49, 0xbf6c835e, v42
	v_sub_f32_e32 v49, v49, v43
	v_fmac_f32_e32 v49, 0xbf6c835e, v44
	v_fmac_f32_e32 v49, 0xbf3504f3, v45
	v_fmac_f32_e32 v49, 0xbec3ef15, v46
	v_mul_f32_e32 v50, v49, v216
	v_fmac_f32_e32 v50, v48, v208
	v_mul_f32_e32 v51, v48, v216
	v_fma_f32 v51, v49, v208, -v51
	v_cvt_pk_bf16_f32 v52, v50, v51
	ds_write_b16 v3, v52 offset:8976
	ds_write_b16_d16_hi v3, v52 offset:13328
	v_add_f32_e32 v48, v16, v24
	v_fmac_f32_e32 v48, 0x3f3504f3, v32
	v_fmac_f32_e32 v48, 0xbf3504f3, v34
	v_sub_f32_e32 v48, v48, v35
	v_fmac_f32_e32 v48, 0xbf3504f3, v36
	v_fmac_f32_e32 v48, 0x3f3504f3, v38
	v_mul_f32_e32 v49, 0xbf3504f3, v40
	v_sub_f32_e32 v49, v49, v41
	v_fmac_f32_e32 v49, 0xbf3504f3, v42
	v_fmac_f32_e32 v49, 0x3f3504f3, v44
	v_add_f32_e32 v49, v49, v45
	v_fmac_f32_e32 v49, 0x3f3504f3, v46
	v_mul_f32_e32 v50, v49, v217
	v_fmac_f32_e32 v50, v48, v209
	v_mul_f32_e32 v51, v48, v217
	v_fma_f32 v51, v49, v209, -v51
	v_cvt_pk_bf16_f32 v52, v50, v51
	ds_write_b16 v3, v52 offset:17680
	ds_write_b16_d16_hi v3, v52 offset:22032
	v_sub_f32_e32 v48, v16, v24
	v_fmac_f32_e32 v48, 0x3ec3ef15, v32
	v_fmac_f32_e32 v48, 0xbf3504f3, v33
	v_fmac_f32_e32 v48, 0xbf6c835e, v34
	v_fmac_f32_e32 v48, 0x3f6c835e, v36
	v_fmac_f32_e32 v48, 0x3f3504f3, v37
	v_fmac_f32_e32 v48, 0xbec3ef15, v38
	v_mul_f32_e32 v49, 0xbf6c835e, v40
	v_fmac_f32_e32 v49, 0xbf3504f3, v41
	v_fmac_f32_e32 v49, 0x3ec3ef15, v42
	v_add_f32_e32 v49, v49, v43
	v_fmac_f32_e32 v49, 0x3ec3ef15, v44
	v_fmac_f32_e32 v49, 0xbf3504f3, v45
	v_fmac_f32_e32 v49, 0xbf6c835e, v46
	v_mul_f32_e32 v50, v49, v218
	v_fmac_f32_e32 v50, v48, v210
	v_mul_f32_e32 v51, v48, v218
	v_fma_f32 v51, v49, v210, -v51
	v_cvt_pk_bf16_f32 v52, v50, v51
	ds_write_b16 v3, v52 offset:26384
	ds_write_b16_d16_hi v3, v52 offset:30736
	v_add_f32_e32 v48, v16, v24
	v_sub_f32_e32 v48, v48, v33
	v_add_f32_e32 v48, v48, v35
	v_sub_f32_e32 v48, v48, v37
	v_sub_f32_e32 v49, 0, v40
	v_add_f32_e32 v49, v49, v42
	v_sub_f32_e32 v49, v49, v44
	v_add_f32_e32 v49, v49, v46
	v_mul_f32_e32 v50, v49, v219
	v_fmac_f32_e32 v50, v48, v211
	v_mul_f32_e32 v51, v48, v219
	v_fma_f32 v51, v49, v211, -v51
	v_cvt_pk_bf16_f32 v52, v50, v51
	ds_write_b16 v4, v52 offset:272
	ds_write_b16_d16_hi v4, v52 offset:4624
	v_sub_f32_e32 v48, v16, v24
	v_fmac_f32_e32 v48, 0xbec3ef15, v32
	v_fmac_f32_e32 v48, 0xbf3504f3, v33
	v_fmac_f32_e32 v48, 0x3f6c835e, v34
	v_fmac_f32_e32 v48, 0xbf6c835e, v36
	v_fmac_f32_e32 v48, 0x3f3504f3, v37
	v_fmac_f32_e32 v48, 0x3ec3ef15, v38
; __device__ __forceinline__ bf16_t f2bf(float f) { return (bf16_t)(cvt_pk_bf16(f, 0.f) & 0xffffu); }
; __device__ __forceinline__ void dft16_phase(const Ctx& X, const bf16_t* HN, bf16_t* GT) {
;     ...
;             for (int kl = 0; kl < 4; ++kl) { const int ka = kq * 4 + kl; if (ka > 8) break;
;                 const float tang = (float)(bp * ka) * (1.0f / 2048.0f); const float tc = cospif(tang), ts = -sinpif(tang);
;                 float cw[16], sw[16];
; #pragma unroll
;                 for (int a = 0; a < 16; ++a) { const int m = (a * ka) & 15; cw[a] = T16[m]; sw[a] = T16[16 + m]; }
; #pragma unroll
;                 for (int e = 0; e < 8; ++e) { float re = 0.f, im = 0.f;
; #pragma unroll
;                     for (int a = 0; a < 16; ++a) { const unsigned wv = xin[a][e >> 1]; const float x = (e & 1) ? bf2f(wv >> 16) : bf2f(wv & 0xffffu); re += x * cw[a]; im -= x * sw[a]; }
;                     const float orr = re * tc - im * ts, oi = re * ts + im * tc;
;                     tile[((kl * 2 + 0) * 64 + cchunk * 8 + e) * 72 + i] = f2bf(orr); tile[((kl * 2 + 1) * 64 + cchunk * 8 + e) * 72 + i] = f2bf(oi); } }
	v_mul_f32_e32 v49, 0xbf6c835e, v40
	v_fmac_f32_e32 v49, 0x3f3504f3, v41
	v_fmac_f32_e32 v49, 0x3ec3ef15, v42
	v_sub_f32_e32 v49, v49, v43
	v_fmac_f32_e32 v49, 0x3ec3ef15, v44
	v_fmac_f32_e32 v49, 0x3f3504f3, v45
	v_fmac_f32_e32 v49, 0xbf6c835e, v46
	v_mul_f32_e32 v50, v49, v220
	v_fmac_f32_e32 v50, v48, v212
	v_mul_f32_e32 v51, v48, v220
	v_fma_f32 v51, v49, v212, -v51
	v_cvt_pk_bf16_f32 v52, v50, v51
	ds_write_b16 v4, v52 offset:8976
	ds_write_b16_d16_hi v4, v52 offset:13328
	v_add_f32_e32 v48, v16, v24
	v_fmac_f32_e32 v48, 0xbf3504f3, v32
	v_fmac_f32_e32 v48, 0x3f3504f3, v34
	v_sub_f32_e32 v48, v48, v35
	v_fmac_f32_e32 v48, 0x3f3504f3, v36
	v_fmac_f32_e32 v48, 0xbf3504f3, v38
	v_mul_f32_e32 v49, 0xbf3504f3, v40
	v_add_f32_e32 v49, v49, v41
	v_fmac_f32_e32 v49, 0xbf3504f3, v42
	v_fmac_f32_e32 v49, 0x3f3504f3, v44
	v_sub_f32_e32 v49, v49, v45
	v_fmac_f32_e32 v49, 0x3f3504f3, v46
	v_mul_f32_e32 v50, v49, v221
	v_fmac_f32_e32 v50, v48, v213
	v_mul_f32_e32 v51, v48, v221
	v_fma_f32 v51, v49, v213, -v51
	v_cvt_pk_bf16_f32 v52, v50, v51
	ds_write_b16 v4, v52 offset:17680
	ds_write_b16_d16_hi v4, v52 offset:22032
	v_sub_f32_e32 v48, v16, v24
	v_fmac_f32_e32 v48, 0xbf6c835e, v32
	v_fmac_f32_e32 v48, 0x3f3504f3, v33
	v_fmac_f32_e32 v48, 0xbec3ef15, v34
	v_fmac_f32_e32 v48, 0x3ec3ef15, v36
	v_fmac_f32_e32 v48, 0xbf3504f3, v37
	v_fmac_f32_e32 v48, 0x3f6c835e, v38
	v_mul_f32_e32 v49, 0xbec3ef15, v40
	v_fmac_f32_e32 v49, 0x3f3504f3, v41
	v_fmac_f32_e32 v49, 0xbf6c835e, v42
	v_add_f32_e32 v49, v49, v43
	v_fmac_f32_e32 v49, 0xbf6c835e, v44
	v_fmac_f32_e32 v49, 0x3f3504f3, v45
	v_fmac_f32_e32 v49, 0xbec3ef15, v46
	v_mul_f32_e32 v50, v49, v222
	v_fmac_f32_e32 v50, v48, v214
	v_mul_f32_e32 v51, v48, v222
	v_fma_f32 v51, v49, v214, -v51
	v_cvt_pk_bf16_f32 v52, v50, v51
	ds_write_b16 v4, v52 offset:26384
	ds_write_b16_d16_hi v4, v52 offset:30736
	v_add_f32_e32 v48, v16, v24
	v_sub_f32_e32 v48, v48, v32
	v_add_f32_e32 v48, v48, v33
	v_sub_f32_e32 v48, v48, v34
	v_add_f32_e32 v48, v48, v35
	v_sub_f32_e32 v48, v48, v36
	v_add_f32_e32 v48, v48, v37
	v_sub_f32_e32 v48, v48, v38
	v_mul_f32_e32 v50, v48, v215
	v_mul_f32_e32 v51, v48, v223
	v_sub_f32_e32 v51, 0, v51
	v_cvt_pk_bf16_f32 v52, v50, v51
	ds_write_b16 v4, v52 offset:35088
	ds_write_b16_d16_hi v4, v52 offset:39440
	v_and_b32_e32 v16, 0xffff0000, v131
	v_and_b32_e32 v17, 0xffff0000, v135
	v_and_b32_e32 v18, 0xffff0000, v139
	v_and_b32_e32 v19, 0xffff0000, v143
	v_and_b32_e32 v20, 0xffff0000, v147
	v_and_b32_e32 v21, 0xffff0000, v151
	v_and_b32_e32 v22, 0xffff0000, v155
	v_and_b32_e32 v23, 0xffff0000, v159
	v_and_b32_e32 v24, 0xffff0000, v163
	v_and_b32_e32 v25, 0xffff0000, v167
	v_and_b32_e32 v26, 0xffff0000, v171
	v_and_b32_e32 v27, 0xffff0000, v175
	v_and_b32_e32 v28, 0xffff0000, v179
	v_and_b32_e32 v29, 0xffff0000, v183
	v_and_b32_e32 v30, 0xffff0000, v187
	v_and_b32_e32 v31, 0xffff0000, v191
	v_add_f32_e32 v32, v17, v31
	v_sub_f32_e32 v40, v17, v31
	v_add_f32_e32 v33, v18, v30
	v_sub_f32_e32 v41, v18, v30
	v_add_f32_e32 v34, v19, v29
	v_sub_f32_e32 v42, v19, v29
	v_add_f32_e32 v35, v20, v28
	v_sub_f32_e32 v43, v20, v28
	v_add_f32_e32 v36, v21, v27
	v_sub_f32_e32 v44, v21, v27
	v_add_f32_e32 v37, v22, v26
	v_sub_f32_e32 v45, v22, v26
	v_add_f32_e32 v38, v23, v25
	v_sub_f32_e32 v46, v23, v25
	v_add_f32_e32 v48, v16, v24
	v_add_f32_e32 v48, v48, v32
	v_add_f32_e32 v48, v48, v33
	v_add_f32_e32 v48, v48, v34
	v_add_f32_e32 v48, v48, v35
	v_add_f32_e32 v48, v48, v36
	v_add_f32_e32 v48, v48, v37
	v_add_f32_e32 v48, v48, v38
	v_cvt_pk_bf16_f32 v52, v48, 0
	ds_write_b16 v3, v52 offset:408
	ds_write_b16_d16_hi v3, v52 offset:4760
	v_sub_f32_e32 v48, v16, v24
	v_fmac_f32_e32 v48, 0x3f6c835e, v32
	v_fmac_f32_e32 v48, 0x3f3504f3, v33
	v_fmac_f32_e32 v48, 0x3ec3ef15, v34
	v_fmac_f32_e32 v48, 0xbec3ef15, v36
	v_fmac_f32_e32 v48, 0xbf3504f3, v37
	v_fmac_f32_e32 v48, 0xbf6c835e, v38
	v_mul_f32_e32 v49, 0xbec3ef15, v40
	v_fmac_f32_e32 v49, 0xbf3504f3, v41
	v_fmac_f32_e32 v49, 0xbf6c835e, v42
	v_sub_f32_e32 v49, v49, v43
	v_fmac_f32_e32 v49, 0xbf6c835e, v44
	v_fmac_f32_e32 v49, 0xbf3504f3, v45
	v_fmac_f32_e32 v49, 0xbec3ef15, v46
	v_mul_f32_e32 v50, v49, v216
	v_fmac_f32_e32 v50, v48, v208
	v_mul_f32_e32 v51, v48, v216
	v_fma_f32 v51, v49, v208, -v51
	v_cvt_pk_bf16_f32 v52, v50, v51
	ds_write_b16 v3, v52 offset:9112
	ds_write_b16_d16_hi v3, v52 offset:13464
	v_add_f32_e32 v48, v16, v24
	v_fmac_f32_e32 v48, 0x3f3504f3, v32
	v_fmac_f32_e32 v48, 0xbf3504f3, v34
	v_sub_f32_e32 v48, v48, v35
	v_fmac_f32_e32 v48, 0xbf3504f3, v36
	v_fmac_f32_e32 v48, 0x3f3504f3, v38
	v_mul_f32_e32 v49, 0xbf3504f3, v40
	v_sub_f32_e32 v49, v49, v41
	v_fmac_f32_e32 v49, 0xbf3504f3, v42
	v_fmac_f32_e32 v49, 0x3f3504f3, v44
	v_add_f32_e32 v49, v49, v45
	v_fmac_f32_e32 v49, 0x3f3504f3, v46
	v_mul_f32_e32 v50, v49, v217
	v_fmac_f32_e32 v50, v48, v209
	v_mul_f32_e32 v51, v48, v217
	v_fma_f32 v51, v49, v209, -v51
	v_cvt_pk_bf16_f32 v52, v50, v51
	ds_write_b16 v3, v52 offset:17816
	ds_write_b16_d16_hi v3, v52 offset:22168
	v_sub_f32_e32 v48, v16, v24
	v_fmac_f32_e32 v48, 0x3ec3ef15, v32
	v_fmac_f32_e32 v48, 0xbf3504f3, v33
	v_fmac_f32_e32 v48, 0xbf6c835e, v34
	v_fmac_f32_e32 v48, 0x3f6c835e, v36
	v_fmac_f32_e32 v48, 0x3f3504f3, v37
	v_fmac_f32_e32 v48, 0xbec3ef15, v38
; __device__ __forceinline__ bf16_t f2bf(float f) { return (bf16_t)(cvt_pk_bf16(f, 0.f) & 0xffffu); }
; __device__ __forceinline__ void dft16_phase(const Ctx& X, const bf16_t* HN, bf16_t* GT) {
;     ...
;             for (int kl = 0; kl < 4; ++kl) { const int ka = kq * 4 + kl; if (ka > 8) break;
;                 const float tang = (float)(bp * ka) * (1.0f / 2048.0f); const float tc = cospif(tang), ts = -sinpif(tang);
;                 float cw[16], sw[16];
; #pragma unroll
;                 for (int a = 0; a < 16; ++a) { const int m = (a * ka) & 15; cw[a] = T16[m]; sw[a] = T16[16 + m]; }
; #pragma unroll
;                 for (int e = 0; e < 8; ++e) { float re = 0.f, im = 0.f;
; #pragma unroll
;                     for (int a = 0; a < 16; ++a) { const unsigned wv = xin[a][e >> 1]; const float x = (e & 1) ? bf2f(wv >> 16) : bf2f(wv & 0xffffu); re += x * cw[a]; im -= x * sw[a]; }
;                     const float orr = re * tc - im * ts, oi = re * ts + im * tc;
;                     tile[((kl * 2 + 0) * 64 + cchunk * 8 + e) * 72 + i] = f2bf(orr); tile[((kl * 2 + 1) * 64 + cchunk * 8 + e) * 72 + i] = f2bf(oi); } }
;             __syncthreads();
; #pragma unroll
;             for (int q = 0; q < 8; ++q) { const int cid = q * 512 + X.tid, row = cid >> 3, c8 = cid & 7, kl = row >> 7, ri = (row >> 6) & 1, ch = row & 63;
;                 if (kq * 4 + kl > 8) continue;
;                 const u32x4 v = *(const u32x4*)(tile + row * 72 + c8 * 8);
;                 *(u32x4*)(GT + ((size_t)(b * 9 + kq * 4 + kl) * 1024 + ch0 + ch) * 512 + ri * 256 + b0 + c8 * 8) = v; }
	v_mul_f32_e32 v49, 0xbf6c835e, v40
	v_fmac_f32_e32 v49, 0xbf3504f3, v41
	v_fmac_f32_e32 v49, 0x3ec3ef15, v42
	v_add_f32_e32 v49, v49, v43
	v_fmac_f32_e32 v49, 0x3ec3ef15, v44
	v_fmac_f32_e32 v49, 0xbf3504f3, v45
	v_fmac_f32_e32 v49, 0xbf6c835e, v46
	v_mul_f32_e32 v50, v49, v218
	v_fmac_f32_e32 v50, v48, v210
	v_mul_f32_e32 v51, v48, v218
	v_fma_f32 v51, v49, v210, -v51
	v_cvt_pk_bf16_f32 v52, v50, v51
	ds_write_b16 v3, v52 offset:26520
	ds_write_b16_d16_hi v3, v52 offset:30872
	v_add_f32_e32 v48, v16, v24
	v_sub_f32_e32 v48, v48, v33
	v_add_f32_e32 v48, v48, v35
	v_sub_f32_e32 v48, v48, v37
	v_sub_f32_e32 v49, 0, v40
	v_add_f32_e32 v49, v49, v42
	v_sub_f32_e32 v49, v49, v44
	v_add_f32_e32 v49, v49, v46
	v_mul_f32_e32 v50, v49, v219
	v_fmac_f32_e32 v50, v48, v211
	v_mul_f32_e32 v51, v48, v219
	v_fma_f32 v51, v49, v211, -v51
	v_cvt_pk_bf16_f32 v52, v50, v51
	ds_write_b16 v4, v52 offset:408
	ds_write_b16_d16_hi v4, v52 offset:4760
	v_sub_f32_e32 v48, v16, v24
	v_fmac_f32_e32 v48, 0xbec3ef15, v32
	v_fmac_f32_e32 v48, 0xbf3504f3, v33
	v_fmac_f32_e32 v48, 0x3f6c835e, v34
	v_fmac_f32_e32 v48, 0xbf6c835e, v36
	v_fmac_f32_e32 v48, 0x3f3504f3, v37
	v_fmac_f32_e32 v48, 0x3ec3ef15, v38
	v_mul_f32_e32 v49, 0xbf6c835e, v40
	v_fmac_f32_e32 v49, 0x3f3504f3, v41
	v_fmac_f32_e32 v49, 0x3ec3ef15, v42
	v_sub_f32_e32 v49, v49, v43
	v_fmac_f32_e32 v49, 0x3ec3ef15, v44
	v_fmac_f32_e32 v49, 0x3f3504f3, v45
	v_fmac_f32_e32 v49, 0xbf6c835e, v46
	v_mul_f32_e32 v50, v49, v220
	v_fmac_f32_e32 v50, v48, v212
	v_mul_f32_e32 v51, v48, v220
	v_fma_f32 v51, v49, v212, -v51
	v_cvt_pk_bf16_f32 v52, v50, v51
	ds_write_b16 v4, v52 offset:9112
	ds_write_b16_d16_hi v4, v52 offset:13464
	v_add_f32_e32 v48, v16, v24
	v_fmac_f32_e32 v48, 0xbf3504f3, v32
	v_fmac_f32_e32 v48, 0x3f3504f3, v34
	v_sub_f32_e32 v48, v48, v35
	v_fmac_f32_e32 v48, 0x3f3504f3, v36
	v_fmac_f32_e32 v48, 0xbf3504f3, v38
	v_mul_f32_e32 v49, 0xbf3504f3, v40
	v_add_f32_e32 v49, v49, v41
	v_fmac_f32_e32 v49, 0xbf3504f3, v42
	v_fmac_f32_e32 v49, 0x3f3504f3, v44
	v_sub_f32_e32 v49, v49, v45
	v_fmac_f32_e32 v49, 0x3f3504f3, v46
	v_mul_f32_e32 v50, v49, v221
	v_fmac_f32_e32 v50, v48, v213
	v_mul_f32_e32 v51, v48, v221
	v_fma_f32 v51, v49, v213, -v51
	v_cvt_pk_bf16_f32 v52, v50, v51
	ds_write_b16 v4, v52 offset:17816
	ds_write_b16_d16_hi v4, v52 offset:22168
	v_sub_f32_e32 v48, v16, v24
	v_fmac_f32_e32 v48, 0xbf6c835e, v32
	v_fmac_f32_e32 v48, 0x3f3504f3, v33
	v_fmac_f32_e32 v48, 0xbec3ef15, v34
	v_fmac_f32_e32 v48, 0x3ec3ef15, v36
	v_fmac_f32_e32 v48, 0xbf3504f3, v37
	v_fmac_f32_e32 v48, 0x3f6c835e, v38
	v_mul_f32_e32 v49, 0xbec3ef15, v40
	v_fmac_f32_e32 v49, 0x3f3504f3, v41
	v_fmac_f32_e32 v49, 0xbf6c835e, v42
	v_add_f32_e32 v49, v49, v43
	v_fmac_f32_e32 v49, 0xbf6c835e, v44
	v_fmac_f32_e32 v49, 0x3f3504f3, v45
	v_fmac_f32_e32 v49, 0xbec3ef15, v46
	v_mul_f32_e32 v50, v49, v222
	v_fmac_f32_e32 v50, v48, v214
	v_mul_f32_e32 v51, v48, v222
	v_fma_f32 v51, v49, v214, -v51
	v_cvt_pk_bf16_f32 v52, v50, v51
	ds_write_b16 v4, v52 offset:26520
	ds_write_b16_d16_hi v4, v52 offset:30872
	v_add_f32_e32 v48, v16, v24
	v_sub_f32_e32 v48, v48, v32
	v_add_f32_e32 v48, v48, v33
	v_sub_f32_e32 v48, v48, v34
	v_add_f32_e32 v48, v48, v35
	v_sub_f32_e32 v48, v48, v36
	v_add_f32_e32 v48, v48, v37
	v_sub_f32_e32 v48, v48, v38
	v_mul_f32_e32 v50, v48, v215
	v_mul_f32_e32 v51, v48, v223
	v_sub_f32_e32 v51, 0, v51
	v_cvt_pk_bf16_f32 v52, v50, v51
	ds_write_b16 v4, v52 offset:35224
	ds_write_b16_d16_hi v4, v52 offset:39576
	s_waitcnt lgkmcnt(0)
	s_barrier
	s_add_u32 s8, s36, 4096
	s_addc_u32 s9, s37, 0
	ds_read_b64 v[20:21], v5 offset:0
	ds_read_b64 v[22:23], v5 offset:8
	ds_read_b64 v[24:25], v5 offset:8704
	ds_read_b64 v[26:27], v5 offset:8712
	ds_read_b64 v[28:29], v5 offset:17408
	ds_read_b64 v[30:31], v5 offset:17416
	s_waitcnt lgkmcnt(4)
	global_store_dwordx4 v7, v[20:23], s[8:9]
	s_add_u32 s8, s8, 0x100000
	s_addc_u32 s9, s9, 0
	ds_read_b64 v[20:21], v5 offset:26112
	ds_read_b64 v[22:23], v5 offset:26120
	s_waitcnt lgkmcnt(4)
	global_store_dwordx4 v7, v[24:27], s[8:9]
	s_add_u32 s8, s8, 0x100000
	s_addc_u32 s9, s9, 0
	ds_read_b64 v[24:25], v6 offset:0
	ds_read_b64 v[26:27], v6 offset:8
	s_waitcnt lgkmcnt(4)
	global_store_dwordx4 v7, v[28:31], s[8:9]
	s_add_u32 s8, s8, 0x100000
	s_addc_u32 s9, s9, 0
	ds_read_b64 v[28:29], v6 offset:8704
	ds_read_b64 v[30:31], v6 offset:8712
	s_waitcnt lgkmcnt(4)
	global_store_dwordx4 v7, v[20:23], s[8:9]
	s_add_u32 s8, s8, 0x100000
	s_addc_u32 s9, s9, 0
	ds_read_b64 v[20:21], v6 offset:17408
	ds_read_b64 v[22:23], v6 offset:17416
	s_waitcnt lgkmcnt(4)
	global_store_dwordx4 v7, v[24:27], s[8:9]
	s_add_u32 s8, s8, 0x100000
	s_addc_u32 s9, s9, 0
	ds_read_b64 v[24:25], v6 offset:26112
	ds_read_b64 v[26:27], v6 offset:26120
	s_waitcnt lgkmcnt(4)
	global_store_dwordx4 v7, v[28:31], s[8:9]
	s_add_u32 s8, s8, 0x100000
	s_addc_u32 s9, s9, 0
	ds_read_b64 v[28:29], v6 offset:34816
	ds_read_b64 v[30:31], v6 offset:34824
	s_waitcnt lgkmcnt(4)
	global_store_dwordx4 v7, v[20:23], s[8:9]
	s_add_u32 s8, s8, 0x100000
	s_addc_u32 s9, s9, 0
	s_waitcnt lgkmcnt(2)
	global_store_dwordx4 v7, v[24:27], s[8:9]
	s_add_u32 s8, s8, 0x100000
	s_addc_u32 s9, s9, 0
	s_waitcnt lgkmcnt(0)
	global_store_dwordx4 v7, v[28:31], s[8:9]
